# E26: G1-even bf16 epilogue stores widened to 16 bytes (registers shared with F-path preload) on top of E25
# speedup vs baseline: 1.0206x; 1.0044x over previous
; #define PG8_STAGE(bufoff, gbase, voff) do { _Pragma("unroll") for (int _i = 0; _i < 2; ++_i) \
;     __builtin_amdgcn_global_load_lds((const unsigned*)((const char*)(gbase) + (voff)[_i]), (LAS unsigned*)(lds + (bufoff) + ldsw + _i * 8192), 16, 0, 0); } while (0)
; #define PG8_LDA(dst, b, h) do { _Pragma("unroll") for (int m = 0; m < 4; ++m) _Pragma("unroll") for (int k = 0; k < 2; ++k) dst[m][k] = *(const LAS bf16x8*)(lds + PG8_SA(b, h) + aoff + m * 2048 + k * 1024); } while (0)
; #define PG8_LDB(dst, b, h) do { _Pragma("unroll") for (int n = 0; n < 2; ++n) _Pragma("unroll") for (int k = 0; k < 2; ++k) dst[n][k] = *(const LAS bf16x8*)(lds + PG8_SB(b, h) + boff + n * 2048 + k * 1024); } while (0)
; #define PG8_BAR __builtin_amdgcn_s_barrier()
; template <class Epi, class Sched>
; __device__ __forceinline__ void gemm_phase(LAS unsigned char* lds, const Gemm g, const Sched& S, const Epi& E) {
;     ...
;     for (int t = 0; t < nt; t += 2) {
;       const bool last = (t == nt - 2);
;       const char* a1 = cA + (size_t)(t + 1) * kstep;
;       const char* a2 = last ? nA : cA + (size_t)(t + 2) * kstep; const char* b2 = last ? nB : cB + (size_t)(t + 2) * kstep;
;       const char* a3 = a2 + kstep; const char* b3 = b2 + kstep;
;       PG8_LDB(B0, 0, 0); PG8_SCHED; PG8_LDA(At, 0, 0); PG8_STAGE(PG8_SA(1, 1), a1 + hstepA, voffA);
;       PG8_WAIT_L(8); PG8_BAR; PG8_WAIT_L(0); PG8_MMA(0, 0, At, B0); PG8_BAR; PG8_SCHED;
;       PG8_LDB(B1, 0, 1); PG8_STAGE(PG8_SB(0, 0), b2, voffB);
;       PG8_BAR; PG8_WAIT_L(0); PG8_MMA(0, 1, At, B1); PG8_BAR;
;       PG8_LDA(At, 0, 1); PG8_STAGE(PG8_SA(0, 0), a2, voffA);
;       PG8_BAR; PG8_WAIT_L(0); PG8_MMA(1, 0, At, B0); PG8_BAR; PG8_SCHED;
;       PG8_STAGE(PG8_SB(0, 1), b2 + hstepB, voffB);
;       PG8_WAIT_V(6); PG8_BAR; PG8_MMA(1, 1, At, B1); PG8_BAR;
;       PG8_LDB(B0, 1, 0); PG8_SCHED; PG8_LDA(At, 1, 0); PG8_STAGE(PG8_SA(0, 1), a2 + hstepA, voffA);
;       PG8_WAIT_L(8); PG8_BAR; PG8_WAIT_L(0); PG8_MMA(0, 0, At, B0); PG8_BAR; PG8_SCHED;
;       PG8_LDB(B1, 1, 1); PG8_STAGE(PG8_SB(1, 0), b3, voffB);
;       PG8_BAR; PG8_WAIT_L(0); PG8_MMA(0, 1, At, B1); PG8_BAR;
;       PG8_LDA(At, 1, 1); PG8_STAGE(PG8_SA(1, 0), a3, voffA);
;       PG8_BAR; PG8_WAIT_L(0); PG8_MMA(1, 0, At, B0); PG8_BAR; PG8_SCHED;
;       PG8_STAGE(PG8_SB(1, 1), b3 + hstepB, voffB);
;       PG8_WAIT_V(6); PG8_BAR; PG8_MMA(1, 1, At, B1); PG8_BAR;
.LBB0_1541:
	s_add_u32 s36, s78, 0xfffc0080
	s_addc_u32 s37, s79, -1
	s_add_i32 s76, 16, 0x10000
	v_add_u32_e32 v153, s76, v150
	ds_read_b128 v[136:139], v153
	ds_read_b128 v[140:143], v153 offset:1024
	ds_read_b128 v[146:149], v153 offset:2048
	ds_read_b128 v[154:157], v153 offset:3072
	s_cmp_eq_u32 s84, 12
	s_cselect_b32 s83, s9, s37
	s_cselect_b32 s82, s11, s36
	s_cselect_b32 s39, s23, s27
	s_cselect_b32 s38, s24, s25
	v_lshl_add_u64 v[214:215], s[78:79], 0, v[132:133]
	s_add_i32 m0, s69, 0xc000
	ds_read_b128 v[158:161], v152
	ds_read_b128 v[162:165], v152 offset:1024
	ds_read_b128 v[166:169], v152 offset:2048
	ds_read_b128 v[170:173], v152 offset:3072
	ds_read_b128 v[174:177], v152 offset:4096
	ds_read_b128 v[178:181], v152 offset:5120
	ds_read_b128 v[182:185], v152 offset:6144
	ds_read_b128 v[198:201], v152 offset:7168
	global_load_lds_dwordx4 v[214:215], off
	v_lshl_add_u64 v[214:215], s[78:79], 0, v[134:135]
	s_add_i32 m0, s69, 0xe000
	s_nop 0
	global_load_lds_dwordx4 v[214:215], off
	s_waitcnt lgkmcnt(8)
	s_barrier
	s_waitcnt lgkmcnt(0)
	s_setprio 1
	s_waitcnt lgkmcnt(0)
	v_mfma_f32_16x16x32_bf16 v[124:127], v[136:139], v[158:161], v[124:127]
	v_mfma_f32_16x16x32_bf16 v[120:123], v[146:149], v[158:161], v[120:123]
	v_mfma_f32_16x16x32_bf16 v[108:111], v[136:139], v[166:169], v[108:111]
	v_mfma_f32_16x16x32_bf16 v[104:107], v[146:149], v[166:169], v[104:107]
	v_mfma_f32_16x16x32_bf16 v[92:95], v[136:139], v[174:177], v[92:95]
	v_mfma_f32_16x16x32_bf16 v[88:91], v[146:149], v[174:177], v[88:91]
	v_mfma_f32_16x16x32_bf16 v[76:79], v[136:139], v[182:185], v[76:79]
	v_mfma_f32_16x16x32_bf16 v[72:75], v[146:149], v[182:185], v[72:75]
	v_mfma_f32_16x16x32_bf16 v[124:127], v[140:143], v[162:165], v[124:127]
	v_mfma_f32_16x16x32_bf16 v[120:123], v[154:157], v[162:165], v[120:123]
	v_mfma_f32_16x16x32_bf16 v[108:111], v[140:143], v[170:173], v[108:111]
	v_mfma_f32_16x16x32_bf16 v[104:107], v[154:157], v[170:173], v[104:107]
	v_mfma_f32_16x16x32_bf16 v[92:95], v[140:143], v[178:181], v[92:95]
	v_mfma_f32_16x16x32_bf16 v[88:91], v[154:157], v[178:181], v[88:91]
	v_mfma_f32_16x16x32_bf16 v[76:79], v[140:143], v[198:201], v[76:79]
	v_mfma_f32_16x16x32_bf16 v[72:75], v[154:157], v[198:201], v[72:75]
	s_setprio 0
	s_barrier
	s_add_i32 s77, 16, 0x14000
	s_add_i32 s36, s76, s68
	v_add_u32_e32 v153, s77, v150
	v_lshl_add_u64 v[230:231], s[38:39], 0, v[128:129]
	s_mov_b32 m0, s36
	ds_read_b128 v[214:217], v153
	ds_read_b128 v[218:221], v153 offset:1024
	ds_read_b128 v[222:225], v153 offset:2048
	ds_read_b128 v[226:229], v153 offset:3072
	global_load_lds_dwordx4 v[230:231], off
	v_lshl_add_u64 v[232:233], s[38:39], 0, v[130:131]
	s_add_i32 m0, s36, 0x2000
	s_nop 0
	global_load_lds_dwordx4 v[232:233], off
	s_barrier
	s_waitcnt lgkmcnt(0)
	s_setprio 1
	s_waitcnt lgkmcnt(0)
	v_mfma_f32_16x16x32_bf16 v[116:119], v[214:217], v[158:161], v[116:119]
	v_mfma_f32_16x16x32_bf16 v[112:115], v[222:225], v[158:161], v[112:115]
	v_mfma_f32_16x16x32_bf16 v[100:103], v[214:217], v[166:169], v[100:103]
	v_mfma_f32_16x16x32_bf16 v[96:99], v[222:225], v[166:169], v[96:99]
	v_mfma_f32_16x16x32_bf16 v[84:87], v[214:217], v[174:177], v[84:87]
	v_mfma_f32_16x16x32_bf16 v[80:83], v[222:225], v[174:177], v[80:83]
	v_mfma_f32_16x16x32_bf16 v[68:71], v[214:217], v[182:185], v[68:71]
	v_mfma_f32_16x16x32_bf16 v[64:67], v[222:225], v[182:185], v[64:67]
	v_mfma_f32_16x16x32_bf16 v[116:119], v[218:221], v[162:165], v[116:119]
	v_mfma_f32_16x16x32_bf16 v[112:115], v[226:229], v[162:165], v[112:115]
	v_mfma_f32_16x16x32_bf16 v[100:103], v[218:221], v[170:173], v[100:103]
	v_mfma_f32_16x16x32_bf16 v[96:99], v[226:229], v[170:173], v[96:99]
	v_mfma_f32_16x16x32_bf16 v[84:87], v[218:221], v[178:181], v[84:87]
	v_mfma_f32_16x16x32_bf16 v[80:83], v[226:229], v[178:181], v[80:83]
	v_mfma_f32_16x16x32_bf16 v[68:71], v[218:221], v[198:201], v[68:71]
	v_mfma_f32_16x16x32_bf16 v[64:67], v[226:229], v[198:201], v[64:67]
	s_setprio 0
	s_mov_b32 m0, s69
	v_lshl_add_u64 v[234:235], s[82:83], 0, v[128:129]
	s_barrier
	ds_read_b128 v[158:161], v152 offset:16384
	ds_read_b128 v[162:165], v152 offset:17408
	ds_read_b128 v[166:169], v152 offset:18432
	ds_read_b128 v[170:173], v152 offset:19456
	ds_read_b128 v[174:177], v152 offset:20480
	ds_read_b128 v[178:181], v152 offset:21504
	ds_read_b128 v[182:185], v152 offset:22528
	ds_read_b128 v[198:201], v152 offset:23552
	global_load_lds_dwordx4 v[234:235], off
	v_lshl_add_u64 v[236:237], s[82:83], 0, v[130:131]
	s_mov_b32 m0, s74
	s_nop 0
	global_load_lds_dwordx4 v[236:237], off
	s_barrier
	s_waitcnt lgkmcnt(0)
	s_setprio 1
	s_waitcnt lgkmcnt(0)
	v_mfma_f32_16x16x32_bf16 v[60:63], v[136:139], v[158:161], v[60:63]
	v_mfma_f32_16x16x32_bf16 v[56:59], v[146:149], v[158:161], v[56:59]
	v_mfma_f32_16x16x32_bf16 v[44:47], v[136:139], v[166:169], v[44:47]
	v_mfma_f32_16x16x32_bf16 v[40:43], v[146:149], v[166:169], v[40:43]
	v_mfma_f32_16x16x32_bf16 v[28:31], v[136:139], v[174:177], v[28:31]
	v_mfma_f32_16x16x32_bf16 v[24:27], v[146:149], v[174:177], v[24:27]
	v_mfma_f32_16x16x32_bf16 v[12:15], v[136:139], v[182:185], v[12:15]
	v_mfma_f32_16x16x32_bf16 v[8:11], v[146:149], v[182:185], v[8:11]
	v_mfma_f32_16x16x32_bf16 v[60:63], v[140:143], v[162:165], v[60:63]
	v_mfma_f32_16x16x32_bf16 v[56:59], v[154:157], v[162:165], v[56:59]
	v_mfma_f32_16x16x32_bf16 v[44:47], v[140:143], v[170:173], v[44:47]
	v_mfma_f32_16x16x32_bf16 v[40:43], v[154:157], v[170:173], v[40:43]
	v_mfma_f32_16x16x32_bf16 v[28:31], v[140:143], v[178:181], v[28:31]
	v_mfma_f32_16x16x32_bf16 v[24:27], v[154:157], v[178:181], v[24:27]
	v_mfma_f32_16x16x32_bf16 v[12:15], v[140:143], v[198:201], v[12:15]
	v_mfma_f32_16x16x32_bf16 v[8:11], v[154:157], v[198:201], v[8:11]
	s_setprio 0
	s_barrier
; #define PG8_STAGE(bufoff, gbase, voff) do { _Pragma("unroll") for (int _i = 0; _i < 2; ++_i) \
;     __builtin_amdgcn_global_load_lds((const unsigned*)((const char*)(gbase) + (voff)[_i]), (LAS unsigned*)(lds + (bufoff) + ldsw + _i * 8192), 16, 0, 0); } while (0)
; #define PG8_LDA(dst, b, h) do { _Pragma("unroll") for (int m = 0; m < 4; ++m) _Pragma("unroll") for (int k = 0; k < 2; ++k) dst[m][k] = *(const LAS bf16x8*)(lds + PG8_SA(b, h) + aoff + m * 2048 + k * 1024); } while (0)
; #define PG8_LDB(dst, b, h) do { _Pragma("unroll") for (int n = 0; n < 2; ++n) _Pragma("unroll") for (int k = 0; k < 2; ++k) dst[n][k] = *(const LAS bf16x8*)(lds + PG8_SB(b, h) + boff + n * 2048 + k * 1024); } while (0)
; #define PG8_BAR __builtin_amdgcn_s_barrier()
; template <class Epi, class Sched>
; __device__ __forceinline__ void gemm_phase(LAS unsigned char* lds, const Gemm g, const Sched& S, const Epi& E) {
;     ...
;     for (int t = 0; t < nt; t += 2) {
;       const bool last = (t == nt - 2);
;       const char* a1 = cA + (size_t)(t + 1) * kstep;
;       const char* a2 = last ? nA : cA + (size_t)(t + 2) * kstep; const char* b2 = last ? nB : cB + (size_t)(t + 2) * kstep;
;       const char* a3 = a2 + kstep; const char* b3 = b2 + kstep;
;       PG8_LDB(B0, 0, 0); PG8_SCHED; PG8_LDA(At, 0, 0); PG8_STAGE(PG8_SA(1, 1), a1 + hstepA, voffA);
;       PG8_WAIT_L(8); PG8_BAR; PG8_WAIT_L(0); PG8_MMA(0, 0, At, B0); PG8_BAR; PG8_SCHED;
;       PG8_LDB(B1, 0, 1); PG8_STAGE(PG8_SB(0, 0), b2, voffB);
;       PG8_BAR; PG8_WAIT_L(0); PG8_MMA(0, 1, At, B1); PG8_BAR;
;       PG8_LDA(At, 0, 1); PG8_STAGE(PG8_SA(0, 0), a2, voffA);
;       PG8_BAR; PG8_WAIT_L(0); PG8_MMA(1, 0, At, B0); PG8_BAR; PG8_SCHED;
;       PG8_STAGE(PG8_SB(0, 1), b2 + hstepB, voffB);
;       PG8_WAIT_V(6); PG8_BAR; PG8_MMA(1, 1, At, B1); PG8_BAR;
;       PG8_LDB(B0, 1, 0); PG8_SCHED; PG8_LDA(At, 1, 0); PG8_STAGE(PG8_SA(0, 1), a2 + hstepA, voffA);
;       PG8_WAIT_L(8); PG8_BAR; PG8_WAIT_L(0); PG8_MMA(0, 0, At, B0); PG8_BAR; PG8_SCHED;
;       PG8_LDB(B1, 1, 1); PG8_STAGE(PG8_SB(1, 0), b3, voffB);
;       PG8_BAR; PG8_WAIT_L(0); PG8_MMA(0, 1, At, B1); PG8_BAR;
;       PG8_LDA(At, 1, 1); PG8_STAGE(PG8_SA(1, 0), a3, voffA);
;       PG8_BAR; PG8_WAIT_L(0); PG8_MMA(1, 0, At, B0); PG8_BAR; PG8_SCHED;
;       PG8_STAGE(PG8_SB(1, 1), b3 + hstepB, voffB);
;       PG8_WAIT_V(6); PG8_BAR; PG8_MMA(1, 1, At, B1); PG8_BAR;
	s_add_u32 s36, s38, 0x40000
	s_addc_u32 s37, s39, 0
	s_add_i32 s76, s77, s68
	v_lshl_add_u64 v[136:137], s[36:37], 0, v[128:129]
	s_mov_b32 m0, s76
	s_nop 0
	global_load_lds_dwordx4 v[136:137], off
	v_lshl_add_u64 v[136:137], s[36:37], 0, v[130:131]
	s_add_i32 m0, s76, 0x2000
	s_nop 0
	global_load_lds_dwordx4 v[136:137], off
	s_waitcnt vmcnt(6)
	s_barrier
	s_setprio 1
	v_mfma_f32_16x16x32_bf16 v[52:55], v[214:217], v[158:161], v[52:55]
	v_mfma_f32_16x16x32_bf16 v[48:51], v[222:225], v[158:161], v[48:51]
	v_mfma_f32_16x16x32_bf16 v[36:39], v[214:217], v[166:169], v[36:39]
	v_mfma_f32_16x16x32_bf16 v[32:35], v[222:225], v[166:169], v[32:35]
	v_mfma_f32_16x16x32_bf16 v[20:23], v[214:217], v[174:177], v[20:23]
	v_mfma_f32_16x16x32_bf16 v[16:19], v[222:225], v[174:177], v[16:19]
	v_mfma_f32_16x16x32_bf16 v[4:7], v[214:217], v[182:185], v[4:7]
	v_mfma_f32_16x16x32_bf16 v[0:3], v[222:225], v[182:185], v[0:3]
	v_mfma_f32_16x16x32_bf16 v[52:55], v[218:221], v[162:165], v[52:55]
	v_mfma_f32_16x16x32_bf16 v[48:51], v[226:229], v[162:165], v[48:51]
	v_mfma_f32_16x16x32_bf16 v[36:39], v[218:221], v[170:173], v[36:39]
	v_mfma_f32_16x16x32_bf16 v[32:35], v[226:229], v[170:173], v[32:35]
	v_mfma_f32_16x16x32_bf16 v[20:23], v[218:221], v[178:181], v[20:23]
	v_mfma_f32_16x16x32_bf16 v[16:19], v[226:229], v[178:181], v[16:19]
	v_mfma_f32_16x16x32_bf16 v[4:7], v[218:221], v[198:201], v[4:7]
	v_mfma_f32_16x16x32_bf16 v[0:3], v[226:229], v[198:201], v[0:3]
	s_setprio 0
	s_add_i32 s76, 16, 0x18000
	v_add_u32_e32 v153, s76, v150
	s_barrier
	ds_read_b128 v[136:139], v153
	ds_read_b128 v[140:143], v153 offset:1024
	ds_read_b128 v[146:149], v153 offset:2048
	ds_read_b128 v[154:157], v153 offset:3072
	s_add_u32 s36, s82, 0x40000
	s_addc_u32 s37, s83, 0
	s_mov_b32 m0, s75
	v_lshl_add_u64 v[214:215], s[36:37], 0, v[128:129]
	ds_read_b128 v[158:161], v152 offset:32768
	ds_read_b128 v[162:165], v152 offset:33792
	ds_read_b128 v[166:169], v152 offset:34816
	ds_read_b128 v[170:173], v152 offset:35840
	ds_read_b128 v[174:177], v152 offset:36864
	ds_read_b128 v[178:181], v152 offset:37888
	ds_read_b128 v[182:185], v152 offset:38912
	ds_read_b128 v[198:201], v152 offset:39936
	global_load_lds_dwordx4 v[214:215], off
	v_lshl_add_u64 v[214:215], s[36:37], 0, v[130:131]
	s_mov_b32 m0, s86
	s_nop 0
	global_load_lds_dwordx4 v[214:215], off
	s_waitcnt lgkmcnt(8)
	s_barrier
	s_waitcnt lgkmcnt(0)
	s_setprio 1
	s_waitcnt lgkmcnt(0)
	v_mfma_f32_16x16x32_bf16 v[124:127], v[136:139], v[158:161], v[124:127]
	v_mfma_f32_16x16x32_bf16 v[120:123], v[146:149], v[158:161], v[120:123]
	v_mfma_f32_16x16x32_bf16 v[108:111], v[136:139], v[166:169], v[108:111]
	v_mfma_f32_16x16x32_bf16 v[104:107], v[146:149], v[166:169], v[104:107]
	v_mfma_f32_16x16x32_bf16 v[92:95], v[136:139], v[174:177], v[92:95]
	v_mfma_f32_16x16x32_bf16 v[88:91], v[146:149], v[174:177], v[88:91]
	v_mfma_f32_16x16x32_bf16 v[76:79], v[136:139], v[182:185], v[76:79]
	v_mfma_f32_16x16x32_bf16 v[72:75], v[146:149], v[182:185], v[72:75]
	v_mfma_f32_16x16x32_bf16 v[124:127], v[140:143], v[162:165], v[124:127]
	v_mfma_f32_16x16x32_bf16 v[120:123], v[154:157], v[162:165], v[120:123]
	v_mfma_f32_16x16x32_bf16 v[108:111], v[140:143], v[170:173], v[108:111]
	v_mfma_f32_16x16x32_bf16 v[104:107], v[154:157], v[170:173], v[104:107]
	v_mfma_f32_16x16x32_bf16 v[92:95], v[140:143], v[178:181], v[92:95]
	v_mfma_f32_16x16x32_bf16 v[88:91], v[154:157], v[178:181], v[88:91]
	v_mfma_f32_16x16x32_bf16 v[76:79], v[140:143], v[198:201], v[76:79]
	v_mfma_f32_16x16x32_bf16 v[72:75], v[154:157], v[198:201], v[72:75]
	s_setprio 0
	s_barrier
	s_add_i32 s77, 16, 0x1c000
	s_add_i32 s36, s76, s68
	v_add_u32_e32 v153, s77, v150
	v_lshl_add_u64 v[230:231], v[230:231], 0, s[62:63]
	s_mov_b32 m0, s36
	ds_read_b128 v[214:217], v153
	ds_read_b128 v[218:221], v153 offset:1024
	ds_read_b128 v[222:225], v153 offset:2048
	ds_read_b128 v[226:229], v153 offset:3072
	global_load_lds_dwordx4 v[230:231], off
	v_lshl_add_u64 v[230:231], v[232:233], 0, s[62:63]
	s_add_i32 m0, s36, 0x2000
	s_nop 0
	global_load_lds_dwordx4 v[230:231], off
	s_barrier
	s_waitcnt lgkmcnt(0)
	s_setprio 1
	s_waitcnt lgkmcnt(0)
	v_mfma_f32_16x16x32_bf16 v[116:119], v[214:217], v[158:161], v[116:119]
	v_mfma_f32_16x16x32_bf16 v[112:115], v[222:225], v[158:161], v[112:115]
	v_mfma_f32_16x16x32_bf16 v[100:103], v[214:217], v[166:169], v[100:103]
	v_mfma_f32_16x16x32_bf16 v[96:99], v[222:225], v[166:169], v[96:99]
	v_mfma_f32_16x16x32_bf16 v[84:87], v[214:217], v[174:177], v[84:87]
	v_mfma_f32_16x16x32_bf16 v[80:83], v[222:225], v[174:177], v[80:83]
	v_mfma_f32_16x16x32_bf16 v[68:71], v[214:217], v[182:185], v[68:71]
	v_mfma_f32_16x16x32_bf16 v[64:67], v[222:225], v[182:185], v[64:67]
	v_mfma_f32_16x16x32_bf16 v[116:119], v[218:221], v[162:165], v[116:119]
	v_mfma_f32_16x16x32_bf16 v[112:115], v[226:229], v[162:165], v[112:115]
	v_mfma_f32_16x16x32_bf16 v[100:103], v[218:221], v[170:173], v[100:103]
	v_mfma_f32_16x16x32_bf16 v[96:99], v[226:229], v[170:173], v[96:99]
	v_mfma_f32_16x16x32_bf16 v[84:87], v[218:221], v[178:181], v[84:87]
	v_mfma_f32_16x16x32_bf16 v[80:83], v[226:229], v[178:181], v[80:83]
	v_mfma_f32_16x16x32_bf16 v[68:71], v[218:221], v[198:201], v[68:71]
	v_mfma_f32_16x16x32_bf16 v[64:67], v[226:229], v[198:201], v[64:67]
	s_setprio 0
	s_mov_b32 m0, s87
	v_lshl_add_u64 v[230:231], v[234:235], 0, s[62:63]
	s_barrier
; __device__ __forceinline__ float sigmoidf_(float v) { return __builtin_amdgcn_rcpf(1.0f + __expf(-v)); }
; __device__ __forceinline__ float siluf_(float v) { return v * sigmoidf_(v); }
; __device__ __forceinline__ void store_bf16x4(bf16_t* p, f32x4 v) { u32x2 w; w.x = cvt_pk_bf16(v[0], v[1]); w.y = cvt_pk_bf16(v[2], v[3]); *(u32x2*)p = w; }
; #define PG8_STAGE(bufoff, gbase, voff) do { _Pragma("unroll") for (int _i = 0; _i < 2; ++_i) \
;     __builtin_amdgcn_global_load_lds((const unsigned*)((const char*)(gbase) + (voff)[_i]), (LAS unsigned*)(lds + (bufoff) + ldsw + _i * 8192), 16, 0, 0); } while (0)
; #define PG8_LDA(dst, b, h) do { _Pragma("unroll") for (int m = 0; m < 4; ++m) _Pragma("unroll") for (int k = 0; k < 2; ++k) dst[m][k] = *(const LAS bf16x8*)(lds + PG8_SA(b, h) + aoff + m * 2048 + k * 1024); } while (0)
; #define PG8_WAIT_V(n) asm volatile("s_waitcnt vmcnt(" #n ")" ::: "memory")
; template <class Epi, class Sched>
; __device__ __forceinline__ void gemm_phase(LAS unsigned char* lds, const Gemm g, const Sched& S, const Epi& E) {
;     ...
;       PG8_WAIT_L(8); PG8_BAR; PG8_WAIT_L(0); PG8_MMA(0, 0, At, B0); PG8_BAR; PG8_SCHED;
;       PG8_LDB(B1, 1, 1); PG8_STAGE(PG8_SB(1, 0), b3, voffB);
;       PG8_BAR; PG8_WAIT_L(0); PG8_MMA(0, 1, At, B1); PG8_BAR;
;       PG8_LDA(At, 1, 1); PG8_STAGE(PG8_SA(1, 0), a3, voffA);
;       PG8_BAR; PG8_WAIT_L(0); PG8_MMA(1, 0, At, B0); PG8_BAR; PG8_SCHED;
;       PG8_STAGE(PG8_SB(1, 1), b3 + hstepB, voffB);
;       PG8_WAIT_V(6); PG8_BAR; PG8_MMA(1, 1, At, B1); PG8_BAR;
;   __device__ __forceinline__ void operator()(const f32x4 (&acc)[2][2][4][2], const pg8::Unit& u, int wr, int wc, int fr, int fq) const {
;     const int pn = u.pn;
;     EPI_LOOP(
;       if (pn < 2) { f32x4 o; for (int j = 0; j < 4; ++j) o[j] = siluf_(v[j]); store_bf16x4(QH + (size_t)row * 512 + col, o); }
;       else if (pn < 6) { const int c = col - 512; const f32x4 lb = *(const f32x4*)(LBj + c); f32x4 o; for (int j = 0; j < 4; ++j) o[j] = lb[j] + (1.f - lb[j]) * sigmoidf_(v[j]); *(f32x4*)(F + (size_t)row * 1024 + c) = o; }
;       else if (pn < 8) { store_bf16x4(VH + (size_t)row * 512 + (col - 1536), v); }
;       else if (pn < 10) { f32x4 o; for (int j = 0; j < 4; ++j) o[j] = siluf_(v[j]); store_bf16x4(G + (size_t)row * 512 + (col - 2048), o); }
;       else { store_bf16x4(CQ + (size_t)row * 768 + (col - 2560), v); }
	ds_read_b128 v[158:161], v152 offset:49152
	ds_read_b128 v[162:165], v152 offset:50176
	ds_read_b128 v[166:169], v152 offset:51200
	ds_read_b128 v[170:173], v152 offset:52224
	ds_read_b128 v[174:177], v152 offset:53248
	ds_read_b128 v[178:181], v152 offset:54272
	ds_read_b128 v[182:185], v152 offset:55296
	ds_read_b128 v[198:201], v152 offset:56320
	global_load_lds_dwordx4 v[230:231], off
	v_lshl_add_u64 v[230:231], v[236:237], 0, s[62:63]
	s_mov_b32 m0, s88
	s_nop 0
	global_load_lds_dwordx4 v[230:231], off
	s_barrier
	s_waitcnt lgkmcnt(0)
	s_setprio 1
	s_waitcnt lgkmcnt(0)
	v_mfma_f32_16x16x32_bf16 v[60:63], v[136:139], v[158:161], v[60:63]
	v_mfma_f32_16x16x32_bf16 v[56:59], v[146:149], v[158:161], v[56:59]
	v_mfma_f32_16x16x32_bf16 v[44:47], v[136:139], v[166:169], v[44:47]
	v_mfma_f32_16x16x32_bf16 v[40:43], v[146:149], v[166:169], v[40:43]
	v_mfma_f32_16x16x32_bf16 v[28:31], v[136:139], v[174:177], v[28:31]
	v_mfma_f32_16x16x32_bf16 v[24:27], v[146:149], v[174:177], v[24:27]
	v_mfma_f32_16x16x32_bf16 v[12:15], v[136:139], v[182:185], v[12:15]
	v_mfma_f32_16x16x32_bf16 v[8:11], v[146:149], v[182:185], v[8:11]
	v_mfma_f32_16x16x32_bf16 v[60:63], v[140:143], v[162:165], v[60:63]
	v_mfma_f32_16x16x32_bf16 v[56:59], v[154:157], v[162:165], v[56:59]
	v_mfma_f32_16x16x32_bf16 v[44:47], v[140:143], v[170:173], v[44:47]
	v_mfma_f32_16x16x32_bf16 v[40:43], v[154:157], v[170:173], v[40:43]
	v_mfma_f32_16x16x32_bf16 v[28:31], v[140:143], v[178:181], v[28:31]
	v_mfma_f32_16x16x32_bf16 v[24:27], v[154:157], v[178:181], v[24:27]
	v_mfma_f32_16x16x32_bf16 v[12:15], v[140:143], v[198:201], v[12:15]
	v_mfma_f32_16x16x32_bf16 v[8:11], v[154:157], v[198:201], v[8:11]
	s_setprio 0
	s_barrier
	s_add_u32 s36, s38, 0x40080
	s_addc_u32 s37, s39, 0
	s_add_i32 s38, s77, s68
	v_lshl_add_u64 v[136:137], s[36:37], 0, v[128:129]
	s_mov_b32 m0, s38
	s_nop 0
	global_load_lds_dwordx4 v[136:137], off
	v_lshl_add_u64 v[136:137], s[36:37], 0, v[130:131]
	s_add_i32 m0, s38, 0x2000
	s_nop 0
	global_load_lds_dwordx4 v[136:137], off
	s_waitcnt vmcnt(6)
	s_barrier
	s_setprio 1
	v_mfma_f32_16x16x32_bf16 v[52:55], v[214:217], v[158:161], v[52:55]
	v_mfma_f32_16x16x32_bf16 v[48:51], v[222:225], v[158:161], v[48:51]
	v_mfma_f32_16x16x32_bf16 v[36:39], v[214:217], v[166:169], v[36:39]
	v_mfma_f32_16x16x32_bf16 v[32:35], v[222:225], v[166:169], v[32:35]
	v_mfma_f32_16x16x32_bf16 v[20:23], v[214:217], v[174:177], v[20:23]
	v_mfma_f32_16x16x32_bf16 v[16:19], v[222:225], v[174:177], v[16:19]
	v_mfma_f32_16x16x32_bf16 v[4:7], v[214:217], v[182:185], v[4:7]
	v_mfma_f32_16x16x32_bf16 v[0:3], v[222:225], v[182:185], v[0:3]
	v_mfma_f32_16x16x32_bf16 v[52:55], v[218:221], v[162:165], v[52:55]
	v_mfma_f32_16x16x32_bf16 v[48:51], v[226:229], v[162:165], v[48:51]
	v_mfma_f32_16x16x32_bf16 v[36:39], v[218:221], v[170:173], v[36:39]
	v_mfma_f32_16x16x32_bf16 v[32:35], v[226:229], v[170:173], v[32:35]
	v_mfma_f32_16x16x32_bf16 v[20:23], v[218:221], v[178:181], v[20:23]
	v_mfma_f32_16x16x32_bf16 v[16:19], v[226:229], v[178:181], v[16:19]
	v_mfma_f32_16x16x32_bf16 v[4:7], v[218:221], v[198:201], v[4:7]
	v_mfma_f32_16x16x32_bf16 v[0:3], v[226:229], v[198:201], v[0:3]
	s_setprio 0
	s_add_i32 s84, s84, 2
	s_add_u32 s78, s78, 0x100
	s_addc_u32 s79, s79, 0
	s_add_u32 s25, s25, 0x100
	s_addc_u32 s27, s27, 0
	s_cmp_gt_u32 s84, 13
	s_barrier
	s_cbranch_scc0 .LBB0_1541
	s_cmp_gt_i32 s8, 1
	s_cselect_b64 s[82:83], -1, 0
	s_cmp_gt_u32 s8, 5
	v_lshl_add_u32 v138, s10, 8, v145
	s_cselect_b64 s[38:39], -1, 0
	s_cmp_gt_u32 s8, 7
	v_lshl_or_b32 v136, s8, 8, v151
	s_cselect_b64 s[84:85], -1, 0
	s_cmp_gt_u32 s8, 9
	v_ashrrev_i32_e32 v139, 31, v138
	v_mad_i64_i32 v[146:147], s[8:9], v138, s64, 0
	s_cselect_b64 s[78:79], -1, 0
	v_lshlrev_b64 v[142:143], 10, v[138:139]
	v_lshlrev_b64 v[140:141], 12, v[138:139]
	v_and_b32_e32 v244, 16, v187
	v_lshrrev_b32_e32 v245, 1, v244
	v_add_u32_e32 v244, v244, v245
	v_mov_b32_e32 v245, v144
	s_andn2_b64 vcc, s[82:83], s[38:39]
	s_cbranch_vccz .Llbv_skip
	v_mov_b32_e32 v148, v136
	v_ashrrev_i32_e32 v149, 31, v136
	v_lshlrev_b64 v[148:149], 2, v[148:149]
	v_lshl_add_u64 v[148:149], s[18:19], 0, v[148:149]
	global_load_dwordx4 v[238:241], v[148:149], off offset:-2048
	global_load_dwordx4 v[242:245], v[148:149], off offset:-1984
	global_load_dwordx4 v[246:249], v[148:149], off offset:-1536
	global_load_dwordx4 v[250:253], v[148:149], off offset:-1472
	s_waitcnt vmcnt(0)
.Llbv_skip:
	s_mov_b64 s[8:9], -1
	s_and_b64 vcc, exec, s[82:83]
	s_cbranch_vccz .LBB0_1556
	s_and_b64 vcc, exec, s[38:39]
	s_cbranch_vccz .LBB0_1553
	s_and_b64 vcc, exec, s[84:85]
	s_cbranch_vccz .LBB0_1550
	s_and_b64 vcc, exec, s[78:79]
	s_cbranch_vccz .LBB0_1547
	v_lshl_add_u64 v[148:149], s[46:47], 0, v[146:147]
	v_mov_b32_e32 v137, v144
	v_lshl_add_u64 v[148:149], v[136:137], 1, v[148:149]
	v_add_co_u32_e32 v148, vcc, 0xfffff000, v148
	v_cvt_pk_bf16_f32 v238, v124, v125
	v_cvt_pk_bf16_f32 v239, v126, v127
	s_mov_b64 s[8:9], 0
	s_nop 0
	v_addc_co_u32_e32 v149, vcc, -1, v149, vcc
.LBB0_1547:
	s_andn2_b64 vcc, exec, s[8:9]
	s_cbranch_vccnz .LBB0_1549
	v_mul_f32_e32 v137, 0xbfb8aa3b, v124
	v_mul_f32_e32 v148, 0xbfb8aa3b, v126
	v_mul_f32_e32 v149, 0xbfb8aa3b, v127
	v_exp_f32_e32 v137, v137
	v_exp_f32_e32 v148, v148
	v_exp_f32_e32 v149, v149
	v_mul_f32_e32 v139, 0xbfb8aa3b, v125
	v_exp_f32_e32 v139, v139
	v_add_f32_e32 v137, 1.0, v137
	v_add_f32_e32 v148, 1.0, v148
	v_add_f32_e32 v149, 1.0, v149
	v_rcp_f32_e32 v137, v137
	v_rcp_f32_e32 v148, v148
	v_rcp_f32_e32 v149, v149
	v_add_f32_e32 v139, 1.0, v139
	v_rcp_f32_e32 v139, v139
	v_mul_f32_e32 v153, v124, v137
	v_mul_f32_e32 v155, v126, v148
	v_mul_f32_e32 v156, v127, v149
	v_lshl_add_u64 v[148:149], s[48:49], 0, v[142:143]
	v_mov_b32_e32 v137, v144
	v_lshl_add_u64 v[148:149], v[136:137], 1, v[148:149]
	v_mul_f32_e32 v139, v125, v139
	v_cvt_pk_bf16_f32 v238, v153, v139
	v_cvt_pk_bf16_f32 v239, v155, v156

; __device__ __forceinline__ void store_bf16x4(bf16_t* p, f32x4 v) { u32x2 w; w.x = cvt_pk_bf16(v[0], v[1]); w.y = cvt_pk_bf16(v[2], v[3]); *(u32x2*)p = w; }
;   __device__ __forceinline__ void operator()(const f32x4 (&acc)[2][2][4][2], const pg8::Unit& u, int wr, int wc, int fr, int fq) const {
;     ...
;       else if (pn < 8) { store_bf16x4(VH + (size_t)row * 512 + (col - 1536), v); }
.LBB0_1550:
	s_andn2_b64 vcc, exec, s[8:9]
	s_cbranch_vccnz .LBB0_1552
	v_lshl_add_u64 v[148:149], s[16:17], 0, v[142:143]
	v_mov_b32_e32 v137, v144
	v_lshl_add_u64 v[148:149], v[136:137], 1, v[148:149]
	v_cvt_pk_bf16_f32 v238, v124, v125
	v_cvt_pk_bf16_f32 v239, v126, v127

; __device__ __forceinline__ float sigmoidf_(float v) { return __builtin_amdgcn_rcpf(1.0f + __expf(-v)); }
; __device__ __forceinline__ float siluf_(float v) { return v * sigmoidf_(v); }
; __device__ __forceinline__ void store_bf16x4(bf16_t* p, f32x4 v) { u32x2 w; w.x = cvt_pk_bf16(v[0], v[1]); w.y = cvt_pk_bf16(v[2], v[3]); *(u32x2*)p = w; }
;   __device__ __forceinline__ void operator()(const f32x4 (&acc)[2][2][4][2], const pg8::Unit& u, int wr, int wc, int fr, int fq) const {
;     ...
;       if (pn < 2) { f32x4 o; for (int j = 0; j < 4; ++j) o[j] = siluf_(v[j]); store_bf16x4(QH + (size_t)row * 512 + col, o); }
;       else if (pn < 6) { const int c = col - 512; const f32x4 lb = *(const f32x4*)(LBj + c); f32x4 o; for (int j = 0; j < 4; ++j) o[j] = lb[j] + (1.f - lb[j]) * sigmoidf_(v[j]); *(f32x4*)(F + (size_t)row * 1024 + c) = o; }
;       else if (pn < 8) { store_bf16x4(VH + (size_t)row * 512 + (col - 1536), v); }
;       else if (pn < 10) { f32x4 o; for (int j = 0; j < 4; ++j) o[j] = siluf_(v[j]); store_bf16x4(G + (size_t)row * 512 + (col - 2048), o); }
;       else { store_bf16x4(CQ + (size_t)row * 768 + (col - 2560), v); }
.LBB0_1556:
	s_andn2_b64 vcc, exec, s[8:9]
	v_lshl_add_u64 v[148:149], s[14:15], 0, v[142:143]
	v_ashrrev_i32_e32 v137, 31, v136
	s_cbranch_vccnz .LBB0_1558
	v_mul_f32_e32 v139, 0xbfb8aa3b, v124
	v_exp_f32_e32 v139, v139
	s_nop 0
	v_add_f32_e32 v139, 1.0, v139
	v_rcp_f32_e32 v139, v139
	s_nop 0
	v_mul_f32_e32 v139, v124, v139
	v_mul_f32_e32 v124, 0xbfb8aa3b, v125
	v_exp_f32_e32 v124, v124
	s_nop 0
	v_add_f32_e32 v124, 1.0, v124
	v_rcp_f32_e32 v124, v124
	s_nop 0
	v_mul_f32_e32 v153, v125, v124
	v_mul_f32_e32 v124, 0xbfb8aa3b, v126
	v_exp_f32_e32 v124, v124
	s_nop 0
	v_add_f32_e32 v124, 1.0, v124
	v_rcp_f32_e32 v124, v124
	s_nop 0
	v_mul_f32_e32 v154, v126, v124
	v_mul_f32_e32 v124, 0xbfb8aa3b, v127
	v_exp_f32_e32 v124, v124
	v_cvt_pk_bf16_f32 v238, v139, v153
	s_nop 0
	v_add_f32_e32 v124, 1.0, v124
	v_rcp_f32_e32 v124, v124
	s_nop 0
	v_mul_f32_e32 v127, v127, v124
	v_lshl_add_u64 v[124:125], v[136:137], 1, v[148:149]
	v_cvt_pk_bf16_f32 v239, v154, v127
.LBB0_1558:
	v_cndmask_b32_e64 v124, 0, 1, s[82:83]
	v_cmp_ne_u32_e64 s[10:11], 1, v124
	v_cndmask_b32_e64 v124, 0, 1, s[38:39]
	s_mov_b64 s[24:25], -1
	s_andn2_b64 vcc, exec, s[82:83]
	v_cmp_ne_u32_e64 s[8:9], 1, v124
	s_cbranch_vccnz .LBB0_1600
	s_and_b64 vcc, exec, s[8:9]
	s_cbranch_vccnz .LBB0_1569
	s_andn2_b64 vcc, exec, s[84:85]
	s_cbranch_vccnz .LBB0_1566
	s_andn2_b64 vcc, exec, s[78:79]
	s_cbranch_vccnz .LBB0_1563
	v_lshl_add_u64 v[124:125], s[46:47], 0, v[146:147]
	v_mov_b32_e32 v126, v136
	v_mov_b32_e32 v127, v144
	v_lshl_add_u64 v[124:125], v[126:127], 1, v[124:125]
	v_add_co_u32_e32 v124, vcc, 0xfffff000, v124
	s_mov_b64 s[24:25], 0
	s_nop 0
	v_addc_co_u32_e32 v125, vcc, -1, v125, vcc
	v_cvt_pk_bf16_f32 v240, v120, v121
	v_cvt_pk_bf16_f32 v241, v122, v123
	s_nop 1
	v_permlane16_swap_b32_e32 v238, v240
	v_permlane16_swap_b32_e32 v239, v241
	v_lshl_add_u64 v[242:243], v[124:125], 0, v[244:245]
	global_store_dwordx4 v[242:243], v[238:241], off offset:-1024
.LBB0_1563:
	s_andn2_b64 vcc, exec, s[24:25]
	s_cbranch_vccnz .LBB0_1565
	v_mul_f32_e32 v124, 0xbfb8aa3b, v120
	v_mul_f32_e32 v125, 0xbfb8aa3b, v121
	v_mul_f32_e32 v126, 0xbfb8aa3b, v122
	v_mul_f32_e32 v127, 0xbfb8aa3b, v123
	v_exp_f32_e32 v124, v124
	v_exp_f32_e32 v125, v125
	v_exp_f32_e32 v126, v126
	v_exp_f32_e32 v127, v127
	v_add_f32_e32 v124, 1.0, v124
	v_add_f32_e32 v125, 1.0, v125
	v_add_f32_e32 v126, 1.0, v126
	v_add_f32_e32 v127, 1.0, v127
	v_rcp_f32_e32 v124, v124
	v_rcp_f32_e32 v125, v125
	v_rcp_f32_e32 v126, v126
	v_rcp_f32_e32 v127, v127
	v_mul_f32_e32 v139, v120, v124
	v_mul_f32_e32 v153, v121, v125
	v_mul_f32_e32 v154, v122, v126
	v_mul_f32_e32 v155, v123, v127
	v_lshl_add_u64 v[124:125], s[48:49], 0, v[142:143]
	v_mov_b32_e32 v126, v136
	v_mov_b32_e32 v127, v144
	v_lshl_add_u64 v[124:125], v[126:127], 1, v[124:125]
	v_cvt_pk_bf16_f32 v240, v139, v153
	v_cvt_pk_bf16_f32 v241, v154, v155
	s_nop 1
	v_permlane16_swap_b32_e32 v238, v240
	v_permlane16_swap_b32_e32 v239, v241
	v_lshl_add_u64 v[242:243], v[124:125], 0, v[244:245]
	global_store_dwordx4 v[242:243], v[238:241], off offset:-4096

; __device__ __forceinline__ void store_bf16x4(bf16_t* p, f32x4 v) { u32x2 w; w.x = cvt_pk_bf16(v[0], v[1]); w.y = cvt_pk_bf16(v[2], v[3]); *(u32x2*)p = w; }
;   __device__ __forceinline__ void operator()(const f32x4 (&acc)[2][2][4][2], const pg8::Unit& u, int wr, int wc, int fr, int fq) const {
;     ...
;       else if (pn < 8) { store_bf16x4(VH + (size_t)row * 512 + (col - 1536), v); }
.LBB0_1566:
	s_andn2_b64 vcc, exec, s[24:25]
	s_cbranch_vccnz .LBB0_1568
	v_lshl_add_u64 v[124:125], s[16:17], 0, v[142:143]
	v_mov_b32_e32 v126, v136
	v_mov_b32_e32 v127, v144
	v_lshl_add_u64 v[124:125], v[126:127], 1, v[124:125]
	v_cvt_pk_bf16_f32 v240, v120, v121
	v_cvt_pk_bf16_f32 v241, v122, v123
	s_nop 1
	v_permlane16_swap_b32_e32 v238, v240
	v_permlane16_swap_b32_e32 v239, v241
	v_lshl_add_u64 v[242:243], v[124:125], 0, v[244:245]
	global_store_dwordx4 v[242:243], v[238:241], off offset:-3072

; __device__ __forceinline__ float siluf_(float v) { return v * sigmoidf_(v); }
; __device__ __forceinline__ void store_bf16x4(bf16_t* p, f32x4 v) { u32x2 w; w.x = cvt_pk_bf16(v[0], v[1]); w.y = cvt_pk_bf16(v[2], v[3]); *(u32x2*)p = w; }
;   __device__ __forceinline__ void operator()(const f32x4 (&acc)[2][2][4][2], const pg8::Unit& u, int wr, int wc, int fr, int fq) const {
;     ...
;       else if (pn < 10) { f32x4 o; for (int j = 0; j < 4; ++j) o[j] = siluf_(v[j]); store_bf16x4(G + (size_t)row * 512 + (col - 2048), o); }
;       else { store_bf16x4(CQ + (size_t)row * 768 + (col - 2560), v); }
.LBB0_1573:
	s_and_b64 vcc, exec, s[8:9]
	s_cbranch_vccnz .LBB0_1583
	s_andn2_b64 vcc, exec, s[84:85]
	s_cbranch_vccnz .LBB0_1580
	s_andn2_b64 vcc, exec, s[78:79]
	s_cbranch_vccnz .LBB0_1577
	v_lshl_add_u64 v[120:121], s[46:47], 0, v[146:147]
	v_mov_b32_e32 v122, v136
	v_mov_b32_e32 v123, v144
	v_lshl_add_u64 v[120:121], v[122:123], 1, v[120:121]
	v_add_co_u32_e32 v120, vcc, 0xfffff000, v120
	s_mov_b64 s[24:25], 0
	s_nop 0
	v_addc_co_u32_e32 v121, vcc, -1, v121, vcc
	v_cvt_pk_bf16_f32 v238, v116, v117
	v_cvt_pk_bf16_f32 v239, v118, v119
.LBB0_1577:
	s_andn2_b64 vcc, exec, s[24:25]
	s_cbranch_vccnz .LBB0_1579
	v_mul_f32_e32 v120, 0xbfb8aa3b, v116
	v_mul_f32_e32 v121, 0xbfb8aa3b, v117
	v_mul_f32_e32 v122, 0xbfb8aa3b, v118
	v_mul_f32_e32 v123, 0xbfb8aa3b, v119
	v_exp_f32_e32 v120, v120
	v_exp_f32_e32 v121, v121
	v_exp_f32_e32 v122, v122
	v_exp_f32_e32 v123, v123
	v_add_f32_e32 v120, 1.0, v120
	v_add_f32_e32 v121, 1.0, v121
	v_add_f32_e32 v122, 1.0, v122
	v_add_f32_e32 v123, 1.0, v123
	v_rcp_f32_e32 v120, v120
	v_rcp_f32_e32 v121, v121
	v_rcp_f32_e32 v122, v122
	v_rcp_f32_e32 v123, v123
	v_mul_f32_e32 v124, v116, v120
	v_mul_f32_e32 v125, v117, v121
	v_mul_f32_e32 v126, v118, v122
	v_mul_f32_e32 v127, v119, v123
	v_lshl_add_u64 v[120:121], s[48:49], 0, v[142:143]
	v_mov_b32_e32 v122, v136
	v_mov_b32_e32 v123, v144
	v_lshl_add_u64 v[120:121], v[122:123], 1, v[120:121]
	v_cvt_pk_bf16_f32 v238, v124, v125
	v_cvt_pk_bf16_f32 v239, v126, v127

; __device__ __forceinline__ void store_bf16x4(bf16_t* p, f32x4 v) { u32x2 w; w.x = cvt_pk_bf16(v[0], v[1]); w.y = cvt_pk_bf16(v[2], v[3]); *(u32x2*)p = w; }
;   __device__ __forceinline__ void operator()(const f32x4 (&acc)[2][2][4][2], const pg8::Unit& u, int wr, int wc, int fr, int fq) const {
;     ...
;       else if (pn < 8) { store_bf16x4(VH + (size_t)row * 512 + (col - 1536), v); }
.LBB0_1580:
	s_andn2_b64 vcc, exec, s[24:25]
	s_cbranch_vccnz .LBB0_1582
	v_lshl_add_u64 v[120:121], s[16:17], 0, v[142:143]
	v_mov_b32_e32 v122, v136
	v_mov_b32_e32 v123, v144
	v_lshl_add_u64 v[120:121], v[122:123], 1, v[120:121]
	v_cvt_pk_bf16_f32 v238, v116, v117
	v_cvt_pk_bf16_f32 v239, v118, v119

; __device__ __forceinline__ float siluf_(float v) { return v * sigmoidf_(v); }
; __device__ __forceinline__ void store_bf16x4(bf16_t* p, f32x4 v) { u32x2 w; w.x = cvt_pk_bf16(v[0], v[1]); w.y = cvt_pk_bf16(v[2], v[3]); *(u32x2*)p = w; }
;   __device__ __forceinline__ void operator()(const f32x4 (&acc)[2][2][4][2], const pg8::Unit& u, int wr, int wc, int fr, int fq) const {
;     ...
;       else if (pn < 10) { f32x4 o; for (int j = 0; j < 4; ++j) o[j] = siluf_(v[j]); store_bf16x4(G + (size_t)row * 512 + (col - 2048), o); }
;       else { store_bf16x4(CQ + (size_t)row * 768 + (col - 2560), v); }
.LBB0_1587:
	s_and_b64 vcc, exec, s[8:9]
	s_cbranch_vccnz .LBB0_1597
	s_andn2_b64 vcc, exec, s[84:85]
	s_cbranch_vccnz .LBB0_1594
	s_andn2_b64 vcc, exec, s[78:79]
	s_cbranch_vccnz .LBB0_1591
	v_lshl_add_u64 v[116:117], s[46:47], 0, v[146:147]
	v_mov_b32_e32 v118, v136
	v_mov_b32_e32 v119, v144
	v_lshl_add_u64 v[116:117], v[118:119], 1, v[116:117]
	v_add_co_u32_e32 v116, vcc, 0xfffff000, v116
	s_mov_b64 s[24:25], 0
	s_nop 0
	v_addc_co_u32_e32 v117, vcc, -1, v117, vcc
	v_cvt_pk_bf16_f32 v240, v112, v113
	v_cvt_pk_bf16_f32 v241, v114, v115
	s_nop 1
	v_permlane16_swap_b32_e32 v238, v240
	v_permlane16_swap_b32_e32 v239, v241
	v_lshl_add_u64 v[242:243], v[116:117], 0, v[244:245]
	global_store_dwordx4 v[242:243], v[238:241], off offset:-768
.LBB0_1591:
	s_andn2_b64 vcc, exec, s[24:25]
	s_cbranch_vccnz .LBB0_1593
	v_mul_f32_e32 v116, 0xbfb8aa3b, v112
	v_mul_f32_e32 v117, 0xbfb8aa3b, v113
	v_mul_f32_e32 v118, 0xbfb8aa3b, v114
	v_mul_f32_e32 v119, 0xbfb8aa3b, v115
	v_exp_f32_e32 v116, v116
	v_exp_f32_e32 v117, v117
	v_exp_f32_e32 v118, v118
	v_exp_f32_e32 v119, v119
	v_add_f32_e32 v116, 1.0, v116
	v_add_f32_e32 v117, 1.0, v117
	v_add_f32_e32 v118, 1.0, v118
	v_add_f32_e32 v119, 1.0, v119
	v_rcp_f32_e32 v116, v116
	v_rcp_f32_e32 v117, v117
	v_rcp_f32_e32 v118, v118
	v_rcp_f32_e32 v119, v119
	v_mul_f32_e32 v120, v112, v116
	v_mul_f32_e32 v121, v113, v117
	v_mul_f32_e32 v122, v114, v118
	v_mul_f32_e32 v123, v115, v119
	v_lshl_add_u64 v[116:117], s[48:49], 0, v[142:143]
	v_mov_b32_e32 v118, v136
	v_mov_b32_e32 v119, v144
	v_lshl_add_u64 v[116:117], v[118:119], 1, v[116:117]
	v_cvt_pk_bf16_f32 v240, v120, v121
	v_cvt_pk_bf16_f32 v241, v122, v123
	s_nop 1
	v_permlane16_swap_b32_e32 v238, v240
	v_permlane16_swap_b32_e32 v239, v241
	v_lshl_add_u64 v[242:243], v[116:117], 0, v[244:245]
	global_store_dwordx4 v[242:243], v[238:241], off offset:-3840

; __device__ __forceinline__ void store_bf16x4(bf16_t* p, f32x4 v) { u32x2 w; w.x = cvt_pk_bf16(v[0], v[1]); w.y = cvt_pk_bf16(v[2], v[3]); *(u32x2*)p = w; }
;   __device__ __forceinline__ void operator()(const f32x4 (&acc)[2][2][4][2], const pg8::Unit& u, int wr, int wc, int fr, int fq) const {
;     ...
;       else if (pn < 8) { store_bf16x4(VH + (size_t)row * 512 + (col - 1536), v); }
.LBB0_1594:
	s_andn2_b64 vcc, exec, s[24:25]
	s_cbranch_vccnz .LBB0_1596
	v_lshl_add_u64 v[116:117], s[16:17], 0, v[142:143]
	v_mov_b32_e32 v118, v136
	v_mov_b32_e32 v119, v144
	v_lshl_add_u64 v[116:117], v[118:119], 1, v[116:117]
	v_cvt_pk_bf16_f32 v240, v112, v113
	v_cvt_pk_bf16_f32 v241, v114, v115
	s_nop 1
	v_permlane16_swap_b32_e32 v238, v240
	v_permlane16_swap_b32_e32 v239, v241
	v_lshl_add_u64 v[242:243], v[116:117], 0, v[244:245]
	global_store_dwordx4 v[242:243], v[238:241], off offset:-2816

; __device__ __forceinline__ float siluf_(float v) { return v * sigmoidf_(v); }
; __device__ __forceinline__ void store_bf16x4(bf16_t* p, f32x4 v) { u32x2 w; w.x = cvt_pk_bf16(v[0], v[1]); w.y = cvt_pk_bf16(v[2], v[3]); *(u32x2*)p = w; }
;   __device__ __forceinline__ void operator()(const f32x4 (&acc)[2][2][4][2], const pg8::Unit& u, int wr, int wc, int fr, int fq) const {
;     ...
;       if (pn < 2) { f32x4 o; for (int j = 0; j < 4; ++j) o[j] = siluf_(v[j]); store_bf16x4(QH + (size_t)row * 512 + col, o); }
.LBB0_1601:
	s_nop 0
	v_mul_f32_e32 v124, 0xbfb8aa3b, v120
	v_exp_f32_e32 v124, v124
	s_nop 0
	v_add_f32_e32 v124, 1.0, v124
	v_rcp_f32_e32 v124, v124
	s_nop 0
	v_mul_f32_e32 v124, v120, v124
	v_mul_f32_e32 v120, 0xbfb8aa3b, v121
	v_exp_f32_e32 v120, v120
	s_nop 0
	v_add_f32_e32 v120, 1.0, v120
	v_rcp_f32_e32 v120, v120
	s_nop 0
	v_mul_f32_e32 v125, v121, v120
	v_mul_f32_e32 v120, 0xbfb8aa3b, v122
	v_exp_f32_e32 v120, v120
	s_nop 0
	v_add_f32_e32 v120, 1.0, v120
	v_rcp_f32_e32 v120, v120
	s_nop 0
	v_mul_f32_e32 v126, v122, v120
	v_mul_f32_e32 v120, 0xbfb8aa3b, v123
	v_exp_f32_e32 v120, v120
	v_cvt_pk_bf16_f32 v240, v124, v125
	s_nop 0
	v_add_f32_e32 v120, 1.0, v120
	v_rcp_f32_e32 v120, v120
	s_nop 0
	v_mul_f32_e32 v123, v123, v120
	v_lshl_add_u64 v[120:121], v[136:137], 1, v[148:149]
	v_cvt_pk_bf16_f32 v241, v126, v123
	s_nop 1
	v_permlane16_swap_b32_e32 v238, v240
	v_permlane16_swap_b32_e32 v239, v241
	v_lshl_add_u64 v[242:243], v[120:121], 0, v[244:245]
	global_store_dwordx4 v[242:243], v[238:241], off
	s_and_b64 vcc, exec, s[10:11]
	s_mov_b64 s[24:25], -1
	s_cbranch_vccz .LBB0_1573

; __device__ __forceinline__ float siluf_(float v) { return v * sigmoidf_(v); }
; __device__ __forceinline__ void store_bf16x4(bf16_t* p, f32x4 v) { u32x2 w; w.x = cvt_pk_bf16(v[0], v[1]); w.y = cvt_pk_bf16(v[2], v[3]); *(u32x2*)p = w; }
;   __device__ __forceinline__ void operator()(const f32x4 (&acc)[2][2][4][2], const pg8::Unit& u, int wr, int wc, int fr, int fq) const {
;     ...
;       if (pn < 2) { f32x4 o; for (int j = 0; j < 4; ++j) o[j] = siluf_(v[j]); store_bf16x4(QH + (size_t)row * 512 + col, o); }
.LBB0_1603:
	s_nop 0
	v_mul_f32_e32 v120, 0xbfb8aa3b, v116
	v_exp_f32_e32 v120, v120
	s_nop 0
	v_add_f32_e32 v120, 1.0, v120
	v_rcp_f32_e32 v120, v120
	s_nop 0
	v_mul_f32_e32 v120, v116, v120
	v_mul_f32_e32 v116, 0xbfb8aa3b, v117
	v_exp_f32_e32 v116, v116
	s_nop 0
	v_add_f32_e32 v116, 1.0, v116
	v_rcp_f32_e32 v116, v116
	s_nop 0
	v_mul_f32_e32 v121, v117, v116
	v_mul_f32_e32 v116, 0xbfb8aa3b, v118
	v_exp_f32_e32 v116, v116
	s_nop 0
	v_add_f32_e32 v116, 1.0, v116
	v_rcp_f32_e32 v116, v116
	s_nop 0
	v_mul_f32_e32 v122, v118, v116
	v_mul_f32_e32 v116, 0xbfb8aa3b, v119
	v_exp_f32_e32 v116, v116
	v_cvt_pk_bf16_f32 v238, v120, v121
	s_nop 0
	v_add_f32_e32 v116, 1.0, v116
	v_rcp_f32_e32 v116, v116
	s_nop 0
	v_mul_f32_e32 v119, v119, v116
	v_lshl_add_u64 v[116:117], v[136:137], 1, v[148:149]
	v_cvt_pk_bf16_f32 v239, v122, v119
	s_and_b64 vcc, exec, s[10:11]
	s_mov_b64 s[24:25], -1
	s_cbranch_vccz .LBB0_1587

; __device__ __forceinline__ float sigmoidf_(float v) { return __builtin_amdgcn_rcpf(1.0f + __expf(-v)); }
; __device__ __forceinline__ float siluf_(float v) { return v * sigmoidf_(v); }
; __device__ __forceinline__ void store_bf16x4(bf16_t* p, f32x4 v) { u32x2 w; w.x = cvt_pk_bf16(v[0], v[1]); w.y = cvt_pk_bf16(v[2], v[3]); *(u32x2*)p = w; }
;   __device__ __forceinline__ void operator()(const f32x4 (&acc)[2][2][4][2], const pg8::Unit& u, int wr, int wc, int fr, int fq) const {
;     ...
;     EPI_LOOP(
;       if (pn < 2) { f32x4 o; for (int j = 0; j < 4; ++j) o[j] = siluf_(v[j]); store_bf16x4(QH + (size_t)row * 512 + col, o); }
;       else if (pn < 6) { const int c = col - 512; const f32x4 lb = *(const f32x4*)(LBj + c); f32x4 o; for (int j = 0; j < 4; ++j) o[j] = lb[j] + (1.f - lb[j]) * sigmoidf_(v[j]); *(f32x4*)(F + (size_t)row * 1024 + c) = o; }
;       else if (pn < 8) { store_bf16x4(VH + (size_t)row * 512 + (col - 1536), v); }
;       else if (pn < 10) { f32x4 o; for (int j = 0; j < 4; ++j) o[j] = siluf_(v[j]); store_bf16x4(G + (size_t)row * 512 + (col - 2048), o); }
;       else { store_bf16x4(CQ + (size_t)row * 768 + (col - 2560), v); }
.LBB0_1605:
	v_mul_f32_e32 v116, 0xbfb8aa3b, v112
	v_exp_f32_e32 v116, v116
	s_nop 0
	v_add_f32_e32 v116, 1.0, v116
	v_rcp_f32_e32 v116, v116
	s_nop 0
	v_mul_f32_e32 v116, v112, v116
	v_mul_f32_e32 v112, 0xbfb8aa3b, v113
	v_exp_f32_e32 v112, v112
	s_nop 0
	v_add_f32_e32 v112, 1.0, v112
	v_rcp_f32_e32 v112, v112
	s_nop 0
	v_mul_f32_e32 v117, v113, v112
	v_mul_f32_e32 v112, 0xbfb8aa3b, v114
	v_exp_f32_e32 v112, v112
	s_nop 0
	v_add_f32_e32 v112, 1.0, v112
	v_rcp_f32_e32 v112, v112
	s_nop 0
	v_mul_f32_e32 v118, v114, v112
	v_mul_f32_e32 v112, 0xbfb8aa3b, v115
	v_exp_f32_e32 v112, v112
	v_cvt_pk_bf16_f32 v240, v116, v117
	s_nop 0
	v_add_f32_e32 v112, 1.0, v112
	v_rcp_f32_e32 v112, v112
	s_nop 0
	v_mul_f32_e32 v115, v115, v112
	v_lshl_add_u64 v[112:113], v[136:137], 1, v[148:149]
	v_cvt_pk_bf16_f32 v241, v118, v115
	s_nop 1
	v_permlane16_swap_b32_e32 v238, v240
	v_permlane16_swap_b32_e32 v239, v241
	v_lshl_add_u64 v[242:243], v[112:113], 0, v[244:245]
	global_store_dwordx4 v[242:243], v[238:241], off offset:256
.LBB0_1606:
	v_or_b32_e32 v112, 16, v138
	v_ashrrev_i32_e32 v113, 31, v112
	v_mad_i64_i32 v[116:117], s[24:25], v112, s64, 0
	v_lshlrev_b64 v[114:115], 10, v[112:113]
	v_lshlrev_b64 v[112:113], 12, v[112:113]
	s_and_b64 vcc, exec, s[10:11]
	s_mov_b64 s[24:25], -1
	s_cbranch_vccnz .LBB0_1662
	s_and_b64 vcc, exec, s[8:9]
	s_cbranch_vccnz .LBB0_1617
	s_andn2_b64 vcc, exec, s[84:85]
	s_cbranch_vccnz .LBB0_1614
	s_andn2_b64 vcc, exec, s[78:79]
	s_cbranch_vccnz .LBB0_1611
	v_lshl_add_u64 v[118:119], s[46:47], 0, v[116:117]
	v_mov_b32_e32 v120, v136
	v_mov_b32_e32 v121, v144
	v_lshl_add_u64 v[118:119], v[120:121], 1, v[118:119]
	v_add_co_u32_e32 v118, vcc, 0xfffff000, v118
	s_mov_b64 s[24:25], 0
	s_nop 0
	v_addc_co_u32_e32 v119, vcc, -1, v119, vcc
	v_cvt_pk_bf16_f32 v238, v108, v109
	v_cvt_pk_bf16_f32 v239, v110, v111
.LBB0_1611:
	s_andn2_b64 vcc, exec, s[24:25]
	s_cbranch_vccnz .LBB0_1613
	v_mul_f32_e32 v118, 0xbfb8aa3b, v108
	v_mul_f32_e32 v119, 0xbfb8aa3b, v109
	v_mul_f32_e32 v120, 0xbfb8aa3b, v110
	v_mul_f32_e32 v121, 0xbfb8aa3b, v111
	v_exp_f32_e32 v118, v118
	v_exp_f32_e32 v119, v119
	v_exp_f32_e32 v120, v120
	v_exp_f32_e32 v121, v121
	v_add_f32_e32 v118, 1.0, v118
	v_add_f32_e32 v119, 1.0, v119
	v_add_f32_e32 v120, 1.0, v120
	v_add_f32_e32 v121, 1.0, v121
	v_rcp_f32_e32 v118, v118
	v_rcp_f32_e32 v119, v119
	v_rcp_f32_e32 v120, v120
	v_rcp_f32_e32 v121, v121
	v_mul_f32_e32 v122, v108, v118
	v_mul_f32_e32 v123, v109, v119
	v_mul_f32_e32 v124, v110, v120
	v_mul_f32_e32 v125, v111, v121
	v_lshl_add_u64 v[118:119], s[48:49], 0, v[114:115]
	v_mov_b32_e32 v120, v136
	v_mov_b32_e32 v121, v144
	v_lshl_add_u64 v[118:119], v[120:121], 1, v[118:119]
	v_cvt_pk_bf16_f32 v238, v122, v123
	v_cvt_pk_bf16_f32 v239, v124, v125

; __device__ __forceinline__ void store_bf16x4(bf16_t* p, f32x4 v) { u32x2 w; w.x = cvt_pk_bf16(v[0], v[1]); w.y = cvt_pk_bf16(v[2], v[3]); *(u32x2*)p = w; }
;   __device__ __forceinline__ void operator()(const f32x4 (&acc)[2][2][4][2], const pg8::Unit& u, int wr, int wc, int fr, int fq) const {
;     ...
;       else if (pn < 8) { store_bf16x4(VH + (size_t)row * 512 + (col - 1536), v); }
.LBB0_1614:
	s_andn2_b64 vcc, exec, s[24:25]
	s_cbranch_vccnz .LBB0_1616
	v_lshl_add_u64 v[118:119], s[16:17], 0, v[114:115]
	v_mov_b32_e32 v120, v136
	v_mov_b32_e32 v121, v144
	v_lshl_add_u64 v[118:119], v[120:121], 1, v[118:119]
	v_cvt_pk_bf16_f32 v238, v108, v109
	v_cvt_pk_bf16_f32 v239, v110, v111

; __device__ __forceinline__ float siluf_(float v) { return v * sigmoidf_(v); }
; __device__ __forceinline__ void store_bf16x4(bf16_t* p, f32x4 v) { u32x2 w; w.x = cvt_pk_bf16(v[0], v[1]); w.y = cvt_pk_bf16(v[2], v[3]); *(u32x2*)p = w; }
;   __device__ __forceinline__ void operator()(const f32x4 (&acc)[2][2][4][2], const pg8::Unit& u, int wr, int wc, int fr, int fq) const {
;     ...
;       else if (pn < 10) { f32x4 o; for (int j = 0; j < 4; ++j) o[j] = siluf_(v[j]); store_bf16x4(G + (size_t)row * 512 + (col - 2048), o); }
;       else { store_bf16x4(CQ + (size_t)row * 768 + (col - 2560), v); }
.LBB0_1621:
	s_and_b64 vcc, exec, s[8:9]
	s_cbranch_vccnz .LBB0_1631
	s_andn2_b64 vcc, exec, s[84:85]
	s_cbranch_vccnz .LBB0_1628
	s_andn2_b64 vcc, exec, s[78:79]
	s_cbranch_vccnz .LBB0_1625
	v_lshl_add_u64 v[108:109], s[46:47], 0, v[116:117]
	v_mov_b32_e32 v110, v136
	v_mov_b32_e32 v111, v144
	v_lshl_add_u64 v[108:109], v[110:111], 1, v[108:109]
	v_add_co_u32_e32 v108, vcc, 0xfffff000, v108
	s_mov_b64 s[24:25], 0
	s_nop 0
	v_addc_co_u32_e32 v109, vcc, -1, v109, vcc
	v_cvt_pk_bf16_f32 v240, v104, v105
	v_cvt_pk_bf16_f32 v241, v106, v107
	s_nop 1
	v_permlane16_swap_b32_e32 v238, v240
	v_permlane16_swap_b32_e32 v239, v241
	v_lshl_add_u64 v[242:243], v[108:109], 0, v[244:245]
	global_store_dwordx4 v[242:243], v[238:241], off offset:-1024
.LBB0_1625:
	s_andn2_b64 vcc, exec, s[24:25]
	s_cbranch_vccnz .LBB0_1627
	v_mul_f32_e32 v108, 0xbfb8aa3b, v104
	v_mul_f32_e32 v109, 0xbfb8aa3b, v105
	v_mul_f32_e32 v110, 0xbfb8aa3b, v106
	v_mul_f32_e32 v111, 0xbfb8aa3b, v107
	v_exp_f32_e32 v108, v108
	v_exp_f32_e32 v109, v109
	v_exp_f32_e32 v110, v110
	v_exp_f32_e32 v111, v111
	v_add_f32_e32 v108, 1.0, v108
	v_add_f32_e32 v109, 1.0, v109
	v_add_f32_e32 v110, 1.0, v110
	v_add_f32_e32 v111, 1.0, v111
	v_rcp_f32_e32 v108, v108
	v_rcp_f32_e32 v109, v109
	v_rcp_f32_e32 v110, v110
	v_rcp_f32_e32 v111, v111
	v_mul_f32_e32 v120, v104, v108
	v_mul_f32_e32 v121, v105, v109
	v_mul_f32_e32 v122, v106, v110
	v_mul_f32_e32 v123, v107, v111
	v_lshl_add_u64 v[108:109], s[48:49], 0, v[114:115]
	v_mov_b32_e32 v110, v136
	v_mov_b32_e32 v111, v144
	v_lshl_add_u64 v[108:109], v[110:111], 1, v[108:109]
	v_cvt_pk_bf16_f32 v240, v120, v121
	v_cvt_pk_bf16_f32 v241, v122, v123
	s_nop 1
	v_permlane16_swap_b32_e32 v238, v240
	v_permlane16_swap_b32_e32 v239, v241
	v_lshl_add_u64 v[242:243], v[108:109], 0, v[244:245]
	global_store_dwordx4 v[242:243], v[238:241], off offset:-4096

; __device__ __forceinline__ void store_bf16x4(bf16_t* p, f32x4 v) { u32x2 w; w.x = cvt_pk_bf16(v[0], v[1]); w.y = cvt_pk_bf16(v[2], v[3]); *(u32x2*)p = w; }
;   __device__ __forceinline__ void operator()(const f32x4 (&acc)[2][2][4][2], const pg8::Unit& u, int wr, int wc, int fr, int fq) const {
;     ...
;       else if (pn < 8) { store_bf16x4(VH + (size_t)row * 512 + (col - 1536), v); }
.LBB0_1628:
	s_andn2_b64 vcc, exec, s[24:25]
	s_cbranch_vccnz .LBB0_1630
	v_lshl_add_u64 v[108:109], s[16:17], 0, v[114:115]
	v_mov_b32_e32 v110, v136
	v_mov_b32_e32 v111, v144
	v_lshl_add_u64 v[108:109], v[110:111], 1, v[108:109]
	v_cvt_pk_bf16_f32 v240, v104, v105
	v_cvt_pk_bf16_f32 v241, v106, v107
	s_nop 1
	v_permlane16_swap_b32_e32 v238, v240
	v_permlane16_swap_b32_e32 v239, v241
	v_lshl_add_u64 v[242:243], v[108:109], 0, v[244:245]
	global_store_dwordx4 v[242:243], v[238:241], off offset:-3072

; __device__ __forceinline__ float siluf_(float v) { return v * sigmoidf_(v); }
; __device__ __forceinline__ void store_bf16x4(bf16_t* p, f32x4 v) { u32x2 w; w.x = cvt_pk_bf16(v[0], v[1]); w.y = cvt_pk_bf16(v[2], v[3]); *(u32x2*)p = w; }
;   __device__ __forceinline__ void operator()(const f32x4 (&acc)[2][2][4][2], const pg8::Unit& u, int wr, int wc, int fr, int fq) const {
;     ...
;       else if (pn < 10) { f32x4 o; for (int j = 0; j < 4; ++j) o[j] = siluf_(v[j]); store_bf16x4(G + (size_t)row * 512 + (col - 2048), o); }
;       else { store_bf16x4(CQ + (size_t)row * 768 + (col - 2560), v); }
.LBB0_1635:
	s_and_b64 vcc, exec, s[8:9]
	s_cbranch_vccnz .LBB0_1645
	s_andn2_b64 vcc, exec, s[84:85]
	s_cbranch_vccnz .LBB0_1642
	s_andn2_b64 vcc, exec, s[78:79]
	s_cbranch_vccnz .LBB0_1639
	v_lshl_add_u64 v[104:105], s[46:47], 0, v[116:117]
	v_mov_b32_e32 v106, v136
	v_mov_b32_e32 v107, v144
	v_lshl_add_u64 v[104:105], v[106:107], 1, v[104:105]
	v_add_co_u32_e32 v104, vcc, 0xfffff000, v104
	s_mov_b64 s[24:25], 0
	s_nop 0
	v_addc_co_u32_e32 v105, vcc, -1, v105, vcc
	v_cvt_pk_bf16_f32 v238, v100, v101
	v_cvt_pk_bf16_f32 v239, v102, v103
.LBB0_1639:
	s_andn2_b64 vcc, exec, s[24:25]
	s_cbranch_vccnz .LBB0_1641
	v_mul_f32_e32 v104, 0xbfb8aa3b, v100
	v_mul_f32_e32 v105, 0xbfb8aa3b, v101
	v_mul_f32_e32 v106, 0xbfb8aa3b, v102
	v_mul_f32_e32 v107, 0xbfb8aa3b, v103
	v_exp_f32_e32 v104, v104
	v_exp_f32_e32 v105, v105
	v_exp_f32_e32 v106, v106
	v_exp_f32_e32 v107, v107
	v_add_f32_e32 v104, 1.0, v104
	v_add_f32_e32 v105, 1.0, v105
	v_add_f32_e32 v106, 1.0, v106
	v_add_f32_e32 v107, 1.0, v107
	v_rcp_f32_e32 v104, v104
	v_rcp_f32_e32 v105, v105
	v_rcp_f32_e32 v106, v106
	v_rcp_f32_e32 v107, v107
	v_mul_f32_e32 v108, v100, v104
	v_mul_f32_e32 v109, v101, v105
	v_mul_f32_e32 v110, v102, v106
	v_mul_f32_e32 v111, v103, v107
	v_lshl_add_u64 v[104:105], s[48:49], 0, v[114:115]
	v_mov_b32_e32 v106, v136
	v_mov_b32_e32 v107, v144
	v_lshl_add_u64 v[104:105], v[106:107], 1, v[104:105]
	v_cvt_pk_bf16_f32 v238, v108, v109
	v_cvt_pk_bf16_f32 v239, v110, v111

; __device__ __forceinline__ void store_bf16x4(bf16_t* p, f32x4 v) { u32x2 w; w.x = cvt_pk_bf16(v[0], v[1]); w.y = cvt_pk_bf16(v[2], v[3]); *(u32x2*)p = w; }
;   __device__ __forceinline__ void operator()(const f32x4 (&acc)[2][2][4][2], const pg8::Unit& u, int wr, int wc, int fr, int fq) const {
;     ...
;       else if (pn < 8) { store_bf16x4(VH + (size_t)row * 512 + (col - 1536), v); }
.LBB0_1642:
	s_andn2_b64 vcc, exec, s[24:25]
	s_cbranch_vccnz .LBB0_1644
	v_lshl_add_u64 v[104:105], s[16:17], 0, v[114:115]
	v_mov_b32_e32 v106, v136
	v_mov_b32_e32 v107, v144
	v_lshl_add_u64 v[104:105], v[106:107], 1, v[104:105]
	v_cvt_pk_bf16_f32 v238, v100, v101
	v_cvt_pk_bf16_f32 v239, v102, v103

; __device__ __forceinline__ float siluf_(float v) { return v * sigmoidf_(v); }
; __device__ __forceinline__ void store_bf16x4(bf16_t* p, f32x4 v) { u32x2 w; w.x = cvt_pk_bf16(v[0], v[1]); w.y = cvt_pk_bf16(v[2], v[3]); *(u32x2*)p = w; }
;   __device__ __forceinline__ void operator()(const f32x4 (&acc)[2][2][4][2], const pg8::Unit& u, int wr, int wc, int fr, int fq) const {
;     ...
;       else if (pn < 10) { f32x4 o; for (int j = 0; j < 4; ++j) o[j] = siluf_(v[j]); store_bf16x4(G + (size_t)row * 512 + (col - 2048), o); }
;       else { store_bf16x4(CQ + (size_t)row * 768 + (col - 2560), v); }
.LBB0_1649:
	s_and_b64 vcc, exec, s[8:9]
	s_cbranch_vccnz .LBB0_1659
	s_andn2_b64 vcc, exec, s[84:85]
	s_cbranch_vccnz .LBB0_1656
	s_andn2_b64 vcc, exec, s[78:79]
	s_cbranch_vccnz .LBB0_1653
	v_lshl_add_u64 v[100:101], s[46:47], 0, v[116:117]
	v_mov_b32_e32 v102, v136
	v_mov_b32_e32 v103, v144
	v_lshl_add_u64 v[100:101], v[102:103], 1, v[100:101]
	v_add_co_u32_e32 v100, vcc, 0xfffff000, v100
	s_mov_b64 s[24:25], 0
	s_nop 0
	v_addc_co_u32_e32 v101, vcc, -1, v101, vcc
	v_cvt_pk_bf16_f32 v240, v96, v97
	v_cvt_pk_bf16_f32 v241, v98, v99
	s_nop 1
	v_permlane16_swap_b32_e32 v238, v240
	v_permlane16_swap_b32_e32 v239, v241
	v_lshl_add_u64 v[242:243], v[100:101], 0, v[244:245]
	global_store_dwordx4 v[242:243], v[238:241], off offset:-768
.LBB0_1653:
	s_andn2_b64 vcc, exec, s[24:25]
	s_cbranch_vccnz .LBB0_1655
	v_mul_f32_e32 v100, 0xbfb8aa3b, v96
	v_mul_f32_e32 v101, 0xbfb8aa3b, v97
	v_mul_f32_e32 v102, 0xbfb8aa3b, v98
	v_mul_f32_e32 v103, 0xbfb8aa3b, v99
	v_exp_f32_e32 v100, v100
	v_exp_f32_e32 v101, v101
	v_exp_f32_e32 v102, v102
	v_exp_f32_e32 v103, v103
	v_add_f32_e32 v100, 1.0, v100
	v_add_f32_e32 v101, 1.0, v101
	v_add_f32_e32 v102, 1.0, v102
	v_add_f32_e32 v103, 1.0, v103
	v_rcp_f32_e32 v100, v100
	v_rcp_f32_e32 v101, v101
	v_rcp_f32_e32 v102, v102
	v_rcp_f32_e32 v103, v103
	v_mul_f32_e32 v104, v96, v100
	v_mul_f32_e32 v105, v97, v101
	v_mul_f32_e32 v106, v98, v102
	v_mul_f32_e32 v107, v99, v103
	v_lshl_add_u64 v[100:101], s[48:49], 0, v[114:115]
	v_mov_b32_e32 v102, v136
	v_mov_b32_e32 v103, v144
	v_lshl_add_u64 v[100:101], v[102:103], 1, v[100:101]
	v_cvt_pk_bf16_f32 v240, v104, v105
	v_cvt_pk_bf16_f32 v241, v106, v107
	s_nop 1
	v_permlane16_swap_b32_e32 v238, v240
	v_permlane16_swap_b32_e32 v239, v241
	v_lshl_add_u64 v[242:243], v[100:101], 0, v[244:245]
	global_store_dwordx4 v[242:243], v[238:241], off offset:-3840

; __device__ __forceinline__ void store_bf16x4(bf16_t* p, f32x4 v) { u32x2 w; w.x = cvt_pk_bf16(v[0], v[1]); w.y = cvt_pk_bf16(v[2], v[3]); *(u32x2*)p = w; }
;   __device__ __forceinline__ void operator()(const f32x4 (&acc)[2][2][4][2], const pg8::Unit& u, int wr, int wc, int fr, int fq) const {
;     ...
;       else if (pn < 8) { store_bf16x4(VH + (size_t)row * 512 + (col - 1536), v); }
.LBB0_1656:
	s_andn2_b64 vcc, exec, s[24:25]
	s_cbranch_vccnz .LBB0_1658
	v_lshl_add_u64 v[100:101], s[16:17], 0, v[114:115]
	v_mov_b32_e32 v102, v136
	v_mov_b32_e32 v103, v144
	v_lshl_add_u64 v[100:101], v[102:103], 1, v[100:101]
	v_cvt_pk_bf16_f32 v240, v96, v97
	v_cvt_pk_bf16_f32 v241, v98, v99
	s_nop 1
	v_permlane16_swap_b32_e32 v238, v240
	v_permlane16_swap_b32_e32 v239, v241
	v_lshl_add_u64 v[242:243], v[100:101], 0, v[244:245]
	global_store_dwordx4 v[242:243], v[238:241], off offset:-2816

; __device__ __forceinline__ float siluf_(float v) { return v * sigmoidf_(v); }
; __device__ __forceinline__ void store_bf16x4(bf16_t* p, f32x4 v) { u32x2 w; w.x = cvt_pk_bf16(v[0], v[1]); w.y = cvt_pk_bf16(v[2], v[3]); *(u32x2*)p = w; }
;   __device__ __forceinline__ void operator()(const f32x4 (&acc)[2][2][4][2], const pg8::Unit& u, int wr, int wc, int fr, int fq) const {
;     ...
;       if (pn < 2) { f32x4 o; for (int j = 0; j < 4; ++j) o[j] = siluf_(v[j]); store_bf16x4(QH + (size_t)row * 512 + col, o); }
.LBB0_1663:
	v_mul_f32_e32 v120, 0xbfb8aa3b, v108
	v_exp_f32_e32 v120, v120
	s_nop 0
	v_add_f32_e32 v120, 1.0, v120
	v_rcp_f32_e32 v120, v120
	s_nop 0
	v_mul_f32_e32 v120, v108, v120
	v_mul_f32_e32 v108, 0xbfb8aa3b, v109
	v_exp_f32_e32 v108, v108
	s_nop 0
	v_add_f32_e32 v108, 1.0, v108
	v_rcp_f32_e32 v108, v108
	s_nop 0
	v_mul_f32_e32 v121, v109, v108
	v_mul_f32_e32 v108, 0xbfb8aa3b, v110
	v_exp_f32_e32 v108, v108
	s_nop 0
	v_add_f32_e32 v108, 1.0, v108
	v_rcp_f32_e32 v108, v108
	s_nop 0
	v_mul_f32_e32 v122, v110, v108
	v_mul_f32_e32 v108, 0xbfb8aa3b, v111
	v_exp_f32_e32 v108, v108
	v_cvt_pk_bf16_f32 v238, v120, v121
	s_nop 0
	v_add_f32_e32 v108, 1.0, v108
	v_rcp_f32_e32 v108, v108
	s_nop 0
	v_mul_f32_e32 v111, v111, v108
	v_lshl_add_u64 v[108:109], v[136:137], 1, v[118:119]
	v_cvt_pk_bf16_f32 v239, v122, v111
	s_and_b64 vcc, exec, s[10:11]
	s_mov_b64 s[24:25], -1
	s_cbranch_vccz .LBB0_1621

; __device__ __forceinline__ float siluf_(float v) { return v * sigmoidf_(v); }
; __device__ __forceinline__ void store_bf16x4(bf16_t* p, f32x4 v) { u32x2 w; w.x = cvt_pk_bf16(v[0], v[1]); w.y = cvt_pk_bf16(v[2], v[3]); *(u32x2*)p = w; }
;   __device__ __forceinline__ void operator()(const f32x4 (&acc)[2][2][4][2], const pg8::Unit& u, int wr, int wc, int fr, int fq) const {
;     ...
;       if (pn < 2) { f32x4 o; for (int j = 0; j < 4; ++j) o[j] = siluf_(v[j]); store_bf16x4(QH + (size_t)row * 512 + col, o); }
.LBB0_1665:
	s_nop 0
	v_mul_f32_e32 v108, 0xbfb8aa3b, v104
	v_exp_f32_e32 v108, v108
	s_nop 0
	v_add_f32_e32 v108, 1.0, v108
	v_rcp_f32_e32 v108, v108
	s_nop 0
	v_mul_f32_e32 v108, v104, v108
	v_mul_f32_e32 v104, 0xbfb8aa3b, v105
	v_exp_f32_e32 v104, v104
	s_nop 0
	v_add_f32_e32 v104, 1.0, v104
	v_rcp_f32_e32 v104, v104
	s_nop 0
	v_mul_f32_e32 v109, v105, v104
	v_mul_f32_e32 v104, 0xbfb8aa3b, v106
	v_exp_f32_e32 v104, v104
	s_nop 0
	v_add_f32_e32 v104, 1.0, v104
	v_rcp_f32_e32 v104, v104
	s_nop 0
	v_mul_f32_e32 v110, v106, v104
	v_mul_f32_e32 v104, 0xbfb8aa3b, v107
	v_exp_f32_e32 v104, v104
	v_cvt_pk_bf16_f32 v240, v108, v109
	s_nop 0
	v_add_f32_e32 v104, 1.0, v104
	v_rcp_f32_e32 v104, v104
	s_nop 0
	v_mul_f32_e32 v107, v107, v104
	v_lshl_add_u64 v[104:105], v[136:137], 1, v[118:119]
	v_cvt_pk_bf16_f32 v241, v110, v107
	s_nop 1
	v_permlane16_swap_b32_e32 v238, v240
	v_permlane16_swap_b32_e32 v239, v241
	v_lshl_add_u64 v[242:243], v[104:105], 0, v[244:245]
	global_store_dwordx4 v[242:243], v[238:241], off
	s_and_b64 vcc, exec, s[10:11]
	s_mov_b64 s[24:25], -1
	s_cbranch_vccz .LBB0_1635

; __device__ __forceinline__ float siluf_(float v) { return v * sigmoidf_(v); }
; __device__ __forceinline__ void store_bf16x4(bf16_t* p, f32x4 v) { u32x2 w; w.x = cvt_pk_bf16(v[0], v[1]); w.y = cvt_pk_bf16(v[2], v[3]); *(u32x2*)p = w; }
;   __device__ __forceinline__ void operator()(const f32x4 (&acc)[2][2][4][2], const pg8::Unit& u, int wr, int wc, int fr, int fq) const {
;     ...
;       if (pn < 2) { f32x4 o; for (int j = 0; j < 4; ++j) o[j] = siluf_(v[j]); store_bf16x4(QH + (size_t)row * 512 + col, o); }
.LBB0_1667:
	s_nop 0
	v_mul_f32_e32 v104, 0xbfb8aa3b, v100
	v_exp_f32_e32 v104, v104
	s_nop 0
	v_add_f32_e32 v104, 1.0, v104
	v_rcp_f32_e32 v104, v104
	s_nop 0
	v_mul_f32_e32 v104, v100, v104
	v_mul_f32_e32 v100, 0xbfb8aa3b, v101
	v_exp_f32_e32 v100, v100
	s_nop 0
	v_add_f32_e32 v100, 1.0, v100
	v_rcp_f32_e32 v100, v100
	s_nop 0
	v_mul_f32_e32 v105, v101, v100
	v_mul_f32_e32 v100, 0xbfb8aa3b, v102
	v_exp_f32_e32 v100, v100
	s_nop 0
	v_add_f32_e32 v100, 1.0, v100
	v_rcp_f32_e32 v100, v100
	s_nop 0
	v_mul_f32_e32 v106, v102, v100
	v_mul_f32_e32 v100, 0xbfb8aa3b, v103
	v_exp_f32_e32 v100, v100
	v_cvt_pk_bf16_f32 v238, v104, v105
	s_nop 0
	v_add_f32_e32 v100, 1.0, v100
	v_rcp_f32_e32 v100, v100
	s_nop 0
	v_mul_f32_e32 v103, v103, v100
	v_lshl_add_u64 v[100:101], v[136:137], 1, v[118:119]
	v_cvt_pk_bf16_f32 v239, v106, v103
	s_and_b64 vcc, exec, s[10:11]
	s_mov_b64 s[24:25], -1
	s_cbranch_vccz .LBB0_1649

; __device__ __forceinline__ float sigmoidf_(float v) { return __builtin_amdgcn_rcpf(1.0f + __expf(-v)); }
; __device__ __forceinline__ float siluf_(float v) { return v * sigmoidf_(v); }
; __device__ __forceinline__ void store_bf16x4(bf16_t* p, f32x4 v) { u32x2 w; w.x = cvt_pk_bf16(v[0], v[1]); w.y = cvt_pk_bf16(v[2], v[3]); *(u32x2*)p = w; }
;   __device__ __forceinline__ void operator()(const f32x4 (&acc)[2][2][4][2], const pg8::Unit& u, int wr, int wc, int fr, int fq) const {
;     ...
;     EPI_LOOP(
;       if (pn < 2) { f32x4 o; for (int j = 0; j < 4; ++j) o[j] = siluf_(v[j]); store_bf16x4(QH + (size_t)row * 512 + col, o); }
;       else if (pn < 6) { const int c = col - 512; const f32x4 lb = *(const f32x4*)(LBj + c); f32x4 o; for (int j = 0; j < 4; ++j) o[j] = lb[j] + (1.f - lb[j]) * sigmoidf_(v[j]); *(f32x4*)(F + (size_t)row * 1024 + c) = o; }
;       else if (pn < 8) { store_bf16x4(VH + (size_t)row * 512 + (col - 1536), v); }
;       else if (pn < 10) { f32x4 o; for (int j = 0; j < 4; ++j) o[j] = siluf_(v[j]); store_bf16x4(G + (size_t)row * 512 + (col - 2048), o); }
;       else { store_bf16x4(CQ + (size_t)row * 768 + (col - 2560), v); }
.LBB0_1669:
	v_mul_f32_e32 v100, 0xbfb8aa3b, v96
	v_exp_f32_e32 v100, v100
	s_nop 0
	v_add_f32_e32 v100, 1.0, v100
	v_rcp_f32_e32 v100, v100
	s_nop 0
	v_mul_f32_e32 v100, v96, v100
	v_mul_f32_e32 v96, 0xbfb8aa3b, v97
	v_exp_f32_e32 v96, v96
	s_nop 0
	v_add_f32_e32 v96, 1.0, v96
	v_rcp_f32_e32 v96, v96
	s_nop 0
	v_mul_f32_e32 v101, v97, v96
	v_mul_f32_e32 v96, 0xbfb8aa3b, v98
	v_exp_f32_e32 v96, v96
	s_nop 0
	v_add_f32_e32 v96, 1.0, v96
	v_rcp_f32_e32 v96, v96
	s_nop 0
	v_mul_f32_e32 v102, v98, v96
	v_mul_f32_e32 v96, 0xbfb8aa3b, v99
	v_exp_f32_e32 v96, v96
	v_cvt_pk_bf16_f32 v240, v100, v101
	s_nop 0
	v_add_f32_e32 v96, 1.0, v96
	v_rcp_f32_e32 v96, v96
	s_nop 0
	v_mul_f32_e32 v99, v99, v96
	v_lshl_add_u64 v[96:97], v[136:137], 1, v[118:119]
	v_cvt_pk_bf16_f32 v241, v102, v99
	s_nop 1
	v_permlane16_swap_b32_e32 v238, v240
	v_permlane16_swap_b32_e32 v239, v241
	v_lshl_add_u64 v[242:243], v[96:97], 0, v[244:245]
	global_store_dwordx4 v[242:243], v[238:241], off offset:256
.LBB0_1670:
	v_or_b32_e32 v96, 32, v138
	v_ashrrev_i32_e32 v97, 31, v96
	v_mad_i64_i32 v[100:101], s[24:25], v96, s64, 0
	v_lshlrev_b64 v[98:99], 10, v[96:97]
	v_lshlrev_b64 v[96:97], 12, v[96:97]
	s_and_b64 vcc, exec, s[10:11]
	s_mov_b64 s[24:25], -1
	s_cbranch_vccnz .LBB0_1726
	s_and_b64 vcc, exec, s[8:9]
	s_cbranch_vccnz .LBB0_1681
	s_andn2_b64 vcc, exec, s[84:85]
	s_cbranch_vccnz .LBB0_1678
	s_andn2_b64 vcc, exec, s[78:79]
	s_cbranch_vccnz .LBB0_1675
	v_lshl_add_u64 v[102:103], s[46:47], 0, v[100:101]
	v_mov_b32_e32 v104, v136
	v_mov_b32_e32 v105, v144
	v_lshl_add_u64 v[102:103], v[104:105], 1, v[102:103]
	v_add_co_u32_e32 v102, vcc, 0xfffff000, v102
	s_mov_b64 s[24:25], 0
	s_nop 0
	v_addc_co_u32_e32 v103, vcc, -1, v103, vcc
	v_cvt_pk_bf16_f32 v238, v92, v93
	v_cvt_pk_bf16_f32 v239, v94, v95
.LBB0_1675:
	s_andn2_b64 vcc, exec, s[24:25]
	s_cbranch_vccnz .LBB0_1677
	v_mul_f32_e32 v102, 0xbfb8aa3b, v92
	v_mul_f32_e32 v103, 0xbfb8aa3b, v93
	v_mul_f32_e32 v104, 0xbfb8aa3b, v94
	v_mul_f32_e32 v105, 0xbfb8aa3b, v95
	v_exp_f32_e32 v102, v102
	v_exp_f32_e32 v103, v103
	v_exp_f32_e32 v104, v104
	v_exp_f32_e32 v105, v105
	v_add_f32_e32 v102, 1.0, v102
	v_add_f32_e32 v103, 1.0, v103
	v_add_f32_e32 v104, 1.0, v104
	v_add_f32_e32 v105, 1.0, v105
	v_rcp_f32_e32 v102, v102
	v_rcp_f32_e32 v103, v103
	v_rcp_f32_e32 v104, v104
	v_rcp_f32_e32 v105, v105
	v_mul_f32_e32 v106, v92, v102
	v_mul_f32_e32 v107, v93, v103
	v_mul_f32_e32 v108, v94, v104
	v_mul_f32_e32 v109, v95, v105
	v_lshl_add_u64 v[102:103], s[48:49], 0, v[98:99]
	v_mov_b32_e32 v104, v136
	v_mov_b32_e32 v105, v144
	v_lshl_add_u64 v[102:103], v[104:105], 1, v[102:103]
	v_cvt_pk_bf16_f32 v238, v106, v107
	v_cvt_pk_bf16_f32 v239, v108, v109

; __device__ __forceinline__ void store_bf16x4(bf16_t* p, f32x4 v) { u32x2 w; w.x = cvt_pk_bf16(v[0], v[1]); w.y = cvt_pk_bf16(v[2], v[3]); *(u32x2*)p = w; }
;   __device__ __forceinline__ void operator()(const f32x4 (&acc)[2][2][4][2], const pg8::Unit& u, int wr, int wc, int fr, int fq) const {
;     ...
;       else if (pn < 8) { store_bf16x4(VH + (size_t)row * 512 + (col - 1536), v); }
.LBB0_1678:
	s_andn2_b64 vcc, exec, s[24:25]
	s_cbranch_vccnz .LBB0_1680
	v_lshl_add_u64 v[102:103], s[16:17], 0, v[98:99]
	v_mov_b32_e32 v104, v136
	v_mov_b32_e32 v105, v144
	v_lshl_add_u64 v[102:103], v[104:105], 1, v[102:103]
	v_cvt_pk_bf16_f32 v238, v92, v93
	v_cvt_pk_bf16_f32 v239, v94, v95

; __device__ __forceinline__ float siluf_(float v) { return v * sigmoidf_(v); }
; __device__ __forceinline__ void store_bf16x4(bf16_t* p, f32x4 v) { u32x2 w; w.x = cvt_pk_bf16(v[0], v[1]); w.y = cvt_pk_bf16(v[2], v[3]); *(u32x2*)p = w; }
;   __device__ __forceinline__ void operator()(const f32x4 (&acc)[2][2][4][2], const pg8::Unit& u, int wr, int wc, int fr, int fq) const {
;     ...
;       else if (pn < 10) { f32x4 o; for (int j = 0; j < 4; ++j) o[j] = siluf_(v[j]); store_bf16x4(G + (size_t)row * 512 + (col - 2048), o); }
;       else { store_bf16x4(CQ + (size_t)row * 768 + (col - 2560), v); }
.LBB0_1685:
	s_and_b64 vcc, exec, s[8:9]
	s_cbranch_vccnz .LBB0_1695
	s_andn2_b64 vcc, exec, s[84:85]
	s_cbranch_vccnz .LBB0_1692
	s_andn2_b64 vcc, exec, s[78:79]
	s_cbranch_vccnz .LBB0_1689
	v_lshl_add_u64 v[92:93], s[46:47], 0, v[100:101]
	v_mov_b32_e32 v94, v136
	v_mov_b32_e32 v95, v144
	v_lshl_add_u64 v[92:93], v[94:95], 1, v[92:93]
	v_add_co_u32_e32 v92, vcc, 0xfffff000, v92
	s_mov_b64 s[24:25], 0
	s_nop 0
	v_addc_co_u32_e32 v93, vcc, -1, v93, vcc
	v_cvt_pk_bf16_f32 v240, v88, v89
	v_cvt_pk_bf16_f32 v241, v90, v91
	s_nop 1
	v_permlane16_swap_b32_e32 v238, v240
	v_permlane16_swap_b32_e32 v239, v241
	v_lshl_add_u64 v[242:243], v[92:93], 0, v[244:245]
	global_store_dwordx4 v[242:243], v[238:241], off offset:-1024
.LBB0_1689:
	s_andn2_b64 vcc, exec, s[24:25]
	s_cbranch_vccnz .LBB0_1691
	v_mul_f32_e32 v92, 0xbfb8aa3b, v88
	v_mul_f32_e32 v93, 0xbfb8aa3b, v89
	v_mul_f32_e32 v94, 0xbfb8aa3b, v90
	v_mul_f32_e32 v95, 0xbfb8aa3b, v91
	v_exp_f32_e32 v92, v92
	v_exp_f32_e32 v93, v93
	v_exp_f32_e32 v94, v94
	v_exp_f32_e32 v95, v95
	v_add_f32_e32 v92, 1.0, v92
	v_add_f32_e32 v93, 1.0, v93
	v_add_f32_e32 v94, 1.0, v94
	v_add_f32_e32 v95, 1.0, v95
	v_rcp_f32_e32 v92, v92
	v_rcp_f32_e32 v93, v93
	v_rcp_f32_e32 v94, v94
	v_rcp_f32_e32 v95, v95
	v_mul_f32_e32 v104, v88, v92
	v_mul_f32_e32 v105, v89, v93
	v_mul_f32_e32 v106, v90, v94
	v_mul_f32_e32 v107, v91, v95
	v_lshl_add_u64 v[92:93], s[48:49], 0, v[98:99]
	v_mov_b32_e32 v94, v136
	v_mov_b32_e32 v95, v144
	v_lshl_add_u64 v[92:93], v[94:95], 1, v[92:93]
	v_cvt_pk_bf16_f32 v240, v104, v105
	v_cvt_pk_bf16_f32 v241, v106, v107
	s_nop 1
	v_permlane16_swap_b32_e32 v238, v240
	v_permlane16_swap_b32_e32 v239, v241
	v_lshl_add_u64 v[242:243], v[92:93], 0, v[244:245]
	global_store_dwordx4 v[242:243], v[238:241], off offset:-4096

; __device__ __forceinline__ void store_bf16x4(bf16_t* p, f32x4 v) { u32x2 w; w.x = cvt_pk_bf16(v[0], v[1]); w.y = cvt_pk_bf16(v[2], v[3]); *(u32x2*)p = w; }
;   __device__ __forceinline__ void operator()(const f32x4 (&acc)[2][2][4][2], const pg8::Unit& u, int wr, int wc, int fr, int fq) const {
;     ...
;       else if (pn < 8) { store_bf16x4(VH + (size_t)row * 512 + (col - 1536), v); }
.LBB0_1692:
	s_andn2_b64 vcc, exec, s[24:25]
	s_cbranch_vccnz .LBB0_1694
	v_lshl_add_u64 v[92:93], s[16:17], 0, v[98:99]
	v_mov_b32_e32 v94, v136
	v_mov_b32_e32 v95, v144
	v_lshl_add_u64 v[92:93], v[94:95], 1, v[92:93]
	v_cvt_pk_bf16_f32 v240, v88, v89
	v_cvt_pk_bf16_f32 v241, v90, v91
	s_nop 1
	v_permlane16_swap_b32_e32 v238, v240
	v_permlane16_swap_b32_e32 v239, v241
	v_lshl_add_u64 v[242:243], v[92:93], 0, v[244:245]
	global_store_dwordx4 v[242:243], v[238:241], off offset:-3072

; __device__ __forceinline__ float siluf_(float v) { return v * sigmoidf_(v); }
; __device__ __forceinline__ void store_bf16x4(bf16_t* p, f32x4 v) { u32x2 w; w.x = cvt_pk_bf16(v[0], v[1]); w.y = cvt_pk_bf16(v[2], v[3]); *(u32x2*)p = w; }
;   __device__ __forceinline__ void operator()(const f32x4 (&acc)[2][2][4][2], const pg8::Unit& u, int wr, int wc, int fr, int fq) const {
;     ...
;       else if (pn < 10) { f32x4 o; for (int j = 0; j < 4; ++j) o[j] = siluf_(v[j]); store_bf16x4(G + (size_t)row * 512 + (col - 2048), o); }
;       else { store_bf16x4(CQ + (size_t)row * 768 + (col - 2560), v); }
.LBB0_1699:
	s_and_b64 vcc, exec, s[8:9]
	s_cbranch_vccnz .LBB0_1709
	s_andn2_b64 vcc, exec, s[84:85]
	s_cbranch_vccnz .LBB0_1706
	s_andn2_b64 vcc, exec, s[78:79]
	s_cbranch_vccnz .LBB0_1703
	v_lshl_add_u64 v[88:89], s[46:47], 0, v[100:101]
	v_mov_b32_e32 v90, v136
	v_mov_b32_e32 v91, v144
	v_lshl_add_u64 v[88:89], v[90:91], 1, v[88:89]
	v_add_co_u32_e32 v88, vcc, 0xfffff000, v88
	s_mov_b64 s[24:25], 0
	s_nop 0
	v_addc_co_u32_e32 v89, vcc, -1, v89, vcc
	v_cvt_pk_bf16_f32 v238, v84, v85
	v_cvt_pk_bf16_f32 v239, v86, v87
.LBB0_1703:
	s_andn2_b64 vcc, exec, s[24:25]
	s_cbranch_vccnz .LBB0_1705
	v_mul_f32_e32 v88, 0xbfb8aa3b, v84
	v_mul_f32_e32 v89, 0xbfb8aa3b, v85
	v_mul_f32_e32 v90, 0xbfb8aa3b, v86
	v_mul_f32_e32 v91, 0xbfb8aa3b, v87
	v_exp_f32_e32 v88, v88
	v_exp_f32_e32 v89, v89
	v_exp_f32_e32 v90, v90
	v_exp_f32_e32 v91, v91
	v_add_f32_e32 v88, 1.0, v88
	v_add_f32_e32 v89, 1.0, v89
	v_add_f32_e32 v90, 1.0, v90
	v_add_f32_e32 v91, 1.0, v91
	v_rcp_f32_e32 v88, v88
	v_rcp_f32_e32 v89, v89
	v_rcp_f32_e32 v90, v90
	v_rcp_f32_e32 v91, v91
	v_mul_f32_e32 v92, v84, v88
	v_mul_f32_e32 v93, v85, v89
	v_mul_f32_e32 v94, v86, v90
	v_mul_f32_e32 v95, v87, v91
	v_lshl_add_u64 v[88:89], s[48:49], 0, v[98:99]
	v_mov_b32_e32 v90, v136
	v_mov_b32_e32 v91, v144
	v_lshl_add_u64 v[88:89], v[90:91], 1, v[88:89]
	v_cvt_pk_bf16_f32 v238, v92, v93
	v_cvt_pk_bf16_f32 v239, v94, v95

; __device__ __forceinline__ void store_bf16x4(bf16_t* p, f32x4 v) { u32x2 w; w.x = cvt_pk_bf16(v[0], v[1]); w.y = cvt_pk_bf16(v[2], v[3]); *(u32x2*)p = w; }
;   __device__ __forceinline__ void operator()(const f32x4 (&acc)[2][2][4][2], const pg8::Unit& u, int wr, int wc, int fr, int fq) const {
;     ...
;       else if (pn < 8) { store_bf16x4(VH + (size_t)row * 512 + (col - 1536), v); }
.LBB0_1706:
	s_andn2_b64 vcc, exec, s[24:25]
	s_cbranch_vccnz .LBB0_1708
	v_lshl_add_u64 v[88:89], s[16:17], 0, v[98:99]
	v_mov_b32_e32 v90, v136
	v_mov_b32_e32 v91, v144
	v_lshl_add_u64 v[88:89], v[90:91], 1, v[88:89]
	v_cvt_pk_bf16_f32 v238, v84, v85
	v_cvt_pk_bf16_f32 v239, v86, v87

; __device__ __forceinline__ float siluf_(float v) { return v * sigmoidf_(v); }
; __device__ __forceinline__ void store_bf16x4(bf16_t* p, f32x4 v) { u32x2 w; w.x = cvt_pk_bf16(v[0], v[1]); w.y = cvt_pk_bf16(v[2], v[3]); *(u32x2*)p = w; }
;   __device__ __forceinline__ void operator()(const f32x4 (&acc)[2][2][4][2], const pg8::Unit& u, int wr, int wc, int fr, int fq) const {
;     ...
;       else if (pn < 10) { f32x4 o; for (int j = 0; j < 4; ++j) o[j] = siluf_(v[j]); store_bf16x4(G + (size_t)row * 512 + (col - 2048), o); }
;       else { store_bf16x4(CQ + (size_t)row * 768 + (col - 2560), v); }
.LBB0_1713:
	s_and_b64 vcc, exec, s[8:9]
	s_cbranch_vccnz .LBB0_1723
	s_andn2_b64 vcc, exec, s[84:85]
	s_cbranch_vccnz .LBB0_1720
	s_andn2_b64 vcc, exec, s[78:79]
	s_cbranch_vccnz .LBB0_1717
	v_lshl_add_u64 v[84:85], s[46:47], 0, v[100:101]
	v_mov_b32_e32 v86, v136
	v_mov_b32_e32 v87, v144
	v_lshl_add_u64 v[84:85], v[86:87], 1, v[84:85]
	v_add_co_u32_e32 v84, vcc, 0xfffff000, v84
	s_mov_b64 s[24:25], 0
	s_nop 0
	v_addc_co_u32_e32 v85, vcc, -1, v85, vcc
	v_cvt_pk_bf16_f32 v240, v80, v81
	v_cvt_pk_bf16_f32 v241, v82, v83
	s_nop 1
	v_permlane16_swap_b32_e32 v238, v240
	v_permlane16_swap_b32_e32 v239, v241
	v_lshl_add_u64 v[242:243], v[84:85], 0, v[244:245]
	global_store_dwordx4 v[242:243], v[238:241], off offset:-768
.LBB0_1717:
	s_andn2_b64 vcc, exec, s[24:25]
	s_cbranch_vccnz .LBB0_1719
	v_mul_f32_e32 v84, 0xbfb8aa3b, v80
	v_mul_f32_e32 v85, 0xbfb8aa3b, v81
	v_mul_f32_e32 v86, 0xbfb8aa3b, v82
	v_mul_f32_e32 v87, 0xbfb8aa3b, v83
	v_exp_f32_e32 v84, v84
	v_exp_f32_e32 v85, v85
	v_exp_f32_e32 v86, v86
	v_exp_f32_e32 v87, v87
	v_add_f32_e32 v84, 1.0, v84
	v_add_f32_e32 v85, 1.0, v85
	v_add_f32_e32 v86, 1.0, v86
	v_add_f32_e32 v87, 1.0, v87
	v_rcp_f32_e32 v84, v84
	v_rcp_f32_e32 v85, v85
	v_rcp_f32_e32 v86, v86
	v_rcp_f32_e32 v87, v87
	v_mul_f32_e32 v88, v80, v84
	v_mul_f32_e32 v89, v81, v85
	v_mul_f32_e32 v90, v82, v86
	v_mul_f32_e32 v91, v83, v87
	v_lshl_add_u64 v[84:85], s[48:49], 0, v[98:99]
	v_mov_b32_e32 v86, v136
	v_mov_b32_e32 v87, v144
	v_lshl_add_u64 v[84:85], v[86:87], 1, v[84:85]
	v_cvt_pk_bf16_f32 v240, v88, v89
	v_cvt_pk_bf16_f32 v241, v90, v91
	s_nop 1
	v_permlane16_swap_b32_e32 v238, v240
	v_permlane16_swap_b32_e32 v239, v241
	v_lshl_add_u64 v[242:243], v[84:85], 0, v[244:245]
	global_store_dwordx4 v[242:243], v[238:241], off offset:-3840

; __device__ __forceinline__ void store_bf16x4(bf16_t* p, f32x4 v) { u32x2 w; w.x = cvt_pk_bf16(v[0], v[1]); w.y = cvt_pk_bf16(v[2], v[3]); *(u32x2*)p = w; }
;   __device__ __forceinline__ void operator()(const f32x4 (&acc)[2][2][4][2], const pg8::Unit& u, int wr, int wc, int fr, int fq) const {
;     ...
;       else if (pn < 8) { store_bf16x4(VH + (size_t)row * 512 + (col - 1536), v); }
.LBB0_1720:
	s_andn2_b64 vcc, exec, s[24:25]
	s_cbranch_vccnz .LBB0_1722
	v_lshl_add_u64 v[84:85], s[16:17], 0, v[98:99]
	v_mov_b32_e32 v86, v136
	v_mov_b32_e32 v87, v144
	v_lshl_add_u64 v[84:85], v[86:87], 1, v[84:85]
	v_cvt_pk_bf16_f32 v240, v80, v81
	v_cvt_pk_bf16_f32 v241, v82, v83
	s_nop 1
	v_permlane16_swap_b32_e32 v238, v240
	v_permlane16_swap_b32_e32 v239, v241
	v_lshl_add_u64 v[242:243], v[84:85], 0, v[244:245]
	global_store_dwordx4 v[242:243], v[238:241], off offset:-2816

; __device__ __forceinline__ float siluf_(float v) { return v * sigmoidf_(v); }
; __device__ __forceinline__ void store_bf16x4(bf16_t* p, f32x4 v) { u32x2 w; w.x = cvt_pk_bf16(v[0], v[1]); w.y = cvt_pk_bf16(v[2], v[3]); *(u32x2*)p = w; }
;   __device__ __forceinline__ void operator()(const f32x4 (&acc)[2][2][4][2], const pg8::Unit& u, int wr, int wc, int fr, int fq) const {
;     ...
;       if (pn < 2) { f32x4 o; for (int j = 0; j < 4; ++j) o[j] = siluf_(v[j]); store_bf16x4(QH + (size_t)row * 512 + col, o); }
.LBB0_1727:
	v_mul_f32_e32 v104, 0xbfb8aa3b, v92
	v_exp_f32_e32 v104, v104
	s_nop 0
	v_add_f32_e32 v104, 1.0, v104
	v_rcp_f32_e32 v104, v104
	s_nop 0
	v_mul_f32_e32 v104, v92, v104
	v_mul_f32_e32 v92, 0xbfb8aa3b, v93
	v_exp_f32_e32 v92, v92
	s_nop 0
	v_add_f32_e32 v92, 1.0, v92
	v_rcp_f32_e32 v92, v92
	s_nop 0
	v_mul_f32_e32 v105, v93, v92
	v_mul_f32_e32 v92, 0xbfb8aa3b, v94
	v_exp_f32_e32 v92, v92
	s_nop 0
	v_add_f32_e32 v92, 1.0, v92
	v_rcp_f32_e32 v92, v92
	s_nop 0
	v_mul_f32_e32 v106, v94, v92
	v_mul_f32_e32 v92, 0xbfb8aa3b, v95
	v_exp_f32_e32 v92, v92
	v_cvt_pk_bf16_f32 v238, v104, v105
	s_nop 0
	v_add_f32_e32 v92, 1.0, v92
	v_rcp_f32_e32 v92, v92
	s_nop 0
	v_mul_f32_e32 v95, v95, v92
	v_lshl_add_u64 v[92:93], v[136:137], 1, v[102:103]
	v_cvt_pk_bf16_f32 v239, v106, v95
	s_and_b64 vcc, exec, s[10:11]
	s_mov_b64 s[24:25], -1
	s_cbranch_vccz .LBB0_1685

; __device__ __forceinline__ float siluf_(float v) { return v * sigmoidf_(v); }
; __device__ __forceinline__ void store_bf16x4(bf16_t* p, f32x4 v) { u32x2 w; w.x = cvt_pk_bf16(v[0], v[1]); w.y = cvt_pk_bf16(v[2], v[3]); *(u32x2*)p = w; }
;   __device__ __forceinline__ void operator()(const f32x4 (&acc)[2][2][4][2], const pg8::Unit& u, int wr, int wc, int fr, int fq) const {
;     ...
;       if (pn < 2) { f32x4 o; for (int j = 0; j < 4; ++j) o[j] = siluf_(v[j]); store_bf16x4(QH + (size_t)row * 512 + col, o); }
.LBB0_1729:
	s_nop 0
	v_mul_f32_e32 v92, 0xbfb8aa3b, v88
	v_exp_f32_e32 v92, v92
	s_nop 0
	v_add_f32_e32 v92, 1.0, v92
	v_rcp_f32_e32 v92, v92
	s_nop 0
	v_mul_f32_e32 v92, v88, v92
	v_mul_f32_e32 v88, 0xbfb8aa3b, v89
	v_exp_f32_e32 v88, v88
	s_nop 0
	v_add_f32_e32 v88, 1.0, v88
	v_rcp_f32_e32 v88, v88
	s_nop 0
	v_mul_f32_e32 v93, v89, v88
	v_mul_f32_e32 v88, 0xbfb8aa3b, v90
	v_exp_f32_e32 v88, v88
	s_nop 0
	v_add_f32_e32 v88, 1.0, v88
	v_rcp_f32_e32 v88, v88
	s_nop 0
	v_mul_f32_e32 v94, v90, v88
	v_mul_f32_e32 v88, 0xbfb8aa3b, v91
	v_exp_f32_e32 v88, v88
	v_cvt_pk_bf16_f32 v240, v92, v93
	s_nop 0
	v_add_f32_e32 v88, 1.0, v88
	v_rcp_f32_e32 v88, v88
	s_nop 0
	v_mul_f32_e32 v91, v91, v88
	v_lshl_add_u64 v[88:89], v[136:137], 1, v[102:103]
	v_cvt_pk_bf16_f32 v241, v94, v91
	s_nop 1
	v_permlane16_swap_b32_e32 v238, v240
	v_permlane16_swap_b32_e32 v239, v241
	v_lshl_add_u64 v[242:243], v[88:89], 0, v[244:245]
	global_store_dwordx4 v[242:243], v[238:241], off
	s_and_b64 vcc, exec, s[10:11]
	s_mov_b64 s[24:25], -1
	s_cbranch_vccz .LBB0_1699

; __device__ __forceinline__ float siluf_(float v) { return v * sigmoidf_(v); }
; __device__ __forceinline__ void store_bf16x4(bf16_t* p, f32x4 v) { u32x2 w; w.x = cvt_pk_bf16(v[0], v[1]); w.y = cvt_pk_bf16(v[2], v[3]); *(u32x2*)p = w; }
;   __device__ __forceinline__ void operator()(const f32x4 (&acc)[2][2][4][2], const pg8::Unit& u, int wr, int wc, int fr, int fq) const {
;     ...
;       if (pn < 2) { f32x4 o; for (int j = 0; j < 4; ++j) o[j] = siluf_(v[j]); store_bf16x4(QH + (size_t)row * 512 + col, o); }
.LBB0_1731:
	s_nop 0
	v_mul_f32_e32 v88, 0xbfb8aa3b, v84
	v_exp_f32_e32 v88, v88
	s_nop 0
	v_add_f32_e32 v88, 1.0, v88
	v_rcp_f32_e32 v88, v88
	s_nop 0
	v_mul_f32_e32 v88, v84, v88
	v_mul_f32_e32 v84, 0xbfb8aa3b, v85
	v_exp_f32_e32 v84, v84
	s_nop 0
	v_add_f32_e32 v84, 1.0, v84
	v_rcp_f32_e32 v84, v84
	s_nop 0
	v_mul_f32_e32 v89, v85, v84
	v_mul_f32_e32 v84, 0xbfb8aa3b, v86
	v_exp_f32_e32 v84, v84
	s_nop 0
	v_add_f32_e32 v84, 1.0, v84
	v_rcp_f32_e32 v84, v84
	s_nop 0
	v_mul_f32_e32 v90, v86, v84
	v_mul_f32_e32 v84, 0xbfb8aa3b, v87
	v_exp_f32_e32 v84, v84
	v_cvt_pk_bf16_f32 v238, v88, v89
	s_nop 0
	v_add_f32_e32 v84, 1.0, v84
	v_rcp_f32_e32 v84, v84
	s_nop 0
	v_mul_f32_e32 v87, v87, v84
	v_lshl_add_u64 v[84:85], v[136:137], 1, v[102:103]
	v_cvt_pk_bf16_f32 v239, v90, v87
	s_and_b64 vcc, exec, s[10:11]
	s_mov_b64 s[24:25], -1
	s_cbranch_vccz .LBB0_1713

; __device__ __forceinline__ float sigmoidf_(float v) { return __builtin_amdgcn_rcpf(1.0f + __expf(-v)); }
; __device__ __forceinline__ float siluf_(float v) { return v * sigmoidf_(v); }
; __device__ __forceinline__ void store_bf16x4(bf16_t* p, f32x4 v) { u32x2 w; w.x = cvt_pk_bf16(v[0], v[1]); w.y = cvt_pk_bf16(v[2], v[3]); *(u32x2*)p = w; }
;   __device__ __forceinline__ void operator()(const f32x4 (&acc)[2][2][4][2], const pg8::Unit& u, int wr, int wc, int fr, int fq) const {
;     ...
;     EPI_LOOP(
;       if (pn < 2) { f32x4 o; for (int j = 0; j < 4; ++j) o[j] = siluf_(v[j]); store_bf16x4(QH + (size_t)row * 512 + col, o); }
;       else if (pn < 6) { const int c = col - 512; const f32x4 lb = *(const f32x4*)(LBj + c); f32x4 o; for (int j = 0; j < 4; ++j) o[j] = lb[j] + (1.f - lb[j]) * sigmoidf_(v[j]); *(f32x4*)(F + (size_t)row * 1024 + c) = o; }
;       else if (pn < 8) { store_bf16x4(VH + (size_t)row * 512 + (col - 1536), v); }
;       else if (pn < 10) { f32x4 o; for (int j = 0; j < 4; ++j) o[j] = siluf_(v[j]); store_bf16x4(G + (size_t)row * 512 + (col - 2048), o); }
;       else { store_bf16x4(CQ + (size_t)row * 768 + (col - 2560), v); }
.LBB0_1733:
	v_mul_f32_e32 v84, 0xbfb8aa3b, v80
	v_exp_f32_e32 v84, v84
	s_nop 0
	v_add_f32_e32 v84, 1.0, v84
	v_rcp_f32_e32 v84, v84
	s_nop 0
	v_mul_f32_e32 v84, v80, v84
	v_mul_f32_e32 v80, 0xbfb8aa3b, v81
	v_exp_f32_e32 v80, v80
	s_nop 0
	v_add_f32_e32 v80, 1.0, v80
	v_rcp_f32_e32 v80, v80
	s_nop 0
	v_mul_f32_e32 v85, v81, v80
	v_mul_f32_e32 v80, 0xbfb8aa3b, v82
	v_exp_f32_e32 v80, v80
	s_nop 0
	v_add_f32_e32 v80, 1.0, v80
	v_rcp_f32_e32 v80, v80
	s_nop 0
	v_mul_f32_e32 v86, v82, v80
	v_mul_f32_e32 v80, 0xbfb8aa3b, v83
	v_exp_f32_e32 v80, v80
	v_cvt_pk_bf16_f32 v240, v84, v85
	s_nop 0
	v_add_f32_e32 v80, 1.0, v80
	v_rcp_f32_e32 v80, v80
	s_nop 0
	v_mul_f32_e32 v83, v83, v80
	v_lshl_add_u64 v[80:81], v[136:137], 1, v[102:103]
	v_cvt_pk_bf16_f32 v241, v86, v83
	s_nop 1
	v_permlane16_swap_b32_e32 v238, v240
	v_permlane16_swap_b32_e32 v239, v241
	v_lshl_add_u64 v[242:243], v[80:81], 0, v[244:245]
	global_store_dwordx4 v[242:243], v[238:241], off offset:256
.LBB0_1734:
	v_or_b32_e32 v80, 48, v138
	v_ashrrev_i32_e32 v81, 31, v80
	v_mad_i64_i32 v[84:85], s[24:25], v80, s64, 0
	v_lshlrev_b64 v[82:83], 10, v[80:81]
	v_lshlrev_b64 v[80:81], 12, v[80:81]
	s_and_b64 vcc, exec, s[10:11]
	s_mov_b64 s[24:25], -1
	s_cbranch_vccnz .LBB0_1790
	s_and_b64 vcc, exec, s[8:9]
	s_cbranch_vccnz .LBB0_1745
	s_andn2_b64 vcc, exec, s[84:85]
	s_cbranch_vccnz .LBB0_1742
	s_andn2_b64 vcc, exec, s[78:79]
	s_cbranch_vccnz .LBB0_1739
	v_lshl_add_u64 v[86:87], s[46:47], 0, v[84:85]
	v_mov_b32_e32 v88, v136
	v_mov_b32_e32 v89, v144
	v_lshl_add_u64 v[86:87], v[88:89], 1, v[86:87]
	v_add_co_u32_e32 v86, vcc, 0xfffff000, v86
	s_mov_b64 s[24:25], 0
	s_nop 0
	v_addc_co_u32_e32 v87, vcc, -1, v87, vcc
	v_cvt_pk_bf16_f32 v238, v76, v77
	v_cvt_pk_bf16_f32 v239, v78, v79
.LBB0_1739:
	s_andn2_b64 vcc, exec, s[24:25]
	s_cbranch_vccnz .LBB0_1741
	v_mul_f32_e32 v86, 0xbfb8aa3b, v76
	v_mul_f32_e32 v87, 0xbfb8aa3b, v77
	v_mul_f32_e32 v88, 0xbfb8aa3b, v78
	v_mul_f32_e32 v89, 0xbfb8aa3b, v79
	v_exp_f32_e32 v86, v86
	v_exp_f32_e32 v87, v87
	v_exp_f32_e32 v88, v88
	v_exp_f32_e32 v89, v89
	v_add_f32_e32 v86, 1.0, v86
	v_add_f32_e32 v87, 1.0, v87
	v_add_f32_e32 v88, 1.0, v88
	v_add_f32_e32 v89, 1.0, v89
	v_rcp_f32_e32 v86, v86
	v_rcp_f32_e32 v87, v87
	v_rcp_f32_e32 v88, v88
	v_rcp_f32_e32 v89, v89
	v_mul_f32_e32 v90, v76, v86
	v_mul_f32_e32 v91, v77, v87
	v_mul_f32_e32 v92, v78, v88
	v_mul_f32_e32 v93, v79, v89
	v_lshl_add_u64 v[86:87], s[48:49], 0, v[82:83]
	v_mov_b32_e32 v88, v136
	v_mov_b32_e32 v89, v144
	v_lshl_add_u64 v[86:87], v[88:89], 1, v[86:87]
	v_cvt_pk_bf16_f32 v238, v90, v91
	v_cvt_pk_bf16_f32 v239, v92, v93

; __device__ __forceinline__ void store_bf16x4(bf16_t* p, f32x4 v) { u32x2 w; w.x = cvt_pk_bf16(v[0], v[1]); w.y = cvt_pk_bf16(v[2], v[3]); *(u32x2*)p = w; }
;   __device__ __forceinline__ void operator()(const f32x4 (&acc)[2][2][4][2], const pg8::Unit& u, int wr, int wc, int fr, int fq) const {
;     ...
;       else if (pn < 8) { store_bf16x4(VH + (size_t)row * 512 + (col - 1536), v); }
.LBB0_1742:
	s_andn2_b64 vcc, exec, s[24:25]
	s_cbranch_vccnz .LBB0_1744
	v_lshl_add_u64 v[86:87], s[16:17], 0, v[82:83]
	v_mov_b32_e32 v88, v136
	v_mov_b32_e32 v89, v144
	v_lshl_add_u64 v[86:87], v[88:89], 1, v[86:87]
	v_cvt_pk_bf16_f32 v238, v76, v77
	v_cvt_pk_bf16_f32 v239, v78, v79

; __device__ __forceinline__ float siluf_(float v) { return v * sigmoidf_(v); }
; __device__ __forceinline__ void store_bf16x4(bf16_t* p, f32x4 v) { u32x2 w; w.x = cvt_pk_bf16(v[0], v[1]); w.y = cvt_pk_bf16(v[2], v[3]); *(u32x2*)p = w; }
;   __device__ __forceinline__ void operator()(const f32x4 (&acc)[2][2][4][2], const pg8::Unit& u, int wr, int wc, int fr, int fq) const {
;     ...
;       else if (pn < 10) { f32x4 o; for (int j = 0; j < 4; ++j) o[j] = siluf_(v[j]); store_bf16x4(G + (size_t)row * 512 + (col - 2048), o); }
;       else { store_bf16x4(CQ + (size_t)row * 768 + (col - 2560), v); }
.LBB0_1749:
	s_and_b64 vcc, exec, s[8:9]
	s_cbranch_vccnz .LBB0_1759
	s_andn2_b64 vcc, exec, s[84:85]
	s_cbranch_vccnz .LBB0_1756
	s_andn2_b64 vcc, exec, s[78:79]
	s_cbranch_vccnz .LBB0_1753
	v_lshl_add_u64 v[76:77], s[46:47], 0, v[84:85]
	v_mov_b32_e32 v78, v136
	v_mov_b32_e32 v79, v144
	v_lshl_add_u64 v[76:77], v[78:79], 1, v[76:77]
	v_add_co_u32_e32 v76, vcc, 0xfffff000, v76
	s_mov_b64 s[24:25], 0
	s_nop 0
	v_addc_co_u32_e32 v77, vcc, -1, v77, vcc
	v_cvt_pk_bf16_f32 v240, v72, v73
	v_cvt_pk_bf16_f32 v241, v74, v75
	s_nop 1
	v_permlane16_swap_b32_e32 v238, v240
	v_permlane16_swap_b32_e32 v239, v241
	v_lshl_add_u64 v[242:243], v[76:77], 0, v[244:245]
	global_store_dwordx4 v[242:243], v[238:241], off offset:-1024
.LBB0_1753:
	s_andn2_b64 vcc, exec, s[24:25]
	s_cbranch_vccnz .LBB0_1755
	v_mul_f32_e32 v76, 0xbfb8aa3b, v72
	v_mul_f32_e32 v77, 0xbfb8aa3b, v73
	v_mul_f32_e32 v78, 0xbfb8aa3b, v74
	v_mul_f32_e32 v79, 0xbfb8aa3b, v75
	v_exp_f32_e32 v76, v76
	v_exp_f32_e32 v77, v77
	v_exp_f32_e32 v78, v78
	v_exp_f32_e32 v79, v79
	v_add_f32_e32 v76, 1.0, v76
	v_add_f32_e32 v77, 1.0, v77
	v_add_f32_e32 v78, 1.0, v78
	v_add_f32_e32 v79, 1.0, v79
	v_rcp_f32_e32 v76, v76
	v_rcp_f32_e32 v77, v77
	v_rcp_f32_e32 v78, v78
	v_rcp_f32_e32 v79, v79
	v_mul_f32_e32 v88, v72, v76
	v_mul_f32_e32 v89, v73, v77
	v_mul_f32_e32 v90, v74, v78
	v_mul_f32_e32 v91, v75, v79
	v_lshl_add_u64 v[76:77], s[48:49], 0, v[82:83]
	v_mov_b32_e32 v78, v136
	v_mov_b32_e32 v79, v144
	v_lshl_add_u64 v[76:77], v[78:79], 1, v[76:77]
	v_cvt_pk_bf16_f32 v240, v88, v89
	v_cvt_pk_bf16_f32 v241, v90, v91
	s_nop 1
	v_permlane16_swap_b32_e32 v238, v240
	v_permlane16_swap_b32_e32 v239, v241
	v_lshl_add_u64 v[242:243], v[76:77], 0, v[244:245]
	global_store_dwordx4 v[242:243], v[238:241], off offset:-4096

; __device__ __forceinline__ void store_bf16x4(bf16_t* p, f32x4 v) { u32x2 w; w.x = cvt_pk_bf16(v[0], v[1]); w.y = cvt_pk_bf16(v[2], v[3]); *(u32x2*)p = w; }
;   __device__ __forceinline__ void operator()(const f32x4 (&acc)[2][2][4][2], const pg8::Unit& u, int wr, int wc, int fr, int fq) const {
;     ...
;       else if (pn < 8) { store_bf16x4(VH + (size_t)row * 512 + (col - 1536), v); }
.LBB0_1756:
	s_andn2_b64 vcc, exec, s[24:25]
	s_cbranch_vccnz .LBB0_1758
	v_lshl_add_u64 v[76:77], s[16:17], 0, v[82:83]
	v_mov_b32_e32 v78, v136
	v_mov_b32_e32 v79, v144
	v_lshl_add_u64 v[76:77], v[78:79], 1, v[76:77]
	v_cvt_pk_bf16_f32 v240, v72, v73
	v_cvt_pk_bf16_f32 v241, v74, v75
	s_nop 1
	v_permlane16_swap_b32_e32 v238, v240
	v_permlane16_swap_b32_e32 v239, v241
	v_lshl_add_u64 v[242:243], v[76:77], 0, v[244:245]
	global_store_dwordx4 v[242:243], v[238:241], off offset:-3072

; __device__ __forceinline__ float siluf_(float v) { return v * sigmoidf_(v); }
; __device__ __forceinline__ void store_bf16x4(bf16_t* p, f32x4 v) { u32x2 w; w.x = cvt_pk_bf16(v[0], v[1]); w.y = cvt_pk_bf16(v[2], v[3]); *(u32x2*)p = w; }
;   __device__ __forceinline__ void operator()(const f32x4 (&acc)[2][2][4][2], const pg8::Unit& u, int wr, int wc, int fr, int fq) const {
;     ...
;       else if (pn < 10) { f32x4 o; for (int j = 0; j < 4; ++j) o[j] = siluf_(v[j]); store_bf16x4(G + (size_t)row * 512 + (col - 2048), o); }
;       else { store_bf16x4(CQ + (size_t)row * 768 + (col - 2560), v); }
.LBB0_1763:
	s_and_b64 vcc, exec, s[8:9]
	s_cbranch_vccnz .LBB0_1773
	s_andn2_b64 vcc, exec, s[84:85]
	s_cbranch_vccnz .LBB0_1770
	s_andn2_b64 vcc, exec, s[78:79]
	s_cbranch_vccnz .LBB0_1767
	v_lshl_add_u64 v[72:73], s[46:47], 0, v[84:85]
	v_mov_b32_e32 v74, v136
	v_mov_b32_e32 v75, v144
	v_lshl_add_u64 v[72:73], v[74:75], 1, v[72:73]
	v_add_co_u32_e32 v72, vcc, 0xfffff000, v72
	s_mov_b64 s[24:25], 0
	s_nop 0
	v_addc_co_u32_e32 v73, vcc, -1, v73, vcc
	v_cvt_pk_bf16_f32 v238, v68, v69
	v_cvt_pk_bf16_f32 v239, v70, v71
.LBB0_1767:
	s_andn2_b64 vcc, exec, s[24:25]
	s_cbranch_vccnz .LBB0_1769
	v_mul_f32_e32 v72, 0xbfb8aa3b, v68
	v_mul_f32_e32 v73, 0xbfb8aa3b, v69
	v_mul_f32_e32 v74, 0xbfb8aa3b, v70
	v_mul_f32_e32 v75, 0xbfb8aa3b, v71
	v_exp_f32_e32 v72, v72
	v_exp_f32_e32 v73, v73
	v_exp_f32_e32 v74, v74
	v_exp_f32_e32 v75, v75
	v_add_f32_e32 v72, 1.0, v72
	v_add_f32_e32 v73, 1.0, v73
	v_add_f32_e32 v74, 1.0, v74
	v_add_f32_e32 v75, 1.0, v75
	v_rcp_f32_e32 v72, v72
	v_rcp_f32_e32 v73, v73
	v_rcp_f32_e32 v74, v74
	v_rcp_f32_e32 v75, v75
	v_mul_f32_e32 v76, v68, v72
	v_mul_f32_e32 v77, v69, v73
	v_mul_f32_e32 v78, v70, v74
	v_mul_f32_e32 v79, v71, v75
	v_lshl_add_u64 v[72:73], s[48:49], 0, v[82:83]
	v_mov_b32_e32 v74, v136
	v_mov_b32_e32 v75, v144
	v_lshl_add_u64 v[72:73], v[74:75], 1, v[72:73]
	v_cvt_pk_bf16_f32 v238, v76, v77
	v_cvt_pk_bf16_f32 v239, v78, v79

; __device__ __forceinline__ void store_bf16x4(bf16_t* p, f32x4 v) { u32x2 w; w.x = cvt_pk_bf16(v[0], v[1]); w.y = cvt_pk_bf16(v[2], v[3]); *(u32x2*)p = w; }
;   __device__ __forceinline__ void operator()(const f32x4 (&acc)[2][2][4][2], const pg8::Unit& u, int wr, int wc, int fr, int fq) const {
;     ...
;       else if (pn < 8) { store_bf16x4(VH + (size_t)row * 512 + (col - 1536), v); }
.LBB0_1770:
	s_andn2_b64 vcc, exec, s[24:25]
	s_cbranch_vccnz .LBB0_1772
	v_lshl_add_u64 v[72:73], s[16:17], 0, v[82:83]
	v_mov_b32_e32 v74, v136
	v_mov_b32_e32 v75, v144
	v_lshl_add_u64 v[72:73], v[74:75], 1, v[72:73]
	v_cvt_pk_bf16_f32 v238, v68, v69
	v_cvt_pk_bf16_f32 v239, v70, v71

; __device__ __forceinline__ float siluf_(float v) { return v * sigmoidf_(v); }
; __device__ __forceinline__ void store_bf16x4(bf16_t* p, f32x4 v) { u32x2 w; w.x = cvt_pk_bf16(v[0], v[1]); w.y = cvt_pk_bf16(v[2], v[3]); *(u32x2*)p = w; }
;   __device__ __forceinline__ void operator()(const f32x4 (&acc)[2][2][4][2], const pg8::Unit& u, int wr, int wc, int fr, int fq) const {
;     ...
;       else if (pn < 10) { f32x4 o; for (int j = 0; j < 4; ++j) o[j] = siluf_(v[j]); store_bf16x4(G + (size_t)row * 512 + (col - 2048), o); }
;       else { store_bf16x4(CQ + (size_t)row * 768 + (col - 2560), v); }
.LBB0_1777:
	s_and_b64 vcc, exec, s[8:9]
	s_cbranch_vccnz .LBB0_1787
	s_andn2_b64 vcc, exec, s[84:85]
	s_cbranch_vccnz .LBB0_1784
	s_andn2_b64 vcc, exec, s[78:79]
	s_cbranch_vccnz .LBB0_1781
	v_lshl_add_u64 v[68:69], s[46:47], 0, v[84:85]
	v_mov_b32_e32 v70, v136
	v_mov_b32_e32 v71, v144
	v_lshl_add_u64 v[68:69], v[70:71], 1, v[68:69]
	v_add_co_u32_e32 v68, vcc, 0xfffff000, v68
	s_mov_b64 s[24:25], 0
	s_nop 0
	v_addc_co_u32_e32 v69, vcc, -1, v69, vcc
	v_cvt_pk_bf16_f32 v240, v64, v65
	v_cvt_pk_bf16_f32 v241, v66, v67
	s_nop 1
	v_permlane16_swap_b32_e32 v238, v240
	v_permlane16_swap_b32_e32 v239, v241
	v_lshl_add_u64 v[242:243], v[68:69], 0, v[244:245]
	global_store_dwordx4 v[242:243], v[238:241], off offset:-768
.LBB0_1781:
	s_andn2_b64 vcc, exec, s[24:25]
	s_cbranch_vccnz .LBB0_1783
	v_mul_f32_e32 v68, 0xbfb8aa3b, v64
	v_mul_f32_e32 v69, 0xbfb8aa3b, v65
	v_mul_f32_e32 v70, 0xbfb8aa3b, v66
	v_mul_f32_e32 v71, 0xbfb8aa3b, v67
	v_exp_f32_e32 v68, v68
	v_exp_f32_e32 v69, v69
	v_exp_f32_e32 v70, v70
	v_exp_f32_e32 v71, v71
	v_add_f32_e32 v68, 1.0, v68
	v_add_f32_e32 v69, 1.0, v69
	v_add_f32_e32 v70, 1.0, v70
	v_add_f32_e32 v71, 1.0, v71
	v_rcp_f32_e32 v68, v68
	v_rcp_f32_e32 v69, v69
	v_rcp_f32_e32 v70, v70
	v_rcp_f32_e32 v71, v71
	v_mul_f32_e32 v72, v64, v68
	v_mul_f32_e32 v73, v65, v69
	v_mul_f32_e32 v74, v66, v70
	v_mul_f32_e32 v75, v67, v71
	v_lshl_add_u64 v[68:69], s[48:49], 0, v[82:83]
	v_mov_b32_e32 v70, v136
	v_mov_b32_e32 v71, v144
	v_lshl_add_u64 v[68:69], v[70:71], 1, v[68:69]
	v_cvt_pk_bf16_f32 v240, v72, v73
	v_cvt_pk_bf16_f32 v241, v74, v75
	s_nop 1
	v_permlane16_swap_b32_e32 v238, v240
	v_permlane16_swap_b32_e32 v239, v241
	v_lshl_add_u64 v[242:243], v[68:69], 0, v[244:245]
	global_store_dwordx4 v[242:243], v[238:241], off offset:-3840

; __device__ __forceinline__ void store_bf16x4(bf16_t* p, f32x4 v) { u32x2 w; w.x = cvt_pk_bf16(v[0], v[1]); w.y = cvt_pk_bf16(v[2], v[3]); *(u32x2*)p = w; }
;   __device__ __forceinline__ void operator()(const f32x4 (&acc)[2][2][4][2], const pg8::Unit& u, int wr, int wc, int fr, int fq) const {
;     ...
;       else if (pn < 8) { store_bf16x4(VH + (size_t)row * 512 + (col - 1536), v); }
.LBB0_1784:
	s_andn2_b64 vcc, exec, s[24:25]
	s_cbranch_vccnz .LBB0_1786
	v_lshl_add_u64 v[68:69], s[16:17], 0, v[82:83]
	v_mov_b32_e32 v70, v136
	v_mov_b32_e32 v71, v144
	v_lshl_add_u64 v[68:69], v[70:71], 1, v[68:69]
	v_cvt_pk_bf16_f32 v240, v64, v65
	v_cvt_pk_bf16_f32 v241, v66, v67
	s_nop 1
	v_permlane16_swap_b32_e32 v238, v240
	v_permlane16_swap_b32_e32 v239, v241
	v_lshl_add_u64 v[242:243], v[68:69], 0, v[244:245]
	global_store_dwordx4 v[242:243], v[238:241], off offset:-2816

; __device__ __forceinline__ float siluf_(float v) { return v * sigmoidf_(v); }
; __device__ __forceinline__ void store_bf16x4(bf16_t* p, f32x4 v) { u32x2 w; w.x = cvt_pk_bf16(v[0], v[1]); w.y = cvt_pk_bf16(v[2], v[3]); *(u32x2*)p = w; }
;   __device__ __forceinline__ void operator()(const f32x4 (&acc)[2][2][4][2], const pg8::Unit& u, int wr, int wc, int fr, int fq) const {
;     ...
;       if (pn < 2) { f32x4 o; for (int j = 0; j < 4; ++j) o[j] = siluf_(v[j]); store_bf16x4(QH + (size_t)row * 512 + col, o); }
.LBB0_1791:
	v_mul_f32_e32 v88, 0xbfb8aa3b, v76
	v_exp_f32_e32 v88, v88
	s_nop 0
	v_add_f32_e32 v88, 1.0, v88
	v_rcp_f32_e32 v88, v88
	s_nop 0
	v_mul_f32_e32 v88, v76, v88
	v_mul_f32_e32 v76, 0xbfb8aa3b, v77
	v_exp_f32_e32 v76, v76
	s_nop 0
	v_add_f32_e32 v76, 1.0, v76
	v_rcp_f32_e32 v76, v76
	s_nop 0
	v_mul_f32_e32 v89, v77, v76
	v_mul_f32_e32 v76, 0xbfb8aa3b, v78
	v_exp_f32_e32 v76, v76
	s_nop 0
	v_add_f32_e32 v76, 1.0, v76
	v_rcp_f32_e32 v76, v76
	s_nop 0
	v_mul_f32_e32 v90, v78, v76
	v_mul_f32_e32 v76, 0xbfb8aa3b, v79
	v_exp_f32_e32 v76, v76
	v_cvt_pk_bf16_f32 v238, v88, v89
	s_nop 0
	v_add_f32_e32 v76, 1.0, v76
	v_rcp_f32_e32 v76, v76
	s_nop 0
	v_mul_f32_e32 v79, v79, v76
	v_lshl_add_u64 v[76:77], v[136:137], 1, v[86:87]
	v_cvt_pk_bf16_f32 v239, v90, v79
	s_and_b64 vcc, exec, s[10:11]
	s_mov_b64 s[24:25], -1
	s_cbranch_vccz .LBB0_1749

; __device__ __forceinline__ float siluf_(float v) { return v * sigmoidf_(v); }
; __device__ __forceinline__ void store_bf16x4(bf16_t* p, f32x4 v) { u32x2 w; w.x = cvt_pk_bf16(v[0], v[1]); w.y = cvt_pk_bf16(v[2], v[3]); *(u32x2*)p = w; }
;   __device__ __forceinline__ void operator()(const f32x4 (&acc)[2][2][4][2], const pg8::Unit& u, int wr, int wc, int fr, int fq) const {
;     ...
;       if (pn < 2) { f32x4 o; for (int j = 0; j < 4; ++j) o[j] = siluf_(v[j]); store_bf16x4(QH + (size_t)row * 512 + col, o); }
.LBB0_1793:
	s_nop 0
	v_mul_f32_e32 v76, 0xbfb8aa3b, v72
	v_exp_f32_e32 v76, v76
	s_nop 0
	v_add_f32_e32 v76, 1.0, v76
	v_rcp_f32_e32 v76, v76
	s_nop 0
	v_mul_f32_e32 v76, v72, v76
	v_mul_f32_e32 v72, 0xbfb8aa3b, v73
	v_exp_f32_e32 v72, v72
	s_nop 0
	v_add_f32_e32 v72, 1.0, v72
	v_rcp_f32_e32 v72, v72
	s_nop 0
	v_mul_f32_e32 v77, v73, v72
	v_mul_f32_e32 v72, 0xbfb8aa3b, v74
	v_exp_f32_e32 v72, v72
	s_nop 0
	v_add_f32_e32 v72, 1.0, v72
	v_rcp_f32_e32 v72, v72
	s_nop 0
	v_mul_f32_e32 v78, v74, v72
	v_mul_f32_e32 v72, 0xbfb8aa3b, v75
	v_exp_f32_e32 v72, v72
	v_cvt_pk_bf16_f32 v240, v76, v77
	s_nop 0
	v_add_f32_e32 v72, 1.0, v72
	v_rcp_f32_e32 v72, v72
	s_nop 0
	v_mul_f32_e32 v75, v75, v72
	v_lshl_add_u64 v[72:73], v[136:137], 1, v[86:87]
	v_cvt_pk_bf16_f32 v241, v78, v75
	s_nop 1
	v_permlane16_swap_b32_e32 v238, v240
	v_permlane16_swap_b32_e32 v239, v241
	v_lshl_add_u64 v[242:243], v[72:73], 0, v[244:245]
	global_store_dwordx4 v[242:243], v[238:241], off
	s_and_b64 vcc, exec, s[10:11]
	s_mov_b64 s[24:25], -1
	s_cbranch_vccz .LBB0_1763

; __device__ __forceinline__ float siluf_(float v) { return v * sigmoidf_(v); }
; __device__ __forceinline__ void store_bf16x4(bf16_t* p, f32x4 v) { u32x2 w; w.x = cvt_pk_bf16(v[0], v[1]); w.y = cvt_pk_bf16(v[2], v[3]); *(u32x2*)p = w; }
;   __device__ __forceinline__ void operator()(const f32x4 (&acc)[2][2][4][2], const pg8::Unit& u, int wr, int wc, int fr, int fq) const {
;     ...
;       if (pn < 2) { f32x4 o; for (int j = 0; j < 4; ++j) o[j] = siluf_(v[j]); store_bf16x4(QH + (size_t)row * 512 + col, o); }
.LBB0_1795:
	s_nop 0
	v_mul_f32_e32 v72, 0xbfb8aa3b, v68
	v_exp_f32_e32 v72, v72
	s_nop 0
	v_add_f32_e32 v72, 1.0, v72
	v_rcp_f32_e32 v72, v72
	s_nop 0
	v_mul_f32_e32 v72, v68, v72
	v_mul_f32_e32 v68, 0xbfb8aa3b, v69
	v_exp_f32_e32 v68, v68
	s_nop 0
	v_add_f32_e32 v68, 1.0, v68
	v_rcp_f32_e32 v68, v68
	s_nop 0
	v_mul_f32_e32 v73, v69, v68
	v_mul_f32_e32 v68, 0xbfb8aa3b, v70
	v_exp_f32_e32 v68, v68
	s_nop 0
	v_add_f32_e32 v68, 1.0, v68
	v_rcp_f32_e32 v68, v68
	s_nop 0
	v_mul_f32_e32 v74, v70, v68
	v_mul_f32_e32 v68, 0xbfb8aa3b, v71
	v_exp_f32_e32 v68, v68
	v_cvt_pk_bf16_f32 v238, v72, v73
	s_nop 0
	v_add_f32_e32 v68, 1.0, v68
	v_rcp_f32_e32 v68, v68
	s_nop 0
	v_mul_f32_e32 v71, v71, v68
	v_lshl_add_u64 v[68:69], v[136:137], 1, v[86:87]
	v_cvt_pk_bf16_f32 v239, v74, v71
	s_and_b64 vcc, exec, s[10:11]
	s_mov_b64 s[24:25], -1
	s_cbranch_vccz .LBB0_1777

; __device__ __forceinline__ float sigmoidf_(float v) { return __builtin_amdgcn_rcpf(1.0f + __expf(-v)); }
; __device__ __forceinline__ float siluf_(float v) { return v * sigmoidf_(v); }
; __device__ __forceinline__ void store_bf16x4(bf16_t* p, f32x4 v) { u32x2 w; w.x = cvt_pk_bf16(v[0], v[1]); w.y = cvt_pk_bf16(v[2], v[3]); *(u32x2*)p = w; }
;   __device__ __forceinline__ void operator()(const f32x4 (&acc)[2][2][4][2], const pg8::Unit& u, int wr, int wc, int fr, int fq) const {
;     ...
;     EPI_LOOP(
;       if (pn < 2) { f32x4 o; for (int j = 0; j < 4; ++j) o[j] = siluf_(v[j]); store_bf16x4(QH + (size_t)row * 512 + col, o); }
;       else if (pn < 6) { const int c = col - 512; const f32x4 lb = *(const f32x4*)(LBj + c); f32x4 o; for (int j = 0; j < 4; ++j) o[j] = lb[j] + (1.f - lb[j]) * sigmoidf_(v[j]); *(f32x4*)(F + (size_t)row * 1024 + c) = o; }
;       else if (pn < 8) { store_bf16x4(VH + (size_t)row * 512 + (col - 1536), v); }
;       else if (pn < 10) { f32x4 o; for (int j = 0; j < 4; ++j) o[j] = siluf_(v[j]); store_bf16x4(G + (size_t)row * 512 + (col - 2048), o); }
;       else { store_bf16x4(CQ + (size_t)row * 768 + (col - 2560), v); }
.LBB0_1797:
	v_mul_f32_e32 v68, 0xbfb8aa3b, v64
	v_exp_f32_e32 v68, v68
	s_nop 0
	v_add_f32_e32 v68, 1.0, v68
	v_rcp_f32_e32 v68, v68
	s_nop 0
	v_mul_f32_e32 v68, v64, v68
	v_mul_f32_e32 v64, 0xbfb8aa3b, v65
	v_exp_f32_e32 v64, v64
	s_nop 0
	v_add_f32_e32 v64, 1.0, v64
	v_rcp_f32_e32 v64, v64
	s_nop 0
	v_mul_f32_e32 v69, v65, v64
	v_mul_f32_e32 v64, 0xbfb8aa3b, v66
	v_exp_f32_e32 v64, v64
	s_nop 0
	v_add_f32_e32 v64, 1.0, v64
	v_rcp_f32_e32 v64, v64
	s_nop 0
	v_mul_f32_e32 v70, v66, v64
	v_mul_f32_e32 v64, 0xbfb8aa3b, v67
	v_exp_f32_e32 v64, v64
	v_cvt_pk_bf16_f32 v240, v68, v69
	s_nop 0
	v_add_f32_e32 v64, 1.0, v64
	v_rcp_f32_e32 v64, v64
	s_nop 0
	v_mul_f32_e32 v67, v67, v64
	v_lshl_add_u64 v[64:65], v[136:137], 1, v[86:87]
	v_cvt_pk_bf16_f32 v241, v70, v67
	s_nop 1
	v_permlane16_swap_b32_e32 v238, v240
	v_permlane16_swap_b32_e32 v239, v241
	v_lshl_add_u64 v[242:243], v[64:65], 0, v[244:245]
	global_store_dwordx4 v[242:243], v[238:241], off offset:256
.LBB0_1798:
	v_add_u32_e32 v64, 0x80, v138
	v_ashrrev_i32_e32 v65, 31, v64
	v_mad_i64_i32 v[68:69], s[24:25], v64, s64, 0
	v_lshlrev_b64 v[66:67], 10, v[64:65]
	v_lshlrev_b64 v[64:65], 12, v[64:65]
	s_and_b64 vcc, exec, s[10:11]
	s_mov_b64 s[24:25], -1
	s_cbranch_vccnz .LBB0_1854
	s_and_b64 vcc, exec, s[8:9]
	s_cbranch_vccnz .LBB0_1809
	s_andn2_b64 vcc, exec, s[84:85]
	s_cbranch_vccnz .LBB0_1806
	s_andn2_b64 vcc, exec, s[78:79]
	s_cbranch_vccnz .LBB0_1803
	v_lshl_add_u64 v[70:71], s[46:47], 0, v[68:69]
	v_mov_b32_e32 v72, v136
	v_mov_b32_e32 v73, v144
	v_lshl_add_u64 v[70:71], v[72:73], 1, v[70:71]
	v_add_co_u32_e32 v70, vcc, 0xfffff000, v70
	s_mov_b64 s[24:25], 0
	s_nop 0
	v_addc_co_u32_e32 v71, vcc, -1, v71, vcc
	v_cvt_pk_bf16_f32 v238, v60, v61
	v_cvt_pk_bf16_f32 v239, v62, v63
.LBB0_1803:
	s_andn2_b64 vcc, exec, s[24:25]
	s_cbranch_vccnz .LBB0_1805
	v_mul_f32_e32 v70, 0xbfb8aa3b, v60
	v_mul_f32_e32 v71, 0xbfb8aa3b, v61
	v_mul_f32_e32 v72, 0xbfb8aa3b, v62
	v_mul_f32_e32 v73, 0xbfb8aa3b, v63
	v_exp_f32_e32 v70, v70
	v_exp_f32_e32 v71, v71
	v_exp_f32_e32 v72, v72
	v_exp_f32_e32 v73, v73
	v_add_f32_e32 v70, 1.0, v70
	v_add_f32_e32 v71, 1.0, v71
	v_add_f32_e32 v72, 1.0, v72
	v_add_f32_e32 v73, 1.0, v73
	v_rcp_f32_e32 v70, v70
	v_rcp_f32_e32 v71, v71
	v_rcp_f32_e32 v72, v72
	v_rcp_f32_e32 v73, v73
	v_mul_f32_e32 v74, v60, v70
	v_mul_f32_e32 v75, v61, v71
	v_mul_f32_e32 v76, v62, v72
	v_mul_f32_e32 v77, v63, v73
	v_lshl_add_u64 v[70:71], s[48:49], 0, v[66:67]
	v_mov_b32_e32 v72, v136
	v_mov_b32_e32 v73, v144
	v_lshl_add_u64 v[70:71], v[72:73], 1, v[70:71]
	v_cvt_pk_bf16_f32 v238, v74, v75
	v_cvt_pk_bf16_f32 v239, v76, v77

; __device__ __forceinline__ void store_bf16x4(bf16_t* p, f32x4 v) { u32x2 w; w.x = cvt_pk_bf16(v[0], v[1]); w.y = cvt_pk_bf16(v[2], v[3]); *(u32x2*)p = w; }
;   __device__ __forceinline__ void operator()(const f32x4 (&acc)[2][2][4][2], const pg8::Unit& u, int wr, int wc, int fr, int fq) const {
;     ...
;       else if (pn < 8) { store_bf16x4(VH + (size_t)row * 512 + (col - 1536), v); }
.LBB0_1806:
	s_andn2_b64 vcc, exec, s[24:25]
	s_cbranch_vccnz .LBB0_1808
	v_lshl_add_u64 v[70:71], s[16:17], 0, v[66:67]
	v_mov_b32_e32 v72, v136
	v_mov_b32_e32 v73, v144
	v_lshl_add_u64 v[70:71], v[72:73], 1, v[70:71]
	v_cvt_pk_bf16_f32 v238, v60, v61
	v_cvt_pk_bf16_f32 v239, v62, v63

; __device__ __forceinline__ float siluf_(float v) { return v * sigmoidf_(v); }
; __device__ __forceinline__ void store_bf16x4(bf16_t* p, f32x4 v) { u32x2 w; w.x = cvt_pk_bf16(v[0], v[1]); w.y = cvt_pk_bf16(v[2], v[3]); *(u32x2*)p = w; }
;   __device__ __forceinline__ void operator()(const f32x4 (&acc)[2][2][4][2], const pg8::Unit& u, int wr, int wc, int fr, int fq) const {
;     ...
;       else if (pn < 10) { f32x4 o; for (int j = 0; j < 4; ++j) o[j] = siluf_(v[j]); store_bf16x4(G + (size_t)row * 512 + (col - 2048), o); }
;       else { store_bf16x4(CQ + (size_t)row * 768 + (col - 2560), v); }
.LBB0_1813:
	s_and_b64 vcc, exec, s[8:9]
	s_cbranch_vccnz .LBB0_1823
	s_andn2_b64 vcc, exec, s[84:85]
	s_cbranch_vccnz .LBB0_1820
	s_andn2_b64 vcc, exec, s[78:79]
	s_cbranch_vccnz .LBB0_1817
	v_lshl_add_u64 v[60:61], s[46:47], 0, v[68:69]
	v_mov_b32_e32 v62, v136
	v_mov_b32_e32 v63, v144
	v_lshl_add_u64 v[60:61], v[62:63], 1, v[60:61]
	v_add_co_u32_e32 v60, vcc, 0xfffff000, v60
	s_mov_b64 s[24:25], 0
	s_nop 0
	v_addc_co_u32_e32 v61, vcc, -1, v61, vcc
	v_cvt_pk_bf16_f32 v240, v56, v57
	v_cvt_pk_bf16_f32 v241, v58, v59
	s_nop 1
	v_permlane16_swap_b32_e32 v238, v240
	v_permlane16_swap_b32_e32 v239, v241
	v_lshl_add_u64 v[242:243], v[60:61], 0, v[244:245]
	global_store_dwordx4 v[242:243], v[238:241], off offset:-1024
.LBB0_1817:
	s_andn2_b64 vcc, exec, s[24:25]
	s_cbranch_vccnz .LBB0_1819
	v_mul_f32_e32 v60, 0xbfb8aa3b, v56
	v_mul_f32_e32 v61, 0xbfb8aa3b, v57
	v_mul_f32_e32 v62, 0xbfb8aa3b, v58
	v_mul_f32_e32 v63, 0xbfb8aa3b, v59
	v_exp_f32_e32 v60, v60
	v_exp_f32_e32 v61, v61
	v_exp_f32_e32 v62, v62
	v_exp_f32_e32 v63, v63
	v_add_f32_e32 v60, 1.0, v60
	v_add_f32_e32 v61, 1.0, v61
	v_add_f32_e32 v62, 1.0, v62
	v_add_f32_e32 v63, 1.0, v63
	v_rcp_f32_e32 v60, v60
	v_rcp_f32_e32 v61, v61
	v_rcp_f32_e32 v62, v62
	v_rcp_f32_e32 v63, v63
	v_mul_f32_e32 v72, v56, v60
	v_mul_f32_e32 v73, v57, v61
	v_mul_f32_e32 v74, v58, v62
	v_mul_f32_e32 v75, v59, v63
	v_lshl_add_u64 v[60:61], s[48:49], 0, v[66:67]
	v_mov_b32_e32 v62, v136
	v_mov_b32_e32 v63, v144
	v_lshl_add_u64 v[60:61], v[62:63], 1, v[60:61]
	v_cvt_pk_bf16_f32 v240, v72, v73
	v_cvt_pk_bf16_f32 v241, v74, v75
	s_nop 1
	v_permlane16_swap_b32_e32 v238, v240
	v_permlane16_swap_b32_e32 v239, v241
	v_lshl_add_u64 v[242:243], v[60:61], 0, v[244:245]
	global_store_dwordx4 v[242:243], v[238:241], off offset:-4096

; __device__ __forceinline__ void store_bf16x4(bf16_t* p, f32x4 v) { u32x2 w; w.x = cvt_pk_bf16(v[0], v[1]); w.y = cvt_pk_bf16(v[2], v[3]); *(u32x2*)p = w; }
;   __device__ __forceinline__ void operator()(const f32x4 (&acc)[2][2][4][2], const pg8::Unit& u, int wr, int wc, int fr, int fq) const {
;     ...
;       else if (pn < 8) { store_bf16x4(VH + (size_t)row * 512 + (col - 1536), v); }
.LBB0_1820:
	s_andn2_b64 vcc, exec, s[24:25]
	s_cbranch_vccnz .LBB0_1822
	v_lshl_add_u64 v[60:61], s[16:17], 0, v[66:67]
	v_mov_b32_e32 v62, v136
	v_mov_b32_e32 v63, v144
	v_lshl_add_u64 v[60:61], v[62:63], 1, v[60:61]
	v_cvt_pk_bf16_f32 v240, v56, v57
	v_cvt_pk_bf16_f32 v241, v58, v59
	s_nop 1
	v_permlane16_swap_b32_e32 v238, v240
	v_permlane16_swap_b32_e32 v239, v241
	v_lshl_add_u64 v[242:243], v[60:61], 0, v[244:245]
	global_store_dwordx4 v[242:243], v[238:241], off offset:-3072

; __device__ __forceinline__ float siluf_(float v) { return v * sigmoidf_(v); }
; __device__ __forceinline__ void store_bf16x4(bf16_t* p, f32x4 v) { u32x2 w; w.x = cvt_pk_bf16(v[0], v[1]); w.y = cvt_pk_bf16(v[2], v[3]); *(u32x2*)p = w; }
;   __device__ __forceinline__ void operator()(const f32x4 (&acc)[2][2][4][2], const pg8::Unit& u, int wr, int wc, int fr, int fq) const {
;     ...
;       else if (pn < 10) { f32x4 o; for (int j = 0; j < 4; ++j) o[j] = siluf_(v[j]); store_bf16x4(G + (size_t)row * 512 + (col - 2048), o); }
;       else { store_bf16x4(CQ + (size_t)row * 768 + (col - 2560), v); }
.LBB0_1827:
	s_and_b64 vcc, exec, s[8:9]
	s_cbranch_vccnz .LBB0_1837
	s_andn2_b64 vcc, exec, s[84:85]
	s_cbranch_vccnz .LBB0_1834
	s_andn2_b64 vcc, exec, s[78:79]
	s_cbranch_vccnz .LBB0_1831
	v_lshl_add_u64 v[56:57], s[46:47], 0, v[68:69]
	v_mov_b32_e32 v58, v136
	v_mov_b32_e32 v59, v144
	v_lshl_add_u64 v[56:57], v[58:59], 1, v[56:57]
	v_add_co_u32_e32 v56, vcc, 0xfffff000, v56
	s_mov_b64 s[24:25], 0
	s_nop 0
	v_addc_co_u32_e32 v57, vcc, -1, v57, vcc
	v_cvt_pk_bf16_f32 v238, v52, v53
	v_cvt_pk_bf16_f32 v239, v54, v55
.LBB0_1831:
	s_andn2_b64 vcc, exec, s[24:25]
	s_cbranch_vccnz .LBB0_1833
	v_mul_f32_e32 v56, 0xbfb8aa3b, v52
	v_mul_f32_e32 v57, 0xbfb8aa3b, v53
	v_mul_f32_e32 v58, 0xbfb8aa3b, v54
	v_mul_f32_e32 v59, 0xbfb8aa3b, v55
	v_exp_f32_e32 v56, v56
	v_exp_f32_e32 v57, v57
	v_exp_f32_e32 v58, v58
	v_exp_f32_e32 v59, v59
	v_add_f32_e32 v56, 1.0, v56
	v_add_f32_e32 v57, 1.0, v57
	v_add_f32_e32 v58, 1.0, v58
	v_add_f32_e32 v59, 1.0, v59
	v_rcp_f32_e32 v56, v56
	v_rcp_f32_e32 v57, v57
	v_rcp_f32_e32 v58, v58
	v_rcp_f32_e32 v59, v59
	v_mul_f32_e32 v60, v52, v56
	v_mul_f32_e32 v61, v53, v57
	v_mul_f32_e32 v62, v54, v58
	v_mul_f32_e32 v63, v55, v59
	v_lshl_add_u64 v[56:57], s[48:49], 0, v[66:67]
	v_mov_b32_e32 v58, v136
	v_mov_b32_e32 v59, v144
	v_lshl_add_u64 v[56:57], v[58:59], 1, v[56:57]
	v_cvt_pk_bf16_f32 v238, v60, v61
	v_cvt_pk_bf16_f32 v239, v62, v63

; __device__ __forceinline__ void store_bf16x4(bf16_t* p, f32x4 v) { u32x2 w; w.x = cvt_pk_bf16(v[0], v[1]); w.y = cvt_pk_bf16(v[2], v[3]); *(u32x2*)p = w; }
;   __device__ __forceinline__ void operator()(const f32x4 (&acc)[2][2][4][2], const pg8::Unit& u, int wr, int wc, int fr, int fq) const {
;     ...
;       else if (pn < 8) { store_bf16x4(VH + (size_t)row * 512 + (col - 1536), v); }
.LBB0_1834:
	s_andn2_b64 vcc, exec, s[24:25]
	s_cbranch_vccnz .LBB0_1836
	v_lshl_add_u64 v[56:57], s[16:17], 0, v[66:67]
	v_mov_b32_e32 v58, v136
	v_mov_b32_e32 v59, v144
	v_lshl_add_u64 v[56:57], v[58:59], 1, v[56:57]
	v_cvt_pk_bf16_f32 v238, v52, v53
	v_cvt_pk_bf16_f32 v239, v54, v55

; __device__ __forceinline__ float siluf_(float v) { return v * sigmoidf_(v); }
; __device__ __forceinline__ void store_bf16x4(bf16_t* p, f32x4 v) { u32x2 w; w.x = cvt_pk_bf16(v[0], v[1]); w.y = cvt_pk_bf16(v[2], v[3]); *(u32x2*)p = w; }
;   __device__ __forceinline__ void operator()(const f32x4 (&acc)[2][2][4][2], const pg8::Unit& u, int wr, int wc, int fr, int fq) const {
;     ...
;       else if (pn < 10) { f32x4 o; for (int j = 0; j < 4; ++j) o[j] = siluf_(v[j]); store_bf16x4(G + (size_t)row * 512 + (col - 2048), o); }
;       else { store_bf16x4(CQ + (size_t)row * 768 + (col - 2560), v); }
.LBB0_1841:
	s_and_b64 vcc, exec, s[8:9]
	s_cbranch_vccnz .LBB0_1851
	s_andn2_b64 vcc, exec, s[84:85]
	s_cbranch_vccnz .LBB0_1848
	s_andn2_b64 vcc, exec, s[78:79]
	s_cbranch_vccnz .LBB0_1845
	v_lshl_add_u64 v[52:53], s[46:47], 0, v[68:69]
	v_mov_b32_e32 v54, v136
	v_mov_b32_e32 v55, v144
	v_lshl_add_u64 v[52:53], v[54:55], 1, v[52:53]
	v_add_co_u32_e32 v52, vcc, 0xfffff000, v52
	s_mov_b64 s[24:25], 0
	s_nop 0
	v_addc_co_u32_e32 v53, vcc, -1, v53, vcc
	v_cvt_pk_bf16_f32 v240, v48, v49
	v_cvt_pk_bf16_f32 v241, v50, v51
	s_nop 1
	v_permlane16_swap_b32_e32 v238, v240
	v_permlane16_swap_b32_e32 v239, v241
	v_lshl_add_u64 v[242:243], v[52:53], 0, v[244:245]
	global_store_dwordx4 v[242:243], v[238:241], off offset:-768
.LBB0_1845:
	s_andn2_b64 vcc, exec, s[24:25]
	s_cbranch_vccnz .LBB0_1847
	v_mul_f32_e32 v52, 0xbfb8aa3b, v48
	v_mul_f32_e32 v53, 0xbfb8aa3b, v49
	v_mul_f32_e32 v54, 0xbfb8aa3b, v50
	v_mul_f32_e32 v55, 0xbfb8aa3b, v51
	v_exp_f32_e32 v52, v52
	v_exp_f32_e32 v53, v53
	v_exp_f32_e32 v54, v54
	v_exp_f32_e32 v55, v55
	v_add_f32_e32 v52, 1.0, v52
	v_add_f32_e32 v53, 1.0, v53
	v_add_f32_e32 v54, 1.0, v54
	v_add_f32_e32 v55, 1.0, v55
	v_rcp_f32_e32 v52, v52
	v_rcp_f32_e32 v53, v53
	v_rcp_f32_e32 v54, v54
	v_rcp_f32_e32 v55, v55
	v_mul_f32_e32 v56, v48, v52
	v_mul_f32_e32 v57, v49, v53
	v_mul_f32_e32 v58, v50, v54
	v_mul_f32_e32 v59, v51, v55
	v_lshl_add_u64 v[52:53], s[48:49], 0, v[66:67]
	v_mov_b32_e32 v54, v136
	v_mov_b32_e32 v55, v144
	v_lshl_add_u64 v[52:53], v[54:55], 1, v[52:53]
	v_cvt_pk_bf16_f32 v240, v56, v57
	v_cvt_pk_bf16_f32 v241, v58, v59
	s_nop 1
	v_permlane16_swap_b32_e32 v238, v240
	v_permlane16_swap_b32_e32 v239, v241
	v_lshl_add_u64 v[242:243], v[52:53], 0, v[244:245]
	global_store_dwordx4 v[242:243], v[238:241], off offset:-3840

; __device__ __forceinline__ void store_bf16x4(bf16_t* p, f32x4 v) { u32x2 w; w.x = cvt_pk_bf16(v[0], v[1]); w.y = cvt_pk_bf16(v[2], v[3]); *(u32x2*)p = w; }
;   __device__ __forceinline__ void operator()(const f32x4 (&acc)[2][2][4][2], const pg8::Unit& u, int wr, int wc, int fr, int fq) const {
;     ...
;       else if (pn < 8) { store_bf16x4(VH + (size_t)row * 512 + (col - 1536), v); }
.LBB0_1848:
	s_andn2_b64 vcc, exec, s[24:25]
	s_cbranch_vccnz .LBB0_1850
	v_lshl_add_u64 v[52:53], s[16:17], 0, v[66:67]
	v_mov_b32_e32 v54, v136
	v_mov_b32_e32 v55, v144
	v_lshl_add_u64 v[52:53], v[54:55], 1, v[52:53]
	v_cvt_pk_bf16_f32 v240, v48, v49
	v_cvt_pk_bf16_f32 v241, v50, v51
	s_nop 1
	v_permlane16_swap_b32_e32 v238, v240
	v_permlane16_swap_b32_e32 v239, v241
	v_lshl_add_u64 v[242:243], v[52:53], 0, v[244:245]
	global_store_dwordx4 v[242:243], v[238:241], off offset:-2816

; __device__ __forceinline__ float siluf_(float v) { return v * sigmoidf_(v); }
; __device__ __forceinline__ void store_bf16x4(bf16_t* p, f32x4 v) { u32x2 w; w.x = cvt_pk_bf16(v[0], v[1]); w.y = cvt_pk_bf16(v[2], v[3]); *(u32x2*)p = w; }
;   __device__ __forceinline__ void operator()(const f32x4 (&acc)[2][2][4][2], const pg8::Unit& u, int wr, int wc, int fr, int fq) const {
;     ...
;       if (pn < 2) { f32x4 o; for (int j = 0; j < 4; ++j) o[j] = siluf_(v[j]); store_bf16x4(QH + (size_t)row * 512 + col, o); }
.LBB0_1855:
	v_mul_f32_e32 v72, 0xbfb8aa3b, v60
	v_exp_f32_e32 v72, v72
	s_nop 0
	v_add_f32_e32 v72, 1.0, v72
	v_rcp_f32_e32 v72, v72
	s_nop 0
	v_mul_f32_e32 v72, v60, v72
	v_mul_f32_e32 v60, 0xbfb8aa3b, v61
	v_exp_f32_e32 v60, v60
	s_nop 0
	v_add_f32_e32 v60, 1.0, v60
	v_rcp_f32_e32 v60, v60
	s_nop 0
	v_mul_f32_e32 v73, v61, v60
	v_mul_f32_e32 v60, 0xbfb8aa3b, v62
	v_exp_f32_e32 v60, v60
	s_nop 0
	v_add_f32_e32 v60, 1.0, v60
	v_rcp_f32_e32 v60, v60
	s_nop 0
	v_mul_f32_e32 v74, v62, v60
	v_mul_f32_e32 v60, 0xbfb8aa3b, v63
	v_exp_f32_e32 v60, v60
	v_cvt_pk_bf16_f32 v238, v72, v73
	s_nop 0
	v_add_f32_e32 v60, 1.0, v60
	v_rcp_f32_e32 v60, v60
	s_nop 0
	v_mul_f32_e32 v63, v63, v60
	v_lshl_add_u64 v[60:61], v[136:137], 1, v[70:71]
	v_cvt_pk_bf16_f32 v239, v74, v63
	s_and_b64 vcc, exec, s[10:11]
	s_mov_b64 s[24:25], -1
	s_cbranch_vccz .LBB0_1813

; __device__ __forceinline__ float siluf_(float v) { return v * sigmoidf_(v); }
; __device__ __forceinline__ void store_bf16x4(bf16_t* p, f32x4 v) { u32x2 w; w.x = cvt_pk_bf16(v[0], v[1]); w.y = cvt_pk_bf16(v[2], v[3]); *(u32x2*)p = w; }
;   __device__ __forceinline__ void operator()(const f32x4 (&acc)[2][2][4][2], const pg8::Unit& u, int wr, int wc, int fr, int fq) const {
;     ...
;       if (pn < 2) { f32x4 o; for (int j = 0; j < 4; ++j) o[j] = siluf_(v[j]); store_bf16x4(QH + (size_t)row * 512 + col, o); }
.LBB0_1857:
	s_nop 0
	v_mul_f32_e32 v60, 0xbfb8aa3b, v56
	v_exp_f32_e32 v60, v60
	s_nop 0
	v_add_f32_e32 v60, 1.0, v60
	v_rcp_f32_e32 v60, v60
	s_nop 0
	v_mul_f32_e32 v60, v56, v60
	v_mul_f32_e32 v56, 0xbfb8aa3b, v57
	v_exp_f32_e32 v56, v56
	s_nop 0
	v_add_f32_e32 v56, 1.0, v56
	v_rcp_f32_e32 v56, v56
	s_nop 0
	v_mul_f32_e32 v61, v57, v56
	v_mul_f32_e32 v56, 0xbfb8aa3b, v58
	v_exp_f32_e32 v56, v56
	s_nop 0
	v_add_f32_e32 v56, 1.0, v56
	v_rcp_f32_e32 v56, v56
	s_nop 0
	v_mul_f32_e32 v62, v58, v56
	v_mul_f32_e32 v56, 0xbfb8aa3b, v59
	v_exp_f32_e32 v56, v56
	v_cvt_pk_bf16_f32 v240, v60, v61
	s_nop 0
	v_add_f32_e32 v56, 1.0, v56
	v_rcp_f32_e32 v56, v56
	s_nop 0
	v_mul_f32_e32 v59, v59, v56
	v_lshl_add_u64 v[56:57], v[136:137], 1, v[70:71]
	v_cvt_pk_bf16_f32 v241, v62, v59
	s_nop 1
	v_permlane16_swap_b32_e32 v238, v240
	v_permlane16_swap_b32_e32 v239, v241
	v_lshl_add_u64 v[242:243], v[56:57], 0, v[244:245]
	global_store_dwordx4 v[242:243], v[238:241], off
	s_and_b64 vcc, exec, s[10:11]
	s_mov_b64 s[24:25], -1
	s_cbranch_vccz .LBB0_1827

; __device__ __forceinline__ float siluf_(float v) { return v * sigmoidf_(v); }
; __device__ __forceinline__ void store_bf16x4(bf16_t* p, f32x4 v) { u32x2 w; w.x = cvt_pk_bf16(v[0], v[1]); w.y = cvt_pk_bf16(v[2], v[3]); *(u32x2*)p = w; }
;   __device__ __forceinline__ void operator()(const f32x4 (&acc)[2][2][4][2], const pg8::Unit& u, int wr, int wc, int fr, int fq) const {
;     ...
;       if (pn < 2) { f32x4 o; for (int j = 0; j < 4; ++j) o[j] = siluf_(v[j]); store_bf16x4(QH + (size_t)row * 512 + col, o); }
.LBB0_1859:
	s_nop 0
	v_mul_f32_e32 v56, 0xbfb8aa3b, v52
	v_exp_f32_e32 v56, v56
	s_nop 0
	v_add_f32_e32 v56, 1.0, v56
	v_rcp_f32_e32 v56, v56
	s_nop 0
	v_mul_f32_e32 v56, v52, v56
	v_mul_f32_e32 v52, 0xbfb8aa3b, v53
	v_exp_f32_e32 v52, v52
	s_nop 0
	v_add_f32_e32 v52, 1.0, v52
	v_rcp_f32_e32 v52, v52
	s_nop 0
	v_mul_f32_e32 v57, v53, v52
	v_mul_f32_e32 v52, 0xbfb8aa3b, v54
	v_exp_f32_e32 v52, v52
	s_nop 0
	v_add_f32_e32 v52, 1.0, v52
	v_rcp_f32_e32 v52, v52
	s_nop 0
	v_mul_f32_e32 v58, v54, v52
	v_mul_f32_e32 v52, 0xbfb8aa3b, v55
	v_exp_f32_e32 v52, v52
	v_cvt_pk_bf16_f32 v238, v56, v57
	s_nop 0
	v_add_f32_e32 v52, 1.0, v52
	v_rcp_f32_e32 v52, v52
	s_nop 0
	v_mul_f32_e32 v55, v55, v52
	v_lshl_add_u64 v[52:53], v[136:137], 1, v[70:71]
	v_cvt_pk_bf16_f32 v239, v58, v55
	s_and_b64 vcc, exec, s[10:11]
	s_mov_b64 s[24:25], -1
	s_cbranch_vccz .LBB0_1841

; __device__ __forceinline__ float sigmoidf_(float v) { return __builtin_amdgcn_rcpf(1.0f + __expf(-v)); }
; __device__ __forceinline__ float siluf_(float v) { return v * sigmoidf_(v); }
; __device__ __forceinline__ void store_bf16x4(bf16_t* p, f32x4 v) { u32x2 w; w.x = cvt_pk_bf16(v[0], v[1]); w.y = cvt_pk_bf16(v[2], v[3]); *(u32x2*)p = w; }
;   __device__ __forceinline__ void operator()(const f32x4 (&acc)[2][2][4][2], const pg8::Unit& u, int wr, int wc, int fr, int fq) const {
;     ...
;     EPI_LOOP(
;       if (pn < 2) { f32x4 o; for (int j = 0; j < 4; ++j) o[j] = siluf_(v[j]); store_bf16x4(QH + (size_t)row * 512 + col, o); }
;       else if (pn < 6) { const int c = col - 512; const f32x4 lb = *(const f32x4*)(LBj + c); f32x4 o; for (int j = 0; j < 4; ++j) o[j] = lb[j] + (1.f - lb[j]) * sigmoidf_(v[j]); *(f32x4*)(F + (size_t)row * 1024 + c) = o; }
;       else if (pn < 8) { store_bf16x4(VH + (size_t)row * 512 + (col - 1536), v); }
;       else if (pn < 10) { f32x4 o; for (int j = 0; j < 4; ++j) o[j] = siluf_(v[j]); store_bf16x4(G + (size_t)row * 512 + (col - 2048), o); }
;       else { store_bf16x4(CQ + (size_t)row * 768 + (col - 2560), v); }
.LBB0_1861:
	v_mul_f32_e32 v52, 0xbfb8aa3b, v48
	v_exp_f32_e32 v52, v52
	s_nop 0
	v_add_f32_e32 v52, 1.0, v52
	v_rcp_f32_e32 v52, v52
	s_nop 0
	v_mul_f32_e32 v52, v48, v52
	v_mul_f32_e32 v48, 0xbfb8aa3b, v49
	v_exp_f32_e32 v48, v48
	s_nop 0
	v_add_f32_e32 v48, 1.0, v48
	v_rcp_f32_e32 v48, v48
	s_nop 0
	v_mul_f32_e32 v53, v49, v48
	v_mul_f32_e32 v48, 0xbfb8aa3b, v50
	v_exp_f32_e32 v48, v48
	s_nop 0
	v_add_f32_e32 v48, 1.0, v48
	v_rcp_f32_e32 v48, v48
	s_nop 0
	v_mul_f32_e32 v54, v50, v48
	v_mul_f32_e32 v48, 0xbfb8aa3b, v51
	v_exp_f32_e32 v48, v48
	v_cvt_pk_bf16_f32 v240, v52, v53
	s_nop 0
	v_add_f32_e32 v48, 1.0, v48
	v_rcp_f32_e32 v48, v48
	s_nop 0
	v_mul_f32_e32 v51, v51, v48
	v_lshl_add_u64 v[48:49], v[136:137], 1, v[70:71]
	v_cvt_pk_bf16_f32 v241, v54, v51
	s_nop 1
	v_permlane16_swap_b32_e32 v238, v240
	v_permlane16_swap_b32_e32 v239, v241
	v_lshl_add_u64 v[242:243], v[48:49], 0, v[244:245]
	global_store_dwordx4 v[242:243], v[238:241], off offset:256
.LBB0_1862:
	v_add_u32_e32 v48, 0x90, v138
	v_ashrrev_i32_e32 v49, 31, v48
	v_mad_i64_i32 v[52:53], s[24:25], v48, s64, 0
	v_lshlrev_b64 v[50:51], 10, v[48:49]
	v_lshlrev_b64 v[48:49], 12, v[48:49]
	s_and_b64 vcc, exec, s[10:11]
	s_mov_b64 s[24:25], -1
	s_cbranch_vccnz .LBB0_1918
	s_and_b64 vcc, exec, s[8:9]
	s_cbranch_vccnz .LBB0_1873
	s_andn2_b64 vcc, exec, s[84:85]
	s_cbranch_vccnz .LBB0_1870
	s_andn2_b64 vcc, exec, s[78:79]
	s_cbranch_vccnz .LBB0_1867
	v_lshl_add_u64 v[54:55], s[46:47], 0, v[52:53]
	v_mov_b32_e32 v56, v136
	v_mov_b32_e32 v57, v144
	v_lshl_add_u64 v[54:55], v[56:57], 1, v[54:55]
	v_add_co_u32_e32 v54, vcc, 0xfffff000, v54
	s_mov_b64 s[24:25], 0
	s_nop 0
	v_addc_co_u32_e32 v55, vcc, -1, v55, vcc
	v_cvt_pk_bf16_f32 v238, v44, v45
	v_cvt_pk_bf16_f32 v239, v46, v47
.LBB0_1867:
	s_andn2_b64 vcc, exec, s[24:25]
	s_cbranch_vccnz .LBB0_1869
	v_mul_f32_e32 v54, 0xbfb8aa3b, v44
	v_mul_f32_e32 v55, 0xbfb8aa3b, v45
	v_mul_f32_e32 v56, 0xbfb8aa3b, v46
	v_mul_f32_e32 v57, 0xbfb8aa3b, v47
	v_exp_f32_e32 v54, v54
	v_exp_f32_e32 v55, v55
	v_exp_f32_e32 v56, v56
	v_exp_f32_e32 v57, v57
	v_add_f32_e32 v54, 1.0, v54
	v_add_f32_e32 v55, 1.0, v55
	v_add_f32_e32 v56, 1.0, v56
	v_add_f32_e32 v57, 1.0, v57
	v_rcp_f32_e32 v54, v54
	v_rcp_f32_e32 v55, v55
	v_rcp_f32_e32 v56, v56
	v_rcp_f32_e32 v57, v57
	v_mul_f32_e32 v58, v44, v54
	v_mul_f32_e32 v59, v45, v55
	v_mul_f32_e32 v60, v46, v56
	v_mul_f32_e32 v61, v47, v57
	v_lshl_add_u64 v[54:55], s[48:49], 0, v[50:51]
	v_mov_b32_e32 v56, v136
	v_mov_b32_e32 v57, v144
	v_lshl_add_u64 v[54:55], v[56:57], 1, v[54:55]
	v_cvt_pk_bf16_f32 v238, v58, v59
	v_cvt_pk_bf16_f32 v239, v60, v61

; __device__ __forceinline__ void store_bf16x4(bf16_t* p, f32x4 v) { u32x2 w; w.x = cvt_pk_bf16(v[0], v[1]); w.y = cvt_pk_bf16(v[2], v[3]); *(u32x2*)p = w; }
;   __device__ __forceinline__ void operator()(const f32x4 (&acc)[2][2][4][2], const pg8::Unit& u, int wr, int wc, int fr, int fq) const {
;     ...
;       else if (pn < 8) { store_bf16x4(VH + (size_t)row * 512 + (col - 1536), v); }
.LBB0_1870:
	s_andn2_b64 vcc, exec, s[24:25]
	s_cbranch_vccnz .LBB0_1872
	v_lshl_add_u64 v[54:55], s[16:17], 0, v[50:51]
	v_mov_b32_e32 v56, v136
	v_mov_b32_e32 v57, v144
	v_lshl_add_u64 v[54:55], v[56:57], 1, v[54:55]
	v_cvt_pk_bf16_f32 v238, v44, v45
	v_cvt_pk_bf16_f32 v239, v46, v47

; __device__ __forceinline__ float sigmoidf_(float v) { return __builtin_amdgcn_rcpf(1.0f + __expf(-v)); }
; __device__ __forceinline__ float siluf_(float v) { return v * sigmoidf_(v); }
; __device__ __forceinline__ void store_bf16x4(bf16_t* p, f32x4 v) { u32x2 w; w.x = cvt_pk_bf16(v[0], v[1]); w.y = cvt_pk_bf16(v[2], v[3]); *(u32x2*)p = w; }
;   __device__ __forceinline__ void operator()(const f32x4 (&acc)[2][2][4][2], const pg8::Unit& u, int wr, int wc, int fr, int fq) const {
;     const int pn = u.pn;
;     EPI_LOOP(
;       if (pn < 2) { f32x4 o; for (int j = 0; j < 4; ++j) o[j] = siluf_(v[j]); store_bf16x4(QH + (size_t)row * 512 + col, o); }
;       else if (pn < 6) { const int c = col - 512; const f32x4 lb = *(const f32x4*)(LBj + c); f32x4 o; for (int j = 0; j < 4; ++j) o[j] = lb[j] + (1.f - lb[j]) * sigmoidf_(v[j]); *(f32x4*)(F + (size_t)row * 1024 + c) = o; }
;       else if (pn < 8) { store_bf16x4(VH + (size_t)row * 512 + (col - 1536), v); }
;       else if (pn < 10) { f32x4 o; for (int j = 0; j < 4; ++j) o[j] = siluf_(v[j]); store_bf16x4(G + (size_t)row * 512 + (col - 2048), o); }
;       else { store_bf16x4(CQ + (size_t)row * 768 + (col - 2560), v); }
.LBB0_1877:
	s_and_b64 vcc, exec, s[8:9]
	s_cbranch_vccnz .LBB0_1887
	s_andn2_b64 vcc, exec, s[84:85]
	s_cbranch_vccnz .LBB0_1884
	s_andn2_b64 vcc, exec, s[78:79]
	s_cbranch_vccnz .LBB0_1881
	v_lshl_add_u64 v[44:45], s[46:47], 0, v[52:53]
	v_mov_b32_e32 v46, v136
	v_mov_b32_e32 v47, v144
	v_lshl_add_u64 v[44:45], v[46:47], 1, v[44:45]
	v_add_co_u32_e32 v44, vcc, 0xfffff000, v44
	s_mov_b64 s[24:25], 0
	s_nop 0
	v_addc_co_u32_e32 v45, vcc, -1, v45, vcc
	v_cvt_pk_bf16_f32 v240, v40, v41
	v_cvt_pk_bf16_f32 v241, v42, v43
	s_nop 1
	v_permlane16_swap_b32_e32 v238, v240
	v_permlane16_swap_b32_e32 v239, v241
	v_lshl_add_u64 v[242:243], v[44:45], 0, v[244:245]
	global_store_dwordx4 v[242:243], v[238:241], off offset:-1024
.LBB0_1881:
	s_andn2_b64 vcc, exec, s[24:25]
	s_cbranch_vccnz .LBB0_1883
	v_mul_f32_e32 v44, 0xbfb8aa3b, v40
	v_mul_f32_e32 v45, 0xbfb8aa3b, v41
	v_mul_f32_e32 v46, 0xbfb8aa3b, v42
	v_mul_f32_e32 v47, 0xbfb8aa3b, v43
	v_exp_f32_e32 v44, v44
	v_exp_f32_e32 v45, v45
	v_exp_f32_e32 v46, v46
	v_exp_f32_e32 v47, v47
	v_add_f32_e32 v44, 1.0, v44
	v_add_f32_e32 v45, 1.0, v45
	v_add_f32_e32 v46, 1.0, v46
	v_add_f32_e32 v47, 1.0, v47
	v_rcp_f32_e32 v44, v44
	v_rcp_f32_e32 v45, v45
	v_rcp_f32_e32 v46, v46
	v_rcp_f32_e32 v47, v47
	v_mul_f32_e32 v56, v40, v44
	v_mul_f32_e32 v57, v41, v45
	v_mul_f32_e32 v58, v42, v46
	v_mul_f32_e32 v59, v43, v47
	v_lshl_add_u64 v[44:45], s[48:49], 0, v[50:51]
	v_mov_b32_e32 v46, v136
	v_mov_b32_e32 v47, v144
	v_lshl_add_u64 v[44:45], v[46:47], 1, v[44:45]
	v_cvt_pk_bf16_f32 v240, v56, v57
	v_cvt_pk_bf16_f32 v241, v58, v59
	s_nop 1
	v_permlane16_swap_b32_e32 v238, v240
	v_permlane16_swap_b32_e32 v239, v241
	v_lshl_add_u64 v[242:243], v[44:45], 0, v[244:245]
	global_store_dwordx4 v[242:243], v[238:241], off offset:-4096

; __device__ __forceinline__ void store_bf16x4(bf16_t* p, f32x4 v) { u32x2 w; w.x = cvt_pk_bf16(v[0], v[1]); w.y = cvt_pk_bf16(v[2], v[3]); *(u32x2*)p = w; }
;   __device__ __forceinline__ void operator()(const f32x4 (&acc)[2][2][4][2], const pg8::Unit& u, int wr, int wc, int fr, int fq) const {
;     ...
;       else if (pn < 8) { store_bf16x4(VH + (size_t)row * 512 + (col - 1536), v); }
.LBB0_1884:
	s_andn2_b64 vcc, exec, s[24:25]
	s_cbranch_vccnz .LBB0_1886
	v_lshl_add_u64 v[44:45], s[16:17], 0, v[50:51]
	v_mov_b32_e32 v46, v136
	v_mov_b32_e32 v47, v144
	v_lshl_add_u64 v[44:45], v[46:47], 1, v[44:45]
	v_cvt_pk_bf16_f32 v240, v40, v41
	v_cvt_pk_bf16_f32 v241, v42, v43
	s_nop 1
	v_permlane16_swap_b32_e32 v238, v240
	v_permlane16_swap_b32_e32 v239, v241
	v_lshl_add_u64 v[242:243], v[44:45], 0, v[244:245]
	global_store_dwordx4 v[242:243], v[238:241], off offset:-3072

; __device__ __forceinline__ float sigmoidf_(float v) { return __builtin_amdgcn_rcpf(1.0f + __expf(-v)); }
; __device__ __forceinline__ float siluf_(float v) { return v * sigmoidf_(v); }
; __device__ __forceinline__ void store_bf16x4(bf16_t* p, f32x4 v) { u32x2 w; w.x = cvt_pk_bf16(v[0], v[1]); w.y = cvt_pk_bf16(v[2], v[3]); *(u32x2*)p = w; }
;   __device__ __forceinline__ void operator()(const f32x4 (&acc)[2][2][4][2], const pg8::Unit& u, int wr, int wc, int fr, int fq) const {
;     const int pn = u.pn;
;     EPI_LOOP(
;       if (pn < 2) { f32x4 o; for (int j = 0; j < 4; ++j) o[j] = siluf_(v[j]); store_bf16x4(QH + (size_t)row * 512 + col, o); }
;       else if (pn < 6) { const int c = col - 512; const f32x4 lb = *(const f32x4*)(LBj + c); f32x4 o; for (int j = 0; j < 4; ++j) o[j] = lb[j] + (1.f - lb[j]) * sigmoidf_(v[j]); *(f32x4*)(F + (size_t)row * 1024 + c) = o; }
;       else if (pn < 8) { store_bf16x4(VH + (size_t)row * 512 + (col - 1536), v); }
;       else if (pn < 10) { f32x4 o; for (int j = 0; j < 4; ++j) o[j] = siluf_(v[j]); store_bf16x4(G + (size_t)row * 512 + (col - 2048), o); }
;       else { store_bf16x4(CQ + (size_t)row * 768 + (col - 2560), v); }
.LBB0_1891:
	s_and_b64 vcc, exec, s[8:9]
	s_cbranch_vccnz .LBB0_1901
	s_andn2_b64 vcc, exec, s[84:85]
	s_cbranch_vccnz .LBB0_1898
	s_andn2_b64 vcc, exec, s[78:79]
	s_cbranch_vccnz .LBB0_1895
	v_lshl_add_u64 v[40:41], s[46:47], 0, v[52:53]
	v_mov_b32_e32 v42, v136
	v_mov_b32_e32 v43, v144
	v_lshl_add_u64 v[40:41], v[42:43], 1, v[40:41]
	v_add_co_u32_e32 v40, vcc, 0xfffff000, v40
	s_mov_b64 s[24:25], 0
	s_nop 0
	v_addc_co_u32_e32 v41, vcc, -1, v41, vcc
	v_cvt_pk_bf16_f32 v238, v36, v37
	v_cvt_pk_bf16_f32 v239, v38, v39
.LBB0_1895:
	s_andn2_b64 vcc, exec, s[24:25]
	s_cbranch_vccnz .LBB0_1897
	v_mul_f32_e32 v40, 0xbfb8aa3b, v36
	v_mul_f32_e32 v41, 0xbfb8aa3b, v37
	v_mul_f32_e32 v42, 0xbfb8aa3b, v38
	v_mul_f32_e32 v43, 0xbfb8aa3b, v39
	v_exp_f32_e32 v40, v40
	v_exp_f32_e32 v41, v41
	v_exp_f32_e32 v42, v42
	v_exp_f32_e32 v43, v43
	v_add_f32_e32 v40, 1.0, v40
	v_add_f32_e32 v41, 1.0, v41
	v_add_f32_e32 v42, 1.0, v42
	v_add_f32_e32 v43, 1.0, v43
	v_rcp_f32_e32 v40, v40
	v_rcp_f32_e32 v41, v41
	v_rcp_f32_e32 v42, v42
	v_rcp_f32_e32 v43, v43
	v_mul_f32_e32 v44, v36, v40
	v_mul_f32_e32 v45, v37, v41
	v_mul_f32_e32 v46, v38, v42
	v_mul_f32_e32 v47, v39, v43
	v_lshl_add_u64 v[40:41], s[48:49], 0, v[50:51]
	v_mov_b32_e32 v42, v136
	v_mov_b32_e32 v43, v144
	v_lshl_add_u64 v[40:41], v[42:43], 1, v[40:41]
	v_cvt_pk_bf16_f32 v238, v44, v45
	v_cvt_pk_bf16_f32 v239, v46, v47

; __device__ __forceinline__ void store_bf16x4(bf16_t* p, f32x4 v) { u32x2 w; w.x = cvt_pk_bf16(v[0], v[1]); w.y = cvt_pk_bf16(v[2], v[3]); *(u32x2*)p = w; }
;   __device__ __forceinline__ void operator()(const f32x4 (&acc)[2][2][4][2], const pg8::Unit& u, int wr, int wc, int fr, int fq) const {
;     ...
;       else if (pn < 8) { store_bf16x4(VH + (size_t)row * 512 + (col - 1536), v); }
.LBB0_1898:
	s_andn2_b64 vcc, exec, s[24:25]
	s_cbranch_vccnz .LBB0_1900
	v_lshl_add_u64 v[40:41], s[16:17], 0, v[50:51]
	v_mov_b32_e32 v42, v136
	v_mov_b32_e32 v43, v144
	v_lshl_add_u64 v[40:41], v[42:43], 1, v[40:41]
	v_cvt_pk_bf16_f32 v238, v36, v37
	v_cvt_pk_bf16_f32 v239, v38, v39

; __device__ __forceinline__ float sigmoidf_(float v) { return __builtin_amdgcn_rcpf(1.0f + __expf(-v)); }
; __device__ __forceinline__ float siluf_(float v) { return v * sigmoidf_(v); }
; __device__ __forceinline__ void store_bf16x4(bf16_t* p, f32x4 v) { u32x2 w; w.x = cvt_pk_bf16(v[0], v[1]); w.y = cvt_pk_bf16(v[2], v[3]); *(u32x2*)p = w; }
;   __device__ __forceinline__ void operator()(const f32x4 (&acc)[2][2][4][2], const pg8::Unit& u, int wr, int wc, int fr, int fq) const {
;     const int pn = u.pn;
;     EPI_LOOP(
;       if (pn < 2) { f32x4 o; for (int j = 0; j < 4; ++j) o[j] = siluf_(v[j]); store_bf16x4(QH + (size_t)row * 512 + col, o); }
;       else if (pn < 6) { const int c = col - 512; const f32x4 lb = *(const f32x4*)(LBj + c); f32x4 o; for (int j = 0; j < 4; ++j) o[j] = lb[j] + (1.f - lb[j]) * sigmoidf_(v[j]); *(f32x4*)(F + (size_t)row * 1024 + c) = o; }
;       else if (pn < 8) { store_bf16x4(VH + (size_t)row * 512 + (col - 1536), v); }
;       else if (pn < 10) { f32x4 o; for (int j = 0; j < 4; ++j) o[j] = siluf_(v[j]); store_bf16x4(G + (size_t)row * 512 + (col - 2048), o); }
;       else { store_bf16x4(CQ + (size_t)row * 768 + (col - 2560), v); }
.LBB0_1905:
	s_and_b64 vcc, exec, s[8:9]
	s_cbranch_vccnz .LBB0_1915
	s_andn2_b64 vcc, exec, s[84:85]
	s_cbranch_vccnz .LBB0_1912
	s_andn2_b64 vcc, exec, s[78:79]
	s_cbranch_vccnz .LBB0_1909
	v_lshl_add_u64 v[36:37], s[46:47], 0, v[52:53]
	v_mov_b32_e32 v38, v136
	v_mov_b32_e32 v39, v144
	v_lshl_add_u64 v[36:37], v[38:39], 1, v[36:37]
	v_add_co_u32_e32 v36, vcc, 0xfffff000, v36
	s_mov_b64 s[24:25], 0
	s_nop 0
	v_addc_co_u32_e32 v37, vcc, -1, v37, vcc
	v_cvt_pk_bf16_f32 v240, v32, v33
	v_cvt_pk_bf16_f32 v241, v34, v35
	s_nop 1
	v_permlane16_swap_b32_e32 v238, v240
	v_permlane16_swap_b32_e32 v239, v241
	v_lshl_add_u64 v[242:243], v[36:37], 0, v[244:245]
	global_store_dwordx4 v[242:243], v[238:241], off offset:-768
.LBB0_1909:
	s_andn2_b64 vcc, exec, s[24:25]
	s_cbranch_vccnz .LBB0_1911
	v_mul_f32_e32 v36, 0xbfb8aa3b, v32
	v_mul_f32_e32 v37, 0xbfb8aa3b, v33
	v_mul_f32_e32 v38, 0xbfb8aa3b, v34
	v_mul_f32_e32 v39, 0xbfb8aa3b, v35
	v_exp_f32_e32 v36, v36
	v_exp_f32_e32 v37, v37
	v_exp_f32_e32 v38, v38
	v_exp_f32_e32 v39, v39
	v_add_f32_e32 v36, 1.0, v36
	v_add_f32_e32 v37, 1.0, v37
	v_add_f32_e32 v38, 1.0, v38
	v_add_f32_e32 v39, 1.0, v39
	v_rcp_f32_e32 v36, v36
	v_rcp_f32_e32 v37, v37
	v_rcp_f32_e32 v38, v38
	v_rcp_f32_e32 v39, v39
	v_mul_f32_e32 v40, v32, v36
	v_mul_f32_e32 v41, v33, v37
	v_mul_f32_e32 v42, v34, v38
	v_mul_f32_e32 v43, v35, v39
	v_lshl_add_u64 v[36:37], s[48:49], 0, v[50:51]
	v_mov_b32_e32 v38, v136
	v_mov_b32_e32 v39, v144
	v_lshl_add_u64 v[36:37], v[38:39], 1, v[36:37]
	v_cvt_pk_bf16_f32 v240, v40, v41
	v_cvt_pk_bf16_f32 v241, v42, v43
	s_nop 1
	v_permlane16_swap_b32_e32 v238, v240
	v_permlane16_swap_b32_e32 v239, v241
	v_lshl_add_u64 v[242:243], v[36:37], 0, v[244:245]
	global_store_dwordx4 v[242:243], v[238:241], off offset:-3840

; __device__ __forceinline__ void store_bf16x4(bf16_t* p, f32x4 v) { u32x2 w; w.x = cvt_pk_bf16(v[0], v[1]); w.y = cvt_pk_bf16(v[2], v[3]); *(u32x2*)p = w; }
;   __device__ __forceinline__ void operator()(const f32x4 (&acc)[2][2][4][2], const pg8::Unit& u, int wr, int wc, int fr, int fq) const {
;     ...
;       else if (pn < 8) { store_bf16x4(VH + (size_t)row * 512 + (col - 1536), v); }
.LBB0_1912:
	s_andn2_b64 vcc, exec, s[24:25]
	s_cbranch_vccnz .LBB0_1914
	v_lshl_add_u64 v[36:37], s[16:17], 0, v[50:51]
	v_mov_b32_e32 v38, v136
	v_mov_b32_e32 v39, v144
	v_lshl_add_u64 v[36:37], v[38:39], 1, v[36:37]
	v_cvt_pk_bf16_f32 v240, v32, v33
	v_cvt_pk_bf16_f32 v241, v34, v35
	s_nop 1
	v_permlane16_swap_b32_e32 v238, v240
	v_permlane16_swap_b32_e32 v239, v241
	v_lshl_add_u64 v[242:243], v[36:37], 0, v[244:245]
	global_store_dwordx4 v[242:243], v[238:241], off offset:-2816

; __device__ __forceinline__ float siluf_(float v) { return v * sigmoidf_(v); }
; __device__ __forceinline__ void store_bf16x4(bf16_t* p, f32x4 v) { u32x2 w; w.x = cvt_pk_bf16(v[0], v[1]); w.y = cvt_pk_bf16(v[2], v[3]); *(u32x2*)p = w; }
;   __device__ __forceinline__ void operator()(const f32x4 (&acc)[2][2][4][2], const pg8::Unit& u, int wr, int wc, int fr, int fq) const {
;     ...
;       if (pn < 2) { f32x4 o; for (int j = 0; j < 4; ++j) o[j] = siluf_(v[j]); store_bf16x4(QH + (size_t)row * 512 + col, o); }
.LBB0_1919:
	v_mul_f32_e32 v56, 0xbfb8aa3b, v44
	v_exp_f32_e32 v56, v56
	s_nop 0
	v_add_f32_e32 v56, 1.0, v56
	v_rcp_f32_e32 v56, v56
	s_nop 0
	v_mul_f32_e32 v56, v44, v56
	v_mul_f32_e32 v44, 0xbfb8aa3b, v45
	v_exp_f32_e32 v44, v44
	s_nop 0
	v_add_f32_e32 v44, 1.0, v44
	v_rcp_f32_e32 v44, v44
	s_nop 0
	v_mul_f32_e32 v57, v45, v44
	v_mul_f32_e32 v44, 0xbfb8aa3b, v46
	v_exp_f32_e32 v44, v44
	s_nop 0
	v_add_f32_e32 v44, 1.0, v44
	v_rcp_f32_e32 v44, v44
	s_nop 0
	v_mul_f32_e32 v58, v46, v44
	v_mul_f32_e32 v44, 0xbfb8aa3b, v47
	v_exp_f32_e32 v44, v44
	v_cvt_pk_bf16_f32 v238, v56, v57
	s_nop 0
	v_add_f32_e32 v44, 1.0, v44
	v_rcp_f32_e32 v44, v44
	s_nop 0
	v_mul_f32_e32 v47, v47, v44
	v_lshl_add_u64 v[44:45], v[136:137], 1, v[54:55]
	v_cvt_pk_bf16_f32 v239, v58, v47
	s_and_b64 vcc, exec, s[10:11]
	s_mov_b64 s[24:25], -1
	s_cbranch_vccz .LBB0_1877

; __device__ __forceinline__ float siluf_(float v) { return v * sigmoidf_(v); }
; __device__ __forceinline__ void store_bf16x4(bf16_t* p, f32x4 v) { u32x2 w; w.x = cvt_pk_bf16(v[0], v[1]); w.y = cvt_pk_bf16(v[2], v[3]); *(u32x2*)p = w; }
;   __device__ __forceinline__ void operator()(const f32x4 (&acc)[2][2][4][2], const pg8::Unit& u, int wr, int wc, int fr, int fq) const {
;     ...
;       if (pn < 2) { f32x4 o; for (int j = 0; j < 4; ++j) o[j] = siluf_(v[j]); store_bf16x4(QH + (size_t)row * 512 + col, o); }
.LBB0_1921:
	s_nop 0
	v_mul_f32_e32 v44, 0xbfb8aa3b, v40
	v_exp_f32_e32 v44, v44
	s_nop 0
	v_add_f32_e32 v44, 1.0, v44
	v_rcp_f32_e32 v44, v44
	s_nop 0
	v_mul_f32_e32 v44, v40, v44
	v_mul_f32_e32 v40, 0xbfb8aa3b, v41
	v_exp_f32_e32 v40, v40
	s_nop 0
	v_add_f32_e32 v40, 1.0, v40
	v_rcp_f32_e32 v40, v40
	s_nop 0
	v_mul_f32_e32 v45, v41, v40
	v_mul_f32_e32 v40, 0xbfb8aa3b, v42
	v_exp_f32_e32 v40, v40
	s_nop 0
	v_add_f32_e32 v40, 1.0, v40
	v_rcp_f32_e32 v40, v40
	s_nop 0
	v_mul_f32_e32 v46, v42, v40
	v_mul_f32_e32 v40, 0xbfb8aa3b, v43
	v_exp_f32_e32 v40, v40
	v_cvt_pk_bf16_f32 v240, v44, v45
	s_nop 0
	v_add_f32_e32 v40, 1.0, v40
	v_rcp_f32_e32 v40, v40
	s_nop 0
	v_mul_f32_e32 v43, v43, v40
	v_lshl_add_u64 v[40:41], v[136:137], 1, v[54:55]
	v_cvt_pk_bf16_f32 v241, v46, v43
	s_nop 1
	v_permlane16_swap_b32_e32 v238, v240
	v_permlane16_swap_b32_e32 v239, v241
	v_lshl_add_u64 v[242:243], v[40:41], 0, v[244:245]
	global_store_dwordx4 v[242:243], v[238:241], off
	s_and_b64 vcc, exec, s[10:11]
	s_mov_b64 s[24:25], -1
	s_cbranch_vccz .LBB0_1891

; __device__ __forceinline__ float siluf_(float v) { return v * sigmoidf_(v); }
; __device__ __forceinline__ void store_bf16x4(bf16_t* p, f32x4 v) { u32x2 w; w.x = cvt_pk_bf16(v[0], v[1]); w.y = cvt_pk_bf16(v[2], v[3]); *(u32x2*)p = w; }
;   __device__ __forceinline__ void operator()(const f32x4 (&acc)[2][2][4][2], const pg8::Unit& u, int wr, int wc, int fr, int fq) const {
;     ...
;       if (pn < 2) { f32x4 o; for (int j = 0; j < 4; ++j) o[j] = siluf_(v[j]); store_bf16x4(QH + (size_t)row * 512 + col, o); }
.LBB0_1923:
	s_nop 0
	v_mul_f32_e32 v40, 0xbfb8aa3b, v36
	v_exp_f32_e32 v40, v40
	s_nop 0
	v_add_f32_e32 v40, 1.0, v40
	v_rcp_f32_e32 v40, v40
	s_nop 0
	v_mul_f32_e32 v40, v36, v40
	v_mul_f32_e32 v36, 0xbfb8aa3b, v37
	v_exp_f32_e32 v36, v36
	s_nop 0
	v_add_f32_e32 v36, 1.0, v36
	v_rcp_f32_e32 v36, v36
	s_nop 0
	v_mul_f32_e32 v41, v37, v36
	v_mul_f32_e32 v36, 0xbfb8aa3b, v38
	v_exp_f32_e32 v36, v36
	s_nop 0
	v_add_f32_e32 v36, 1.0, v36
	v_rcp_f32_e32 v36, v36
	s_nop 0
	v_mul_f32_e32 v42, v38, v36
	v_mul_f32_e32 v36, 0xbfb8aa3b, v39
	v_exp_f32_e32 v36, v36
	v_cvt_pk_bf16_f32 v238, v40, v41
	s_nop 0
	v_add_f32_e32 v36, 1.0, v36
	v_rcp_f32_e32 v36, v36
	s_nop 0
	v_mul_f32_e32 v39, v39, v36
	v_lshl_add_u64 v[36:37], v[136:137], 1, v[54:55]
	v_cvt_pk_bf16_f32 v239, v42, v39
	s_and_b64 vcc, exec, s[10:11]
	s_mov_b64 s[24:25], -1
	s_cbranch_vccz .LBB0_1905

; __device__ __forceinline__ float sigmoidf_(float v) { return __builtin_amdgcn_rcpf(1.0f + __expf(-v)); }
; __device__ __forceinline__ float siluf_(float v) { return v * sigmoidf_(v); }
; __device__ __forceinline__ void store_bf16x4(bf16_t* p, f32x4 v) { u32x2 w; w.x = cvt_pk_bf16(v[0], v[1]); w.y = cvt_pk_bf16(v[2], v[3]); *(u32x2*)p = w; }
;   __device__ __forceinline__ void operator()(const f32x4 (&acc)[2][2][4][2], const pg8::Unit& u, int wr, int wc, int fr, int fq) const {
;     const int pn = u.pn;
;     EPI_LOOP(
;       if (pn < 2) { f32x4 o; for (int j = 0; j < 4; ++j) o[j] = siluf_(v[j]); store_bf16x4(QH + (size_t)row * 512 + col, o); }
;       else if (pn < 6) { const int c = col - 512; const f32x4 lb = *(const f32x4*)(LBj + c); f32x4 o; for (int j = 0; j < 4; ++j) o[j] = lb[j] + (1.f - lb[j]) * sigmoidf_(v[j]); *(f32x4*)(F + (size_t)row * 1024 + c) = o; }
;       else if (pn < 8) { store_bf16x4(VH + (size_t)row * 512 + (col - 1536), v); }
;       else if (pn < 10) { f32x4 o; for (int j = 0; j < 4; ++j) o[j] = siluf_(v[j]); store_bf16x4(G + (size_t)row * 512 + (col - 2048), o); }
;       else { store_bf16x4(CQ + (size_t)row * 768 + (col - 2560), v); }
.LBB0_1925:
	v_mul_f32_e32 v36, 0xbfb8aa3b, v32
	v_exp_f32_e32 v36, v36
	s_nop 0
	v_add_f32_e32 v36, 1.0, v36
	v_rcp_f32_e32 v36, v36
	s_nop 0
	v_mul_f32_e32 v36, v32, v36
	v_mul_f32_e32 v32, 0xbfb8aa3b, v33
	v_exp_f32_e32 v32, v32
	s_nop 0
	v_add_f32_e32 v32, 1.0, v32
	v_rcp_f32_e32 v32, v32
	s_nop 0
	v_mul_f32_e32 v37, v33, v32
	v_mul_f32_e32 v32, 0xbfb8aa3b, v34
	v_exp_f32_e32 v32, v32
	s_nop 0
	v_add_f32_e32 v32, 1.0, v32
	v_rcp_f32_e32 v32, v32
	s_nop 0
	v_mul_f32_e32 v38, v34, v32
	v_mul_f32_e32 v32, 0xbfb8aa3b, v35
	v_exp_f32_e32 v32, v32
	v_cvt_pk_bf16_f32 v240, v36, v37
	s_nop 0
	v_add_f32_e32 v32, 1.0, v32
	v_rcp_f32_e32 v32, v32
	s_nop 0
	v_mul_f32_e32 v35, v35, v32
	v_lshl_add_u64 v[32:33], v[136:137], 1, v[54:55]
	v_cvt_pk_bf16_f32 v241, v38, v35
	s_nop 1
	v_permlane16_swap_b32_e32 v238, v240
	v_permlane16_swap_b32_e32 v239, v241
	v_lshl_add_u64 v[242:243], v[32:33], 0, v[244:245]
	global_store_dwordx4 v[242:243], v[238:241], off offset:256
.LBB0_1926:
	v_add_u32_e32 v32, 0xa0, v138
	v_ashrrev_i32_e32 v33, 31, v32
	v_mad_i64_i32 v[36:37], s[24:25], v32, s64, 0
	v_lshlrev_b64 v[34:35], 10, v[32:33]
	v_lshlrev_b64 v[32:33], 12, v[32:33]
	s_and_b64 vcc, exec, s[10:11]
	s_mov_b64 s[24:25], -1
	s_cbranch_vccnz .LBB0_1982
	s_and_b64 vcc, exec, s[8:9]
	s_cbranch_vccnz .LBB0_1937
	s_andn2_b64 vcc, exec, s[84:85]
	s_cbranch_vccnz .LBB0_1934
	s_andn2_b64 vcc, exec, s[78:79]
	s_cbranch_vccnz .LBB0_1931
	v_lshl_add_u64 v[38:39], s[46:47], 0, v[36:37]
	v_mov_b32_e32 v40, v136
	v_mov_b32_e32 v41, v144
	v_lshl_add_u64 v[38:39], v[40:41], 1, v[38:39]
	v_add_co_u32_e32 v38, vcc, 0xfffff000, v38
	s_mov_b64 s[24:25], 0
	s_nop 0
	v_addc_co_u32_e32 v39, vcc, -1, v39, vcc
	v_cvt_pk_bf16_f32 v238, v28, v29
	v_cvt_pk_bf16_f32 v239, v30, v31
.LBB0_1931:
	s_andn2_b64 vcc, exec, s[24:25]
	s_cbranch_vccnz .LBB0_1933
	v_mul_f32_e32 v38, 0xbfb8aa3b, v28
	v_mul_f32_e32 v39, 0xbfb8aa3b, v29
	v_mul_f32_e32 v40, 0xbfb8aa3b, v30
	v_mul_f32_e32 v41, 0xbfb8aa3b, v31
	v_exp_f32_e32 v38, v38
	v_exp_f32_e32 v39, v39
	v_exp_f32_e32 v40, v40
	v_exp_f32_e32 v41, v41
	v_add_f32_e32 v38, 1.0, v38
	v_add_f32_e32 v39, 1.0, v39
	v_add_f32_e32 v40, 1.0, v40
	v_add_f32_e32 v41, 1.0, v41
	v_rcp_f32_e32 v38, v38
	v_rcp_f32_e32 v39, v39
	v_rcp_f32_e32 v40, v40
	v_rcp_f32_e32 v41, v41
	v_mul_f32_e32 v42, v28, v38
	v_mul_f32_e32 v43, v29, v39
	v_mul_f32_e32 v44, v30, v40
	v_mul_f32_e32 v45, v31, v41
	v_lshl_add_u64 v[38:39], s[48:49], 0, v[34:35]
	v_mov_b32_e32 v40, v136
	v_mov_b32_e32 v41, v144
	v_lshl_add_u64 v[38:39], v[40:41], 1, v[38:39]
	v_cvt_pk_bf16_f32 v238, v42, v43
	v_cvt_pk_bf16_f32 v239, v44, v45

; __device__ __forceinline__ void store_bf16x4(bf16_t* p, f32x4 v) { u32x2 w; w.x = cvt_pk_bf16(v[0], v[1]); w.y = cvt_pk_bf16(v[2], v[3]); *(u32x2*)p = w; }
;   __device__ __forceinline__ void operator()(const f32x4 (&acc)[2][2][4][2], const pg8::Unit& u, int wr, int wc, int fr, int fq) const {
;     ...
;       else if (pn < 8) { store_bf16x4(VH + (size_t)row * 512 + (col - 1536), v); }
.LBB0_1934:
	s_andn2_b64 vcc, exec, s[24:25]
	s_cbranch_vccnz .LBB0_1936
	v_lshl_add_u64 v[38:39], s[16:17], 0, v[34:35]
	v_mov_b32_e32 v40, v136
	v_mov_b32_e32 v41, v144
	v_lshl_add_u64 v[38:39], v[40:41], 1, v[38:39]
	v_cvt_pk_bf16_f32 v238, v28, v29
	v_cvt_pk_bf16_f32 v239, v30, v31

; __device__ __forceinline__ float sigmoidf_(float v) { return __builtin_amdgcn_rcpf(1.0f + __expf(-v)); }
; __device__ __forceinline__ float siluf_(float v) { return v * sigmoidf_(v); }
; __device__ __forceinline__ void store_bf16x4(bf16_t* p, f32x4 v) { u32x2 w; w.x = cvt_pk_bf16(v[0], v[1]); w.y = cvt_pk_bf16(v[2], v[3]); *(u32x2*)p = w; }
;   __device__ __forceinline__ void operator()(const f32x4 (&acc)[2][2][4][2], const pg8::Unit& u, int wr, int wc, int fr, int fq) const {
;     const int pn = u.pn;
;     EPI_LOOP(
;       if (pn < 2) { f32x4 o; for (int j = 0; j < 4; ++j) o[j] = siluf_(v[j]); store_bf16x4(QH + (size_t)row * 512 + col, o); }
;       else if (pn < 6) { const int c = col - 512; const f32x4 lb = *(const f32x4*)(LBj + c); f32x4 o; for (int j = 0; j < 4; ++j) o[j] = lb[j] + (1.f - lb[j]) * sigmoidf_(v[j]); *(f32x4*)(F + (size_t)row * 1024 + c) = o; }
;       else if (pn < 8) { store_bf16x4(VH + (size_t)row * 512 + (col - 1536), v); }
;       else if (pn < 10) { f32x4 o; for (int j = 0; j < 4; ++j) o[j] = siluf_(v[j]); store_bf16x4(G + (size_t)row * 512 + (col - 2048), o); }
;       else { store_bf16x4(CQ + (size_t)row * 768 + (col - 2560), v); }
.LBB0_1941:
	s_and_b64 vcc, exec, s[8:9]
	s_cbranch_vccnz .LBB0_1951
	s_andn2_b64 vcc, exec, s[84:85]
	s_cbranch_vccnz .LBB0_1948
	s_andn2_b64 vcc, exec, s[78:79]
	s_cbranch_vccnz .LBB0_1945
	v_lshl_add_u64 v[28:29], s[46:47], 0, v[36:37]
	v_mov_b32_e32 v30, v136
	v_mov_b32_e32 v31, v144
	v_lshl_add_u64 v[28:29], v[30:31], 1, v[28:29]
	v_add_co_u32_e32 v28, vcc, 0xfffff000, v28
	s_mov_b64 s[24:25], 0
	s_nop 0
	v_addc_co_u32_e32 v29, vcc, -1, v29, vcc
	v_cvt_pk_bf16_f32 v240, v24, v25
	v_cvt_pk_bf16_f32 v241, v26, v27
	s_nop 1
	v_permlane16_swap_b32_e32 v238, v240
	v_permlane16_swap_b32_e32 v239, v241
	v_lshl_add_u64 v[242:243], v[28:29], 0, v[244:245]
	global_store_dwordx4 v[242:243], v[238:241], off offset:-1024
.LBB0_1945:
	s_andn2_b64 vcc, exec, s[24:25]
	s_cbranch_vccnz .LBB0_1947
	v_mul_f32_e32 v28, 0xbfb8aa3b, v24
	v_mul_f32_e32 v29, 0xbfb8aa3b, v25
	v_mul_f32_e32 v30, 0xbfb8aa3b, v26
	v_mul_f32_e32 v31, 0xbfb8aa3b, v27
	v_exp_f32_e32 v28, v28
	v_exp_f32_e32 v29, v29
	v_exp_f32_e32 v30, v30
	v_exp_f32_e32 v31, v31
	v_add_f32_e32 v28, 1.0, v28
	v_add_f32_e32 v29, 1.0, v29
	v_add_f32_e32 v30, 1.0, v30
	v_add_f32_e32 v31, 1.0, v31
	v_rcp_f32_e32 v28, v28
	v_rcp_f32_e32 v29, v29
	v_rcp_f32_e32 v30, v30
	v_rcp_f32_e32 v31, v31
	v_mul_f32_e32 v40, v24, v28
	v_mul_f32_e32 v41, v25, v29
	v_mul_f32_e32 v42, v26, v30
	v_mul_f32_e32 v43, v27, v31
	v_lshl_add_u64 v[28:29], s[48:49], 0, v[34:35]
	v_mov_b32_e32 v30, v136
	v_mov_b32_e32 v31, v144
	v_lshl_add_u64 v[28:29], v[30:31], 1, v[28:29]
	v_cvt_pk_bf16_f32 v240, v40, v41
	v_cvt_pk_bf16_f32 v241, v42, v43
	s_nop 1
	v_permlane16_swap_b32_e32 v238, v240
	v_permlane16_swap_b32_e32 v239, v241
	v_lshl_add_u64 v[242:243], v[28:29], 0, v[244:245]
	global_store_dwordx4 v[242:243], v[238:241], off offset:-4096

; __device__ __forceinline__ void store_bf16x4(bf16_t* p, f32x4 v) { u32x2 w; w.x = cvt_pk_bf16(v[0], v[1]); w.y = cvt_pk_bf16(v[2], v[3]); *(u32x2*)p = w; }
;   __device__ __forceinline__ void operator()(const f32x4 (&acc)[2][2][4][2], const pg8::Unit& u, int wr, int wc, int fr, int fq) const {
;     ...
;       else if (pn < 8) { store_bf16x4(VH + (size_t)row * 512 + (col - 1536), v); }
.LBB0_1948:
	s_andn2_b64 vcc, exec, s[24:25]
	s_cbranch_vccnz .LBB0_1950
	v_lshl_add_u64 v[28:29], s[16:17], 0, v[34:35]
	v_mov_b32_e32 v30, v136
	v_mov_b32_e32 v31, v144
	v_lshl_add_u64 v[28:29], v[30:31], 1, v[28:29]
	v_cvt_pk_bf16_f32 v240, v24, v25
	v_cvt_pk_bf16_f32 v241, v26, v27
	s_nop 1
	v_permlane16_swap_b32_e32 v238, v240
	v_permlane16_swap_b32_e32 v239, v241
	v_lshl_add_u64 v[242:243], v[28:29], 0, v[244:245]
	global_store_dwordx4 v[242:243], v[238:241], off offset:-3072

; __device__ __forceinline__ float sigmoidf_(float v) { return __builtin_amdgcn_rcpf(1.0f + __expf(-v)); }
; __device__ __forceinline__ float siluf_(float v) { return v * sigmoidf_(v); }
; __device__ __forceinline__ void store_bf16x4(bf16_t* p, f32x4 v) { u32x2 w; w.x = cvt_pk_bf16(v[0], v[1]); w.y = cvt_pk_bf16(v[2], v[3]); *(u32x2*)p = w; }
;   __device__ __forceinline__ void operator()(const f32x4 (&acc)[2][2][4][2], const pg8::Unit& u, int wr, int wc, int fr, int fq) const {
;     const int pn = u.pn;
;     EPI_LOOP(
;       if (pn < 2) { f32x4 o; for (int j = 0; j < 4; ++j) o[j] = siluf_(v[j]); store_bf16x4(QH + (size_t)row * 512 + col, o); }
;       else if (pn < 6) { const int c = col - 512; const f32x4 lb = *(const f32x4*)(LBj + c); f32x4 o; for (int j = 0; j < 4; ++j) o[j] = lb[j] + (1.f - lb[j]) * sigmoidf_(v[j]); *(f32x4*)(F + (size_t)row * 1024 + c) = o; }
;       else if (pn < 8) { store_bf16x4(VH + (size_t)row * 512 + (col - 1536), v); }
;       else if (pn < 10) { f32x4 o; for (int j = 0; j < 4; ++j) o[j] = siluf_(v[j]); store_bf16x4(G + (size_t)row * 512 + (col - 2048), o); }
;       else { store_bf16x4(CQ + (size_t)row * 768 + (col - 2560), v); }
.LBB0_1955:
	s_and_b64 vcc, exec, s[8:9]
	s_cbranch_vccnz .LBB0_1965
	s_andn2_b64 vcc, exec, s[84:85]
	s_cbranch_vccnz .LBB0_1962
	s_andn2_b64 vcc, exec, s[78:79]
	s_cbranch_vccnz .LBB0_1959
	v_lshl_add_u64 v[24:25], s[46:47], 0, v[36:37]
	v_mov_b32_e32 v26, v136
	v_mov_b32_e32 v27, v144
	v_lshl_add_u64 v[24:25], v[26:27], 1, v[24:25]
	v_add_co_u32_e32 v24, vcc, 0xfffff000, v24
	s_mov_b64 s[24:25], 0
	s_nop 0
	v_addc_co_u32_e32 v25, vcc, -1, v25, vcc
	v_cvt_pk_bf16_f32 v238, v20, v21
	v_cvt_pk_bf16_f32 v239, v22, v23
.LBB0_1959:
	s_andn2_b64 vcc, exec, s[24:25]
	s_cbranch_vccnz .LBB0_1961
	v_mul_f32_e32 v24, 0xbfb8aa3b, v20
	v_mul_f32_e32 v25, 0xbfb8aa3b, v21
	v_mul_f32_e32 v26, 0xbfb8aa3b, v22
	v_mul_f32_e32 v27, 0xbfb8aa3b, v23
	v_exp_f32_e32 v24, v24
	v_exp_f32_e32 v25, v25
	v_exp_f32_e32 v26, v26
	v_exp_f32_e32 v27, v27
	v_add_f32_e32 v24, 1.0, v24
	v_add_f32_e32 v25, 1.0, v25
	v_add_f32_e32 v26, 1.0, v26
	v_add_f32_e32 v27, 1.0, v27
	v_rcp_f32_e32 v24, v24
	v_rcp_f32_e32 v25, v25
	v_rcp_f32_e32 v26, v26
	v_rcp_f32_e32 v27, v27
	v_mul_f32_e32 v28, v20, v24
	v_mul_f32_e32 v29, v21, v25
	v_mul_f32_e32 v30, v22, v26
	v_mul_f32_e32 v31, v23, v27
	v_lshl_add_u64 v[24:25], s[48:49], 0, v[34:35]
	v_mov_b32_e32 v26, v136
	v_mov_b32_e32 v27, v144
	v_lshl_add_u64 v[24:25], v[26:27], 1, v[24:25]
	v_cvt_pk_bf16_f32 v238, v28, v29
	v_cvt_pk_bf16_f32 v239, v30, v31

; __device__ __forceinline__ void store_bf16x4(bf16_t* p, f32x4 v) { u32x2 w; w.x = cvt_pk_bf16(v[0], v[1]); w.y = cvt_pk_bf16(v[2], v[3]); *(u32x2*)p = w; }
;   __device__ __forceinline__ void operator()(const f32x4 (&acc)[2][2][4][2], const pg8::Unit& u, int wr, int wc, int fr, int fq) const {
;     ...
;       else if (pn < 8) { store_bf16x4(VH + (size_t)row * 512 + (col - 1536), v); }
.LBB0_1962:
	s_andn2_b64 vcc, exec, s[24:25]
	s_cbranch_vccnz .LBB0_1964
	v_lshl_add_u64 v[24:25], s[16:17], 0, v[34:35]
	v_mov_b32_e32 v26, v136
	v_mov_b32_e32 v27, v144
	v_lshl_add_u64 v[24:25], v[26:27], 1, v[24:25]
	v_cvt_pk_bf16_f32 v238, v20, v21
	v_cvt_pk_bf16_f32 v239, v22, v23

; __device__ __forceinline__ float sigmoidf_(float v) { return __builtin_amdgcn_rcpf(1.0f + __expf(-v)); }
; __device__ __forceinline__ float siluf_(float v) { return v * sigmoidf_(v); }
; __device__ __forceinline__ void store_bf16x4(bf16_t* p, f32x4 v) { u32x2 w; w.x = cvt_pk_bf16(v[0], v[1]); w.y = cvt_pk_bf16(v[2], v[3]); *(u32x2*)p = w; }
;   __device__ __forceinline__ void operator()(const f32x4 (&acc)[2][2][4][2], const pg8::Unit& u, int wr, int wc, int fr, int fq) const {
;     const int pn = u.pn;
;     EPI_LOOP(
;       if (pn < 2) { f32x4 o; for (int j = 0; j < 4; ++j) o[j] = siluf_(v[j]); store_bf16x4(QH + (size_t)row * 512 + col, o); }
;       else if (pn < 6) { const int c = col - 512; const f32x4 lb = *(const f32x4*)(LBj + c); f32x4 o; for (int j = 0; j < 4; ++j) o[j] = lb[j] + (1.f - lb[j]) * sigmoidf_(v[j]); *(f32x4*)(F + (size_t)row * 1024 + c) = o; }
;       else if (pn < 8) { store_bf16x4(VH + (size_t)row * 512 + (col - 1536), v); }
;       else if (pn < 10) { f32x4 o; for (int j = 0; j < 4; ++j) o[j] = siluf_(v[j]); store_bf16x4(G + (size_t)row * 512 + (col - 2048), o); }
;       else { store_bf16x4(CQ + (size_t)row * 768 + (col - 2560), v); }
.LBB0_1969:
	s_and_b64 vcc, exec, s[8:9]
	s_cbranch_vccnz .LBB0_1979
	s_andn2_b64 vcc, exec, s[84:85]
	s_cbranch_vccnz .LBB0_1976
	s_andn2_b64 vcc, exec, s[78:79]
	s_cbranch_vccnz .LBB0_1973
	v_lshl_add_u64 v[20:21], s[46:47], 0, v[36:37]
	v_mov_b32_e32 v22, v136
	v_mov_b32_e32 v23, v144
	v_lshl_add_u64 v[20:21], v[22:23], 1, v[20:21]
	v_add_co_u32_e32 v20, vcc, 0xfffff000, v20
	s_mov_b64 s[24:25], 0
	s_nop 0
	v_addc_co_u32_e32 v21, vcc, -1, v21, vcc
	v_cvt_pk_bf16_f32 v240, v16, v17
	v_cvt_pk_bf16_f32 v241, v18, v19
	s_nop 1
	v_permlane16_swap_b32_e32 v238, v240
	v_permlane16_swap_b32_e32 v239, v241
	v_lshl_add_u64 v[242:243], v[20:21], 0, v[244:245]
	global_store_dwordx4 v[242:243], v[238:241], off offset:-768
.LBB0_1973:
	s_andn2_b64 vcc, exec, s[24:25]
	s_cbranch_vccnz .LBB0_1975
	v_mul_f32_e32 v20, 0xbfb8aa3b, v16
	v_mul_f32_e32 v21, 0xbfb8aa3b, v17
	v_mul_f32_e32 v22, 0xbfb8aa3b, v18
	v_mul_f32_e32 v23, 0xbfb8aa3b, v19
	v_exp_f32_e32 v20, v20
	v_exp_f32_e32 v21, v21
	v_exp_f32_e32 v22, v22
	v_exp_f32_e32 v23, v23
	v_add_f32_e32 v20, 1.0, v20
	v_add_f32_e32 v21, 1.0, v21
	v_add_f32_e32 v22, 1.0, v22
	v_add_f32_e32 v23, 1.0, v23
	v_rcp_f32_e32 v20, v20
	v_rcp_f32_e32 v21, v21
	v_rcp_f32_e32 v22, v22
	v_rcp_f32_e32 v23, v23
	v_mul_f32_e32 v24, v16, v20
	v_mul_f32_e32 v25, v17, v21
	v_mul_f32_e32 v26, v18, v22
	v_mul_f32_e32 v27, v19, v23
	v_lshl_add_u64 v[20:21], s[48:49], 0, v[34:35]
	v_mov_b32_e32 v22, v136
	v_mov_b32_e32 v23, v144
	v_lshl_add_u64 v[20:21], v[22:23], 1, v[20:21]
	v_cvt_pk_bf16_f32 v240, v24, v25
	v_cvt_pk_bf16_f32 v241, v26, v27
	s_nop 1
	v_permlane16_swap_b32_e32 v238, v240
	v_permlane16_swap_b32_e32 v239, v241
	v_lshl_add_u64 v[242:243], v[20:21], 0, v[244:245]
	global_store_dwordx4 v[242:243], v[238:241], off offset:-3840

; __device__ __forceinline__ void store_bf16x4(bf16_t* p, f32x4 v) { u32x2 w; w.x = cvt_pk_bf16(v[0], v[1]); w.y = cvt_pk_bf16(v[2], v[3]); *(u32x2*)p = w; }
;   __device__ __forceinline__ void operator()(const f32x4 (&acc)[2][2][4][2], const pg8::Unit& u, int wr, int wc, int fr, int fq) const {
;     ...
;       else if (pn < 8) { store_bf16x4(VH + (size_t)row * 512 + (col - 1536), v); }
.LBB0_1976:
	s_andn2_b64 vcc, exec, s[24:25]
	s_cbranch_vccnz .LBB0_1978
	v_lshl_add_u64 v[20:21], s[16:17], 0, v[34:35]
	v_mov_b32_e32 v22, v136
	v_mov_b32_e32 v23, v144
	v_lshl_add_u64 v[20:21], v[22:23], 1, v[20:21]
	v_cvt_pk_bf16_f32 v240, v16, v17
	v_cvt_pk_bf16_f32 v241, v18, v19
	s_nop 1
	v_permlane16_swap_b32_e32 v238, v240
	v_permlane16_swap_b32_e32 v239, v241
	v_lshl_add_u64 v[242:243], v[20:21], 0, v[244:245]
	global_store_dwordx4 v[242:243], v[238:241], off offset:-2816

; __device__ __forceinline__ float siluf_(float v) { return v * sigmoidf_(v); }
; __device__ __forceinline__ void store_bf16x4(bf16_t* p, f32x4 v) { u32x2 w; w.x = cvt_pk_bf16(v[0], v[1]); w.y = cvt_pk_bf16(v[2], v[3]); *(u32x2*)p = w; }
;   __device__ __forceinline__ void operator()(const f32x4 (&acc)[2][2][4][2], const pg8::Unit& u, int wr, int wc, int fr, int fq) const {
;     ...
;       if (pn < 2) { f32x4 o; for (int j = 0; j < 4; ++j) o[j] = siluf_(v[j]); store_bf16x4(QH + (size_t)row * 512 + col, o); }
.LBB0_1983:
	v_mul_f32_e32 v40, 0xbfb8aa3b, v28
	v_exp_f32_e32 v40, v40
	s_nop 0
	v_add_f32_e32 v40, 1.0, v40
	v_rcp_f32_e32 v40, v40
	s_nop 0
	v_mul_f32_e32 v40, v28, v40
	v_mul_f32_e32 v28, 0xbfb8aa3b, v29
	v_exp_f32_e32 v28, v28
	s_nop 0
	v_add_f32_e32 v28, 1.0, v28
	v_rcp_f32_e32 v28, v28
	s_nop 0
	v_mul_f32_e32 v41, v29, v28
	v_mul_f32_e32 v28, 0xbfb8aa3b, v30
	v_exp_f32_e32 v28, v28
	s_nop 0
	v_add_f32_e32 v28, 1.0, v28
	v_rcp_f32_e32 v28, v28
	s_nop 0
	v_mul_f32_e32 v42, v30, v28
	v_mul_f32_e32 v28, 0xbfb8aa3b, v31
	v_exp_f32_e32 v28, v28
	v_cvt_pk_bf16_f32 v238, v40, v41
	s_nop 0
	v_add_f32_e32 v28, 1.0, v28
	v_rcp_f32_e32 v28, v28
	s_nop 0
	v_mul_f32_e32 v31, v31, v28
	v_lshl_add_u64 v[28:29], v[136:137], 1, v[38:39]
	v_cvt_pk_bf16_f32 v239, v42, v31
	s_and_b64 vcc, exec, s[10:11]
	s_mov_b64 s[24:25], -1
	s_cbranch_vccz .LBB0_1941

; __device__ __forceinline__ float siluf_(float v) { return v * sigmoidf_(v); }
; __device__ __forceinline__ void store_bf16x4(bf16_t* p, f32x4 v) { u32x2 w; w.x = cvt_pk_bf16(v[0], v[1]); w.y = cvt_pk_bf16(v[2], v[3]); *(u32x2*)p = w; }
;   __device__ __forceinline__ void operator()(const f32x4 (&acc)[2][2][4][2], const pg8::Unit& u, int wr, int wc, int fr, int fq) const {
;     ...
;       if (pn < 2) { f32x4 o; for (int j = 0; j < 4; ++j) o[j] = siluf_(v[j]); store_bf16x4(QH + (size_t)row * 512 + col, o); }
.LBB0_1985:
	s_nop 0
	v_mul_f32_e32 v28, 0xbfb8aa3b, v24
	v_exp_f32_e32 v28, v28
	s_nop 0
	v_add_f32_e32 v28, 1.0, v28
	v_rcp_f32_e32 v28, v28
	s_nop 0
	v_mul_f32_e32 v28, v24, v28
	v_mul_f32_e32 v24, 0xbfb8aa3b, v25
	v_exp_f32_e32 v24, v24
	s_nop 0
	v_add_f32_e32 v24, 1.0, v24
	v_rcp_f32_e32 v24, v24
	s_nop 0
	v_mul_f32_e32 v29, v25, v24
	v_mul_f32_e32 v24, 0xbfb8aa3b, v26
	v_exp_f32_e32 v24, v24
	s_nop 0
	v_add_f32_e32 v24, 1.0, v24
	v_rcp_f32_e32 v24, v24
	s_nop 0
	v_mul_f32_e32 v30, v26, v24
	v_mul_f32_e32 v24, 0xbfb8aa3b, v27
	v_exp_f32_e32 v24, v24
	v_cvt_pk_bf16_f32 v240, v28, v29
	s_nop 0
	v_add_f32_e32 v24, 1.0, v24
	v_rcp_f32_e32 v24, v24
	s_nop 0
	v_mul_f32_e32 v27, v27, v24
	v_lshl_add_u64 v[24:25], v[136:137], 1, v[38:39]
	v_cvt_pk_bf16_f32 v241, v30, v27
	s_nop 1
	v_permlane16_swap_b32_e32 v238, v240
	v_permlane16_swap_b32_e32 v239, v241
	v_lshl_add_u64 v[242:243], v[24:25], 0, v[244:245]
	global_store_dwordx4 v[242:243], v[238:241], off
	s_and_b64 vcc, exec, s[10:11]
	s_mov_b64 s[24:25], -1
	s_cbranch_vccz .LBB0_1955

; __device__ __forceinline__ float siluf_(float v) { return v * sigmoidf_(v); }
; __device__ __forceinline__ void store_bf16x4(bf16_t* p, f32x4 v) { u32x2 w; w.x = cvt_pk_bf16(v[0], v[1]); w.y = cvt_pk_bf16(v[2], v[3]); *(u32x2*)p = w; }
;   __device__ __forceinline__ void operator()(const f32x4 (&acc)[2][2][4][2], const pg8::Unit& u, int wr, int wc, int fr, int fq) const {
;     ...
;       if (pn < 2) { f32x4 o; for (int j = 0; j < 4; ++j) o[j] = siluf_(v[j]); store_bf16x4(QH + (size_t)row * 512 + col, o); }
.LBB0_1987:
	s_nop 0
	v_mul_f32_e32 v24, 0xbfb8aa3b, v20
	v_exp_f32_e32 v24, v24
	s_nop 0
	v_add_f32_e32 v24, 1.0, v24
	v_rcp_f32_e32 v24, v24
	s_nop 0
	v_mul_f32_e32 v24, v20, v24
	v_mul_f32_e32 v20, 0xbfb8aa3b, v21
	v_exp_f32_e32 v20, v20
	s_nop 0
	v_add_f32_e32 v20, 1.0, v20
	v_rcp_f32_e32 v20, v20
	s_nop 0
	v_mul_f32_e32 v25, v21, v20
	v_mul_f32_e32 v20, 0xbfb8aa3b, v22
	v_exp_f32_e32 v20, v20
	s_nop 0
	v_add_f32_e32 v20, 1.0, v20
	v_rcp_f32_e32 v20, v20
	s_nop 0
	v_mul_f32_e32 v26, v22, v20
	v_mul_f32_e32 v20, 0xbfb8aa3b, v23
	v_exp_f32_e32 v20, v20
	v_cvt_pk_bf16_f32 v238, v24, v25
	s_nop 0
	v_add_f32_e32 v20, 1.0, v20
	v_rcp_f32_e32 v20, v20
	s_nop 0
	v_mul_f32_e32 v23, v23, v20
	v_lshl_add_u64 v[20:21], v[136:137], 1, v[38:39]
	v_cvt_pk_bf16_f32 v239, v26, v23
	s_and_b64 vcc, exec, s[10:11]
	s_mov_b64 s[24:25], -1
	s_cbranch_vccz .LBB0_1969

; __device__ __forceinline__ float sigmoidf_(float v) { return __builtin_amdgcn_rcpf(1.0f + __expf(-v)); }
; __device__ __forceinline__ float siluf_(float v) { return v * sigmoidf_(v); }
; __device__ __forceinline__ void store_bf16x4(bf16_t* p, f32x4 v) { u32x2 w; w.x = cvt_pk_bf16(v[0], v[1]); w.y = cvt_pk_bf16(v[2], v[3]); *(u32x2*)p = w; }
;   __device__ __forceinline__ void operator()(const f32x4 (&acc)[2][2][4][2], const pg8::Unit& u, int wr, int wc, int fr, int fq) const {
;     const int pn = u.pn;
;     EPI_LOOP(
;       if (pn < 2) { f32x4 o; for (int j = 0; j < 4; ++j) o[j] = siluf_(v[j]); store_bf16x4(QH + (size_t)row * 512 + col, o); }
;       else if (pn < 6) { const int c = col - 512; const f32x4 lb = *(const f32x4*)(LBj + c); f32x4 o; for (int j = 0; j < 4; ++j) o[j] = lb[j] + (1.f - lb[j]) * sigmoidf_(v[j]); *(f32x4*)(F + (size_t)row * 1024 + c) = o; }
;       else if (pn < 8) { store_bf16x4(VH + (size_t)row * 512 + (col - 1536), v); }
;       else if (pn < 10) { f32x4 o; for (int j = 0; j < 4; ++j) o[j] = siluf_(v[j]); store_bf16x4(G + (size_t)row * 512 + (col - 2048), o); }
;       else { store_bf16x4(CQ + (size_t)row * 768 + (col - 2560), v); }
.LBB0_1989:
	v_mul_f32_e32 v20, 0xbfb8aa3b, v16
	v_exp_f32_e32 v20, v20
	s_nop 0
	v_add_f32_e32 v20, 1.0, v20
	v_rcp_f32_e32 v20, v20
	s_nop 0
	v_mul_f32_e32 v20, v16, v20
	v_mul_f32_e32 v16, 0xbfb8aa3b, v17
	v_exp_f32_e32 v16, v16
	s_nop 0
	v_add_f32_e32 v16, 1.0, v16
	v_rcp_f32_e32 v16, v16
	s_nop 0
	v_mul_f32_e32 v21, v17, v16
	v_mul_f32_e32 v16, 0xbfb8aa3b, v18
	v_exp_f32_e32 v16, v16
	s_nop 0
	v_add_f32_e32 v16, 1.0, v16
	v_rcp_f32_e32 v16, v16
	s_nop 0
	v_mul_f32_e32 v22, v18, v16
	v_mul_f32_e32 v16, 0xbfb8aa3b, v19
	v_exp_f32_e32 v16, v16
	v_cvt_pk_bf16_f32 v240, v20, v21
	s_nop 0
	v_add_f32_e32 v16, 1.0, v16
	v_rcp_f32_e32 v16, v16
	s_nop 0
	v_mul_f32_e32 v19, v19, v16
	v_lshl_add_u64 v[16:17], v[136:137], 1, v[38:39]
	v_cvt_pk_bf16_f32 v241, v22, v19
	s_nop 1
	v_permlane16_swap_b32_e32 v238, v240
	v_permlane16_swap_b32_e32 v239, v241
	v_lshl_add_u64 v[242:243], v[16:17], 0, v[244:245]
	global_store_dwordx4 v[242:243], v[238:241], off offset:256
.LBB0_1990:
	v_add_u32_e32 v16, 0xb0, v138
	v_ashrrev_i32_e32 v17, 31, v16
	v_mad_i64_i32 v[20:21], s[24:25], v16, s64, 0
	v_lshlrev_b64 v[18:19], 10, v[16:17]
	v_lshlrev_b64 v[16:17], 12, v[16:17]
	s_and_b64 vcc, exec, s[10:11]
	s_mov_b64 s[24:25], -1
	s_cbranch_vccnz .LBB0_2046
	s_and_b64 vcc, exec, s[8:9]
	s_cbranch_vccnz .LBB0_2001
	s_andn2_b64 vcc, exec, s[84:85]
	s_cbranch_vccnz .LBB0_1998
	s_andn2_b64 vcc, exec, s[78:79]
	s_cbranch_vccnz .LBB0_1995
	v_lshl_add_u64 v[22:23], s[46:47], 0, v[20:21]
	v_mov_b32_e32 v24, v136
	v_mov_b32_e32 v25, v144
	v_lshl_add_u64 v[22:23], v[24:25], 1, v[22:23]
	v_add_co_u32_e32 v22, vcc, 0xfffff000, v22
	s_mov_b64 s[24:25], 0
	s_nop 0
	v_addc_co_u32_e32 v23, vcc, -1, v23, vcc
	v_cvt_pk_bf16_f32 v238, v12, v13
	v_cvt_pk_bf16_f32 v239, v14, v15
.LBB0_1995:
	s_andn2_b64 vcc, exec, s[24:25]
	s_cbranch_vccnz .LBB0_1997
	v_mul_f32_e32 v22, 0xbfb8aa3b, v12
	v_mul_f32_e32 v23, 0xbfb8aa3b, v13
	v_mul_f32_e32 v24, 0xbfb8aa3b, v14
	v_mul_f32_e32 v25, 0xbfb8aa3b, v15
	v_exp_f32_e32 v22, v22
	v_exp_f32_e32 v23, v23
	v_exp_f32_e32 v24, v24
	v_exp_f32_e32 v25, v25
	v_add_f32_e32 v22, 1.0, v22
	v_add_f32_e32 v23, 1.0, v23
	v_add_f32_e32 v24, 1.0, v24
	v_add_f32_e32 v25, 1.0, v25
	v_rcp_f32_e32 v22, v22
	v_rcp_f32_e32 v23, v23
	v_rcp_f32_e32 v24, v24
	v_rcp_f32_e32 v25, v25
	v_mul_f32_e32 v26, v12, v22
	v_mul_f32_e32 v27, v13, v23
	v_mul_f32_e32 v28, v14, v24
	v_mul_f32_e32 v29, v15, v25
	v_lshl_add_u64 v[22:23], s[48:49], 0, v[18:19]
	v_mov_b32_e32 v24, v136
	v_mov_b32_e32 v25, v144
	v_lshl_add_u64 v[22:23], v[24:25], 1, v[22:23]
	v_cvt_pk_bf16_f32 v238, v26, v27
	v_cvt_pk_bf16_f32 v239, v28, v29

; __device__ __forceinline__ void store_bf16x4(bf16_t* p, f32x4 v) { u32x2 w; w.x = cvt_pk_bf16(v[0], v[1]); w.y = cvt_pk_bf16(v[2], v[3]); *(u32x2*)p = w; }
;   __device__ __forceinline__ void operator()(const f32x4 (&acc)[2][2][4][2], const pg8::Unit& u, int wr, int wc, int fr, int fq) const {
;     ...
;       else if (pn < 8) { store_bf16x4(VH + (size_t)row * 512 + (col - 1536), v); }
.LBB0_1998:
	s_andn2_b64 vcc, exec, s[24:25]
	s_cbranch_vccnz .LBB0_2000
	v_lshl_add_u64 v[22:23], s[16:17], 0, v[18:19]
	v_mov_b32_e32 v24, v136
	v_mov_b32_e32 v25, v144
	v_lshl_add_u64 v[22:23], v[24:25], 1, v[22:23]
	v_cvt_pk_bf16_f32 v238, v12, v13
	v_cvt_pk_bf16_f32 v239, v14, v15

; __device__ __forceinline__ float sigmoidf_(float v) { return __builtin_amdgcn_rcpf(1.0f + __expf(-v)); }
; __device__ __forceinline__ float siluf_(float v) { return v * sigmoidf_(v); }
; __device__ __forceinline__ void store_bf16x4(bf16_t* p, f32x4 v) { u32x2 w; w.x = cvt_pk_bf16(v[0], v[1]); w.y = cvt_pk_bf16(v[2], v[3]); *(u32x2*)p = w; }
;   __device__ __forceinline__ void operator()(const f32x4 (&acc)[2][2][4][2], const pg8::Unit& u, int wr, int wc, int fr, int fq) const {
;     const int pn = u.pn;
;     EPI_LOOP(
;       if (pn < 2) { f32x4 o; for (int j = 0; j < 4; ++j) o[j] = siluf_(v[j]); store_bf16x4(QH + (size_t)row * 512 + col, o); }
;       else if (pn < 6) { const int c = col - 512; const f32x4 lb = *(const f32x4*)(LBj + c); f32x4 o; for (int j = 0; j < 4; ++j) o[j] = lb[j] + (1.f - lb[j]) * sigmoidf_(v[j]); *(f32x4*)(F + (size_t)row * 1024 + c) = o; }
;       else if (pn < 8) { store_bf16x4(VH + (size_t)row * 512 + (col - 1536), v); }
;       else if (pn < 10) { f32x4 o; for (int j = 0; j < 4; ++j) o[j] = siluf_(v[j]); store_bf16x4(G + (size_t)row * 512 + (col - 2048), o); }
;       else { store_bf16x4(CQ + (size_t)row * 768 + (col - 2560), v); }
.LBB0_2005:
	s_and_b64 vcc, exec, s[8:9]
	s_cbranch_vccnz .LBB0_2015
	s_andn2_b64 vcc, exec, s[84:85]
	s_cbranch_vccnz .LBB0_2012
	s_andn2_b64 vcc, exec, s[78:79]
	s_cbranch_vccnz .LBB0_2009
	v_lshl_add_u64 v[12:13], s[46:47], 0, v[20:21]
	v_mov_b32_e32 v14, v136
	v_mov_b32_e32 v15, v144
	v_lshl_add_u64 v[12:13], v[14:15], 1, v[12:13]
	v_add_co_u32_e32 v12, vcc, 0xfffff000, v12
	s_mov_b64 s[24:25], 0
	s_nop 0
	v_addc_co_u32_e32 v13, vcc, -1, v13, vcc
	v_cvt_pk_bf16_f32 v240, v8, v9
	v_cvt_pk_bf16_f32 v241, v10, v11
	s_nop 1
	v_permlane16_swap_b32_e32 v238, v240
	v_permlane16_swap_b32_e32 v239, v241
	v_lshl_add_u64 v[242:243], v[12:13], 0, v[244:245]
	global_store_dwordx4 v[242:243], v[238:241], off offset:-1024
.LBB0_2009:
	s_andn2_b64 vcc, exec, s[24:25]
	s_cbranch_vccnz .LBB0_2011
	v_mul_f32_e32 v12, 0xbfb8aa3b, v8
	v_mul_f32_e32 v13, 0xbfb8aa3b, v9
	v_mul_f32_e32 v14, 0xbfb8aa3b, v10
	v_mul_f32_e32 v15, 0xbfb8aa3b, v11
	v_exp_f32_e32 v12, v12
	v_exp_f32_e32 v13, v13
	v_exp_f32_e32 v14, v14
	v_exp_f32_e32 v15, v15
	v_add_f32_e32 v12, 1.0, v12
	v_add_f32_e32 v13, 1.0, v13
	v_add_f32_e32 v14, 1.0, v14
	v_add_f32_e32 v15, 1.0, v15
	v_rcp_f32_e32 v12, v12
	v_rcp_f32_e32 v13, v13
	v_rcp_f32_e32 v14, v14
	v_rcp_f32_e32 v15, v15
	v_mul_f32_e32 v24, v8, v12
	v_mul_f32_e32 v25, v9, v13
	v_mul_f32_e32 v26, v10, v14
	v_mul_f32_e32 v27, v11, v15
	v_lshl_add_u64 v[12:13], s[48:49], 0, v[18:19]
	v_mov_b32_e32 v14, v136
	v_mov_b32_e32 v15, v144
	v_lshl_add_u64 v[12:13], v[14:15], 1, v[12:13]
	v_cvt_pk_bf16_f32 v240, v24, v25
	v_cvt_pk_bf16_f32 v241, v26, v27
	s_nop 1
	v_permlane16_swap_b32_e32 v238, v240
	v_permlane16_swap_b32_e32 v239, v241
	v_lshl_add_u64 v[242:243], v[12:13], 0, v[244:245]
	global_store_dwordx4 v[242:243], v[238:241], off offset:-4096

; __device__ __forceinline__ void store_bf16x4(bf16_t* p, f32x4 v) { u32x2 w; w.x = cvt_pk_bf16(v[0], v[1]); w.y = cvt_pk_bf16(v[2], v[3]); *(u32x2*)p = w; }
;   __device__ __forceinline__ void operator()(const f32x4 (&acc)[2][2][4][2], const pg8::Unit& u, int wr, int wc, int fr, int fq) const {
;     ...
;       else if (pn < 8) { store_bf16x4(VH + (size_t)row * 512 + (col - 1536), v); }
.LBB0_2012:
	s_andn2_b64 vcc, exec, s[24:25]
	s_cbranch_vccnz .LBB0_2014
	v_lshl_add_u64 v[12:13], s[16:17], 0, v[18:19]
	v_mov_b32_e32 v14, v136
	v_mov_b32_e32 v15, v144
	v_lshl_add_u64 v[12:13], v[14:15], 1, v[12:13]
	v_cvt_pk_bf16_f32 v240, v8, v9
	v_cvt_pk_bf16_f32 v241, v10, v11
	s_nop 1
	v_permlane16_swap_b32_e32 v238, v240
	v_permlane16_swap_b32_e32 v239, v241
	v_lshl_add_u64 v[242:243], v[12:13], 0, v[244:245]
	global_store_dwordx4 v[242:243], v[238:241], off offset:-3072

; __device__ __forceinline__ float sigmoidf_(float v) { return __builtin_amdgcn_rcpf(1.0f + __expf(-v)); }
; __device__ __forceinline__ float siluf_(float v) { return v * sigmoidf_(v); }
; __device__ __forceinline__ void store_bf16x4(bf16_t* p, f32x4 v) { u32x2 w; w.x = cvt_pk_bf16(v[0], v[1]); w.y = cvt_pk_bf16(v[2], v[3]); *(u32x2*)p = w; }
;   __device__ __forceinline__ void operator()(const f32x4 (&acc)[2][2][4][2], const pg8::Unit& u, int wr, int wc, int fr, int fq) const {
;     const int pn = u.pn;
;     EPI_LOOP(
;       if (pn < 2) { f32x4 o; for (int j = 0; j < 4; ++j) o[j] = siluf_(v[j]); store_bf16x4(QH + (size_t)row * 512 + col, o); }
;       else if (pn < 6) { const int c = col - 512; const f32x4 lb = *(const f32x4*)(LBj + c); f32x4 o; for (int j = 0; j < 4; ++j) o[j] = lb[j] + (1.f - lb[j]) * sigmoidf_(v[j]); *(f32x4*)(F + (size_t)row * 1024 + c) = o; }
;       else if (pn < 8) { store_bf16x4(VH + (size_t)row * 512 + (col - 1536), v); }
;       else if (pn < 10) { f32x4 o; for (int j = 0; j < 4; ++j) o[j] = siluf_(v[j]); store_bf16x4(G + (size_t)row * 512 + (col - 2048), o); }
;       else { store_bf16x4(CQ + (size_t)row * 768 + (col - 2560), v); }
.LBB0_2019:
	s_and_b64 vcc, exec, s[8:9]
	s_cbranch_vccnz .LBB0_2029
	s_andn2_b64 vcc, exec, s[84:85]
	s_cbranch_vccnz .LBB0_2026
	s_andn2_b64 vcc, exec, s[78:79]
	s_cbranch_vccnz .LBB0_2023
	v_lshl_add_u64 v[8:9], s[46:47], 0, v[20:21]
	v_mov_b32_e32 v10, v136
	v_mov_b32_e32 v11, v144
	v_lshl_add_u64 v[8:9], v[10:11], 1, v[8:9]
	v_add_co_u32_e32 v8, vcc, 0xfffff000, v8
	s_mov_b64 s[24:25], 0
	s_nop 0
	v_addc_co_u32_e32 v9, vcc, -1, v9, vcc
	v_cvt_pk_bf16_f32 v238, v4, v5
	v_cvt_pk_bf16_f32 v239, v6, v7
.LBB0_2023:
	s_andn2_b64 vcc, exec, s[24:25]
	s_cbranch_vccnz .LBB0_2025
	v_mul_f32_e32 v8, 0xbfb8aa3b, v4
	v_mul_f32_e32 v9, 0xbfb8aa3b, v5
	v_mul_f32_e32 v10, 0xbfb8aa3b, v6
	v_mul_f32_e32 v11, 0xbfb8aa3b, v7
	v_exp_f32_e32 v8, v8
	v_exp_f32_e32 v9, v9
	v_exp_f32_e32 v10, v10
	v_exp_f32_e32 v11, v11
	v_add_f32_e32 v8, 1.0, v8
	v_add_f32_e32 v9, 1.0, v9
	v_add_f32_e32 v10, 1.0, v10
	v_add_f32_e32 v11, 1.0, v11
	v_rcp_f32_e32 v8, v8
	v_rcp_f32_e32 v9, v9
	v_rcp_f32_e32 v10, v10
	v_rcp_f32_e32 v11, v11
	v_mul_f32_e32 v12, v4, v8
	v_mul_f32_e32 v13, v5, v9
	v_mul_f32_e32 v14, v6, v10
	v_mul_f32_e32 v15, v7, v11
	v_lshl_add_u64 v[8:9], s[48:49], 0, v[18:19]
	v_mov_b32_e32 v10, v136
	v_mov_b32_e32 v11, v144
	v_lshl_add_u64 v[8:9], v[10:11], 1, v[8:9]
	v_cvt_pk_bf16_f32 v238, v12, v13
	v_cvt_pk_bf16_f32 v239, v14, v15

; __device__ __forceinline__ void store_bf16x4(bf16_t* p, f32x4 v) { u32x2 w; w.x = cvt_pk_bf16(v[0], v[1]); w.y = cvt_pk_bf16(v[2], v[3]); *(u32x2*)p = w; }
;   __device__ __forceinline__ void operator()(const f32x4 (&acc)[2][2][4][2], const pg8::Unit& u, int wr, int wc, int fr, int fq) const {
;     ...
;       else if (pn < 8) { store_bf16x4(VH + (size_t)row * 512 + (col - 1536), v); }
.LBB0_2026:
	s_andn2_b64 vcc, exec, s[24:25]
	s_cbranch_vccnz .LBB0_2028
	v_lshl_add_u64 v[8:9], s[16:17], 0, v[18:19]
	v_mov_b32_e32 v10, v136
	v_mov_b32_e32 v11, v144
	v_lshl_add_u64 v[8:9], v[10:11], 1, v[8:9]
	v_cvt_pk_bf16_f32 v238, v4, v5
	v_cvt_pk_bf16_f32 v239, v6, v7

; __device__ __forceinline__ float sigmoidf_(float v) { return __builtin_amdgcn_rcpf(1.0f + __expf(-v)); }
; __device__ __forceinline__ float siluf_(float v) { return v * sigmoidf_(v); }
; __device__ __forceinline__ void store_bf16x4(bf16_t* p, f32x4 v) { u32x2 w; w.x = cvt_pk_bf16(v[0], v[1]); w.y = cvt_pk_bf16(v[2], v[3]); *(u32x2*)p = w; }
;   __device__ __forceinline__ void operator()(const f32x4 (&acc)[2][2][4][2], const pg8::Unit& u, int wr, int wc, int fr, int fq) const {
;     const int pn = u.pn;
;     EPI_LOOP(
;       if (pn < 2) { f32x4 o; for (int j = 0; j < 4; ++j) o[j] = siluf_(v[j]); store_bf16x4(QH + (size_t)row * 512 + col, o); }
;       else if (pn < 6) { const int c = col - 512; const f32x4 lb = *(const f32x4*)(LBj + c); f32x4 o; for (int j = 0; j < 4; ++j) o[j] = lb[j] + (1.f - lb[j]) * sigmoidf_(v[j]); *(f32x4*)(F + (size_t)row * 1024 + c) = o; }
;       else if (pn < 8) { store_bf16x4(VH + (size_t)row * 512 + (col - 1536), v); }
;       else if (pn < 10) { f32x4 o; for (int j = 0; j < 4; ++j) o[j] = siluf_(v[j]); store_bf16x4(G + (size_t)row * 512 + (col - 2048), o); }
;       else { store_bf16x4(CQ + (size_t)row * 768 + (col - 2560), v); }
.LBB0_2033:
	s_and_b64 vcc, exec, s[8:9]
	s_mov_b64 s[8:9], -1
	s_cbranch_vccnz .LBB0_2043
	s_andn2_b64 vcc, exec, s[84:85]
	s_cbranch_vccnz .LBB0_2040
	s_andn2_b64 vcc, exec, s[78:79]
	s_cbranch_vccnz .LBB0_2037
	v_lshl_add_u64 v[4:5], s[46:47], 0, v[20:21]
	v_mov_b32_e32 v6, v136
	v_mov_b32_e32 v7, v144
	v_lshl_add_u64 v[4:5], v[6:7], 1, v[4:5]
	v_add_co_u32_e32 v4, vcc, 0xfffff000, v4
	s_mov_b64 s[8:9], 0
	s_nop 0
	v_addc_co_u32_e32 v5, vcc, -1, v5, vcc
	v_cvt_pk_bf16_f32 v240, v0, v1
	v_cvt_pk_bf16_f32 v241, v2, v3
	s_nop 1
	v_permlane16_swap_b32_e32 v238, v240
	v_permlane16_swap_b32_e32 v239, v241
	v_lshl_add_u64 v[242:243], v[4:5], 0, v[244:245]
	global_store_dwordx4 v[242:243], v[238:241], off offset:-768
.LBB0_2037:
	s_andn2_b64 vcc, exec, s[8:9]
	s_cbranch_vccnz .LBB0_2039
	v_mul_f32_e32 v4, 0xbfb8aa3b, v0
	v_mul_f32_e32 v5, 0xbfb8aa3b, v1
	v_mul_f32_e32 v6, 0xbfb8aa3b, v2
	v_mul_f32_e32 v7, 0xbfb8aa3b, v3
	v_exp_f32_e32 v4, v4
	v_exp_f32_e32 v5, v5
	v_exp_f32_e32 v6, v6
	v_exp_f32_e32 v7, v7
	v_add_f32_e32 v4, 1.0, v4
	v_add_f32_e32 v5, 1.0, v5
	v_add_f32_e32 v6, 1.0, v6
	v_add_f32_e32 v7, 1.0, v7
	v_rcp_f32_e32 v4, v4
	v_rcp_f32_e32 v5, v5
	v_rcp_f32_e32 v6, v6
	v_rcp_f32_e32 v7, v7
	v_mul_f32_e32 v8, v0, v4
	v_mul_f32_e32 v9, v1, v5
	v_mul_f32_e32 v10, v2, v6
	v_mul_f32_e32 v11, v3, v7
	v_lshl_add_u64 v[4:5], s[48:49], 0, v[18:19]
	v_mov_b32_e32 v6, v136
	v_mov_b32_e32 v7, v144
	v_lshl_add_u64 v[4:5], v[6:7], 1, v[4:5]
	v_cvt_pk_bf16_f32 v240, v8, v9
	v_cvt_pk_bf16_f32 v241, v10, v11
	s_nop 1
	v_permlane16_swap_b32_e32 v238, v240
	v_permlane16_swap_b32_e32 v239, v241
	v_lshl_add_u64 v[242:243], v[4:5], 0, v[244:245]
	global_store_dwordx4 v[242:243], v[238:241], off offset:-3840

; __device__ __forceinline__ void store_bf16x4(bf16_t* p, f32x4 v) { u32x2 w; w.x = cvt_pk_bf16(v[0], v[1]); w.y = cvt_pk_bf16(v[2], v[3]); *(u32x2*)p = w; }
;   __device__ __forceinline__ void operator()(const f32x4 (&acc)[2][2][4][2], const pg8::Unit& u, int wr, int wc, int fr, int fq) const {
;     ...
;       else if (pn < 8) { store_bf16x4(VH + (size_t)row * 512 + (col - 1536), v); }
.LBB0_2040:
	s_andn2_b64 vcc, exec, s[8:9]
	s_cbranch_vccnz .LBB0_2042
	v_lshl_add_u64 v[4:5], s[16:17], 0, v[18:19]
	v_mov_b32_e32 v6, v136
	v_mov_b32_e32 v7, v144
	v_lshl_add_u64 v[4:5], v[6:7], 1, v[4:5]
	v_cvt_pk_bf16_f32 v240, v0, v1
	v_cvt_pk_bf16_f32 v241, v2, v3
	s_nop 1
	v_permlane16_swap_b32_e32 v238, v240
	v_permlane16_swap_b32_e32 v239, v241
	v_lshl_add_u64 v[242:243], v[4:5], 0, v[244:245]
	global_store_dwordx4 v[242:243], v[238:241], off offset:-2816

; __device__ __forceinline__ float siluf_(float v) { return v * sigmoidf_(v); }
; __device__ __forceinline__ void store_bf16x4(bf16_t* p, f32x4 v) { u32x2 w; w.x = cvt_pk_bf16(v[0], v[1]); w.y = cvt_pk_bf16(v[2], v[3]); *(u32x2*)p = w; }
;   __device__ __forceinline__ void operator()(const f32x4 (&acc)[2][2][4][2], const pg8::Unit& u, int wr, int wc, int fr, int fq) const {
;     ...
;       if (pn < 2) { f32x4 o; for (int j = 0; j < 4; ++j) o[j] = siluf_(v[j]); store_bf16x4(QH + (size_t)row * 512 + col, o); }
.LBB0_2047:
	v_mul_f32_e32 v24, 0xbfb8aa3b, v12
	v_exp_f32_e32 v24, v24
	s_nop 0
	v_add_f32_e32 v24, 1.0, v24
	v_rcp_f32_e32 v24, v24
	s_nop 0
	v_mul_f32_e32 v24, v12, v24
	v_mul_f32_e32 v12, 0xbfb8aa3b, v13
	v_exp_f32_e32 v12, v12
	s_nop 0
	v_add_f32_e32 v12, 1.0, v12
	v_rcp_f32_e32 v12, v12
	s_nop 0
	v_mul_f32_e32 v25, v13, v12
	v_mul_f32_e32 v12, 0xbfb8aa3b, v14
	v_exp_f32_e32 v12, v12
	s_nop 0
	v_add_f32_e32 v12, 1.0, v12
	v_rcp_f32_e32 v12, v12
	s_nop 0
	v_mul_f32_e32 v26, v14, v12
	v_mul_f32_e32 v12, 0xbfb8aa3b, v15
	v_exp_f32_e32 v12, v12
	v_cvt_pk_bf16_f32 v238, v24, v25
	s_nop 0
	v_add_f32_e32 v12, 1.0, v12
	v_rcp_f32_e32 v12, v12
	s_nop 0
	v_mul_f32_e32 v15, v15, v12
	v_lshl_add_u64 v[12:13], v[136:137], 1, v[22:23]
	v_cvt_pk_bf16_f32 v239, v26, v15
	s_and_b64 vcc, exec, s[10:11]
	s_mov_b64 s[24:25], -1
	s_cbranch_vccz .LBB0_2005

; __device__ __forceinline__ float siluf_(float v) { return v * sigmoidf_(v); }
; __device__ __forceinline__ void store_bf16x4(bf16_t* p, f32x4 v) { u32x2 w; w.x = cvt_pk_bf16(v[0], v[1]); w.y = cvt_pk_bf16(v[2], v[3]); *(u32x2*)p = w; }
;   __device__ __forceinline__ void operator()(const f32x4 (&acc)[2][2][4][2], const pg8::Unit& u, int wr, int wc, int fr, int fq) const {
;     ...
;       if (pn < 2) { f32x4 o; for (int j = 0; j < 4; ++j) o[j] = siluf_(v[j]); store_bf16x4(QH + (size_t)row * 512 + col, o); }
.LBB0_2049:
	s_nop 0
	v_mul_f32_e32 v12, 0xbfb8aa3b, v8
	v_exp_f32_e32 v12, v12
	s_nop 0
	v_add_f32_e32 v12, 1.0, v12
	v_rcp_f32_e32 v12, v12
	s_nop 0
	v_mul_f32_e32 v12, v8, v12
	v_mul_f32_e32 v8, 0xbfb8aa3b, v9
	v_exp_f32_e32 v8, v8
	s_nop 0
	v_add_f32_e32 v8, 1.0, v8
	v_rcp_f32_e32 v8, v8
	s_nop 0
	v_mul_f32_e32 v13, v9, v8
	v_mul_f32_e32 v8, 0xbfb8aa3b, v10
	v_exp_f32_e32 v8, v8
	s_nop 0
	v_add_f32_e32 v8, 1.0, v8
	v_rcp_f32_e32 v8, v8
	s_nop 0
	v_mul_f32_e32 v14, v10, v8
	v_mul_f32_e32 v8, 0xbfb8aa3b, v11
	v_exp_f32_e32 v8, v8
	v_cvt_pk_bf16_f32 v240, v12, v13
	s_nop 0
	v_add_f32_e32 v8, 1.0, v8
	v_rcp_f32_e32 v8, v8
	s_nop 0
	v_mul_f32_e32 v11, v11, v8
	v_lshl_add_u64 v[8:9], v[136:137], 1, v[22:23]
	v_cvt_pk_bf16_f32 v241, v14, v11
	s_nop 1
	v_permlane16_swap_b32_e32 v238, v240
	v_permlane16_swap_b32_e32 v239, v241
	v_lshl_add_u64 v[242:243], v[8:9], 0, v[244:245]
	global_store_dwordx4 v[242:243], v[238:241], off
	s_and_b64 vcc, exec, s[10:11]
	s_mov_b64 s[24:25], -1
	s_cbranch_vccz .LBB0_2019

; __device__ __forceinline__ float siluf_(float v) { return v * sigmoidf_(v); }
; __device__ __forceinline__ void store_bf16x4(bf16_t* p, f32x4 v) { u32x2 w; w.x = cvt_pk_bf16(v[0], v[1]); w.y = cvt_pk_bf16(v[2], v[3]); *(u32x2*)p = w; }
;   __device__ __forceinline__ void operator()(const f32x4 (&acc)[2][2][4][2], const pg8::Unit& u, int wr, int wc, int fr, int fq) const {
;     ...
;       if (pn < 2) { f32x4 o; for (int j = 0; j < 4; ++j) o[j] = siluf_(v[j]); store_bf16x4(QH + (size_t)row * 512 + col, o); }
.LBB0_2051:
	s_nop 0
	v_mul_f32_e32 v8, 0xbfb8aa3b, v4
	v_exp_f32_e32 v8, v8
	s_nop 0
	v_add_f32_e32 v8, 1.0, v8
	v_rcp_f32_e32 v8, v8
	s_nop 0
	v_mul_f32_e32 v8, v4, v8
	v_mul_f32_e32 v4, 0xbfb8aa3b, v5
	v_exp_f32_e32 v4, v4
	s_nop 0
	v_add_f32_e32 v4, 1.0, v4
	v_rcp_f32_e32 v4, v4
	s_nop 0
	v_mul_f32_e32 v9, v5, v4
	v_mul_f32_e32 v4, 0xbfb8aa3b, v6
	v_exp_f32_e32 v4, v4
	s_nop 0
	v_add_f32_e32 v4, 1.0, v4
	v_rcp_f32_e32 v4, v4
	s_nop 0
	v_mul_f32_e32 v10, v6, v4
	v_mul_f32_e32 v4, 0xbfb8aa3b, v7
	v_exp_f32_e32 v4, v4
	v_cvt_pk_bf16_f32 v238, v8, v9
	s_nop 0
	v_add_f32_e32 v4, 1.0, v4
	v_rcp_f32_e32 v4, v4
	s_nop 0
	v_mul_f32_e32 v7, v7, v4
	v_lshl_add_u64 v[4:5], v[136:137], 1, v[22:23]
	v_cvt_pk_bf16_f32 v239, v10, v7
	s_and_b64 vcc, exec, s[10:11]
	s_mov_b64 s[10:11], -1
	s_cbranch_vccz .LBB0_2033

; __device__ __forceinline__ float siluf_(float v) { return v * sigmoidf_(v); }
; __device__ __forceinline__ void store_bf16x4(bf16_t* p, f32x4 v) { u32x2 w; w.x = cvt_pk_bf16(v[0], v[1]); w.y = cvt_pk_bf16(v[2], v[3]); *(u32x2*)p = w; }
; template <class Epi, class Sched>
; __device__ __forceinline__ void gemm_phase(LAS unsigned char* lds, const Gemm g, const Sched& S, const Epi& E) {
;     ...
;     E(acc, cur, wr, wc, fr, fq);
;     if (!has_next) break;
; #pragma unroll
;     for (int a = 0; a < 2; ++a)
; #pragma unroll
;       for (int b = 0; b < 2; ++b)
; #pragma unroll
;         for (int m = 0; m < 4; ++m)
; #pragma unroll
;           for (int n = 0; n < 2; ++n) acc[a][b][m][n] = (f32x4){0.f, 0.f, 0.f, 0.f};
;     cur = nxt; cA = nA; cB = nB; ++ui;
;   __device__ __forceinline__ void operator()(const f32x4 (&acc)[2][2][4][2], const pg8::Unit& u, int wr, int wc, int fr, int fq) const {
;     ...
;       if (pn < 2) { f32x4 o; for (int j = 0; j < 4; ++j) o[j] = siluf_(v[j]); store_bf16x4(QH + (size_t)row * 512 + col, o); }
.LBB0_2053:
	v_mul_f32_e32 v4, 0xbfb8aa3b, v0
	v_exp_f32_e32 v4, v4
	s_nop 0
	v_add_f32_e32 v4, 1.0, v4
	v_rcp_f32_e32 v4, v4
	s_nop 0
	v_mul_f32_e32 v4, v0, v4
	v_mul_f32_e32 v0, 0xbfb8aa3b, v1
	v_exp_f32_e32 v0, v0
	s_nop 0
	v_add_f32_e32 v0, 1.0, v0
	v_rcp_f32_e32 v0, v0
	s_nop 0
	v_mul_f32_e32 v5, v1, v0
	v_mul_f32_e32 v0, 0xbfb8aa3b, v2
	v_exp_f32_e32 v0, v0
	s_nop 0
	v_add_f32_e32 v0, 1.0, v0
	v_rcp_f32_e32 v0, v0
	s_nop 0
	v_mul_f32_e32 v6, v2, v0
	v_mul_f32_e32 v0, 0xbfb8aa3b, v3
	v_exp_f32_e32 v0, v0
	v_cvt_pk_bf16_f32 v240, v4, v5
	s_nop 0
	v_add_f32_e32 v0, 1.0, v0
	v_rcp_f32_e32 v0, v0
	s_nop 0
	v_mul_f32_e32 v3, v3, v0
	v_lshl_add_u64 v[0:1], v[136:137], 1, v[22:23]
	v_cvt_pk_bf16_f32 v241, v6, v3
	s_nop 1
	v_permlane16_swap_b32_e32 v238, v240
	v_permlane16_swap_b32_e32 v239, v241
	v_lshl_add_u64 v[242:243], v[0:1], 0, v[244:245]
	global_store_dwordx4 v[242:243], v[238:241], off offset:256
	s_branch .LBB0_1533
